# GEMM phase blocks: MFMA issue order changed to a snake over the operand grid so consecutive MFMAs share one input operand (pure permutation of independent MFMAs)
# baseline (speedup 1.0000x reference)
; #define PG8_STAGE(bufoff, gbase, voff) do { _Pragma("unroll") for (int _i = 0; _i < 2; ++_i) \
;         __builtin_amdgcn_global_load_lds((const unsigned*)((const char*)(gbase) + (voff)[_i]), (LAS unsigned*)(lds + (bufoff) + ldsw + _i * 8192), 16, 0, 0); } while (0)
; #define PG8_LDA(dst, b, h) do { _Pragma("unroll") for (int m = 0; m < 4; ++m) _Pragma("unroll") for (int k = 0; k < 2; ++k) dst[m][k] = *(const LAS bf16x8*)(lds + PG8_SA(b, h) + aoff + m * 2048 + k * 1024); } while (0)
; #define PG8_LDB(dst, b, h) do { _Pragma("unroll") for (int n = 0; n < 2; ++n) _Pragma("unroll") for (int k = 0; k < 2; ++k) dst[n][k] = *(const LAS bf16x8*)(lds + PG8_SB(b, h) + boff + n * 2048 + k * 1024); } while (0)
; #define PG8_MMA(ai, bj, At, Bt) do { __builtin_amdgcn_s_setprio(1); _Pragma("unroll") for (int m = 0; m < 4; ++m) _Pragma("unroll") for (int n = 0; n < 2; ++n) _Pragma("unroll") for (int k = 0; k < 2; ++k) \
;         acc[ai][bj][m][n] = __builtin_amdgcn_mfma_f32_16x16x32_bf16(Bt[n][k], At[m][k], acc[ai][bj][m][n], 0, 0, 0); __builtin_amdgcn_s_setprio(0); } while (0)
; #define PG8_WAIT_V(n) asm volatile("s_waitcnt vmcnt(" #n ")" ::: "memory")
; #define PG8_WAIT_L(n) asm volatile("s_waitcnt lgkmcnt(" #n ")" ::: "memory")
; #define PG8_BAR __builtin_amdgcn_s_barrier()
; #define PG8_SCHED __builtin_amdgcn_sched_barrier(0)
; template <class Epi>
; __device__ __forceinline__ void gemm_phase(LAS unsigned char* lds, const Gemm g, const StaticOrder& S, const Epi& E) {
;     ...
;         for (int t = 0; t < nt; t += 2) {
;             const bool last = (t == nt - 2);
;             const char* a1 = cA + (size_t)(t + 1) * kstep;
;             const char* a2 = last ? nA : cA + (size_t)(t + 2) * kstep; const char* b2 = last ? nB : cB + (size_t)(t + 2) * kstep;
;             const char* a3 = a2 + kstep; const char* b3 = b2 + kstep;
;             PG8_LDB(B0, 0, 0); PG8_LDB(B1, 0, 1); PG8_SCHED; PG8_LDA(At, 0, 0); PG8_STAGE(PG8_SA(1, 1), a1 + hstepA, voffA);
;             PG8_WAIT_V(8); PG8_WAIT_L(0); PG8_BAR; PG8_MMA(0, 0, At, B0); PG8_MMA(0, 1, At, B1); PG8_BAR; PG8_SCHED;
;             PG8_LDA(At, 0, 1); PG8_STAGE(PG8_SB(0, 0), b2, voffB); PG8_STAGE(PG8_SB(0, 1), b2 + hstepB, voffB); PG8_STAGE(PG8_SA(0, 0), a2, voffA);
;             PG8_WAIT_V(8); PG8_WAIT_L(0); PG8_BAR; PG8_MMA(1, 0, At, B0); PG8_MMA(1, 1, At, B1); PG8_BAR; PG8_SCHED;
.LBB0_245:
	ds_read_b128 v[152:155], v148
	ds_read_b128 v[156:159], v148 offset:1024
	ds_read_b128 v[160:163], v148 offset:2048
	ds_read_b128 v[164:167], v148 offset:3072
	ds_read_b128 v[168:171], v149
	ds_read_b128 v[172:175], v149 offset:1024
	ds_read_b128 v[176:179], v149 offset:2048
	ds_read_b128 v[180:183], v149 offset:3072
	s_add_i32 s64, s26, 2
	s_add_u32 s27, s24, 0xfff80080
	s_addc_u32 s30, s25, -1
	s_cmp_eq_u32 s54, s26
	s_cselect_b32 s26, s61, s62
	s_cselect_b32 s31, s15, s30
	s_cselect_b32 s30, s17, s27
	s_cselect_b32 s27, s60, s63
	v_lshl_add_u64 v[220:221], s[24:25], 0, v[138:139]
	s_add_i32 m0, s44, 0xc000
	ds_read_b128 v[184:187], v150
	ds_read_b128 v[188:191], v150 offset:1024
	ds_read_b128 v[192:195], v150 offset:2048
	ds_read_b128 v[196:199], v150 offset:3072
	ds_read_b128 v[200:203], v150 offset:4096
	ds_read_b128 v[208:211], v150 offset:5120
	ds_read_b128 v[212:215], v150 offset:6144
	ds_read_b128 v[216:219], v150 offset:7168
	global_load_lds_dwordx4 v[220:221], off
	v_lshl_add_u64 v[220:221], s[24:25], 0, v[140:141]
	s_add_i32 m0, s44, 0xe000
	s_nop 0
	global_load_lds_dwordx4 v[220:221], off
	s_waitcnt vmcnt(8)
	s_waitcnt lgkmcnt(0)
	s_barrier
	s_setprio 1
	s_waitcnt lgkmcnt(0)
	v_mfma_f32_16x16x32_bf16 v[120:123], v[152:155], v[184:187], v[120:123]
	v_mfma_f32_16x16x32_bf16 v[116:119], v[160:163], v[184:187], v[116:119]
	v_mfma_f32_16x16x32_bf16 v[124:127], v[168:171], v[184:187], v[124:127]
	v_mfma_f32_16x16x32_bf16 v[112:115], v[176:179], v[184:187], v[112:115]
	v_mfma_f32_16x16x32_bf16 v[96:99], v[176:179], v[192:195], v[96:99]
	v_mfma_f32_16x16x32_bf16 v[104:107], v[168:171], v[192:195], v[104:107]
	v_mfma_f32_16x16x32_bf16 v[100:103], v[160:163], v[192:195], v[100:103]
	v_mfma_f32_16x16x32_bf16 v[108:111], v[152:155], v[192:195], v[108:111]
	v_mfma_f32_16x16x32_bf16 v[92:95], v[152:155], v[200:203], v[92:95]
	v_mfma_f32_16x16x32_bf16 v[84:87], v[160:163], v[200:203], v[84:87]
	v_mfma_f32_16x16x32_bf16 v[88:91], v[168:171], v[200:203], v[88:91]
	v_mfma_f32_16x16x32_bf16 v[80:83], v[176:179], v[200:203], v[80:83]
	v_mfma_f32_16x16x32_bf16 v[64:67], v[176:179], v[212:215], v[64:67]
	v_mfma_f32_16x16x32_bf16 v[72:75], v[168:171], v[212:215], v[72:75]
	v_mfma_f32_16x16x32_bf16 v[68:71], v[160:163], v[212:215], v[68:71]
	v_mfma_f32_16x16x32_bf16 v[76:79], v[152:155], v[212:215], v[76:79]
	s_setprio 0
	s_setprio 1
	v_mfma_f32_16x16x32_bf16 v[120:123], v[156:159], v[188:191], v[120:123]
	v_mfma_f32_16x16x32_bf16 v[116:119], v[164:167], v[188:191], v[116:119]
	v_mfma_f32_16x16x32_bf16 v[124:127], v[172:175], v[188:191], v[124:127]
	v_mfma_f32_16x16x32_bf16 v[112:115], v[180:183], v[188:191], v[112:115]
	v_mfma_f32_16x16x32_bf16 v[96:99], v[180:183], v[196:199], v[96:99]
	v_mfma_f32_16x16x32_bf16 v[104:107], v[172:175], v[196:199], v[104:107]
	v_mfma_f32_16x16x32_bf16 v[100:103], v[164:167], v[196:199], v[100:103]
	v_mfma_f32_16x16x32_bf16 v[108:111], v[156:159], v[196:199], v[108:111]
	v_mfma_f32_16x16x32_bf16 v[92:95], v[156:159], v[208:211], v[92:95]
	v_mfma_f32_16x16x32_bf16 v[84:87], v[164:167], v[208:211], v[84:87]
	v_mfma_f32_16x16x32_bf16 v[88:91], v[172:175], v[208:211], v[88:91]
	v_mfma_f32_16x16x32_bf16 v[80:83], v[180:183], v[208:211], v[80:83]
	v_mfma_f32_16x16x32_bf16 v[64:67], v[180:183], v[216:219], v[64:67]
	v_mfma_f32_16x16x32_bf16 v[72:75], v[172:175], v[216:219], v[72:75]
	v_mfma_f32_16x16x32_bf16 v[68:71], v[164:167], v[216:219], v[68:71]
	v_mfma_f32_16x16x32_bf16 v[76:79], v[156:159], v[216:219], v[76:79]
	s_setprio 0
	s_barrier
	s_add_i32 s65, s57, s33
	v_lshl_add_u64 v[220:221], s[26:27], 0, v[132:133]
	s_mov_b32 m0, s65
	ds_read_b128 v[184:187], v150 offset:16384
	ds_read_b128 v[188:191], v150 offset:17408
	ds_read_b128 v[192:195], v150 offset:18432
	ds_read_b128 v[196:199], v150 offset:19456
	ds_read_b128 v[200:203], v150 offset:20480
	ds_read_b128 v[208:211], v150 offset:21504
	ds_read_b128 v[212:215], v150 offset:22528
	ds_read_b128 v[216:219], v150 offset:23552
	global_load_lds_dwordx4 v[220:221], off
	s_add_i32 m0, s65, 0x2000
	s_add_u32 s66, s26, 0x80000
	v_lshl_add_u64 v[222:223], s[26:27], 0, v[128:129]
	s_addc_u32 s67, s27, 0
	s_add_i32 s65, s58, s33
	global_load_lds_dwordx4 v[222:223], off
	v_lshl_add_u64 v[224:225], s[66:67], 0, v[132:133]
	s_mov_b32 m0, s65
	v_lshl_add_u64 v[226:227], s[30:31], 0, v[130:131]
	global_load_lds_dwordx4 v[224:225], off
	v_lshl_add_u64 v[224:225], s[66:67], 0, v[128:129]
	s_add_i32 m0, s65, 0x2000
	s_nop 0
	global_load_lds_dwordx4 v[224:225], off
	v_lshl_add_u64 v[224:225], s[30:31], 0, v[134:135]
	s_mov_b32 m0, s44
	s_nop 0
	global_load_lds_dwordx4 v[224:225], off
	s_mov_b32 m0, s45
	s_nop 0
	global_load_lds_dwordx4 v[226:227], off
	s_waitcnt vmcnt(8)
	s_waitcnt lgkmcnt(0)
	s_barrier
; #define PG8_STAGE(bufoff, gbase, voff) do { _Pragma("unroll") for (int _i = 0; _i < 2; ++_i) \
;         __builtin_amdgcn_global_load_lds((const unsigned*)((const char*)(gbase) + (voff)[_i]), (LAS unsigned*)(lds + (bufoff) + ldsw + _i * 8192), 16, 0, 0); } while (0)
; #define PG8_LDA(dst, b, h) do { _Pragma("unroll") for (int m = 0; m < 4; ++m) _Pragma("unroll") for (int k = 0; k < 2; ++k) dst[m][k] = *(const LAS bf16x8*)(lds + PG8_SA(b, h) + aoff + m * 2048 + k * 1024); } while (0)
; #define PG8_LDB(dst, b, h) do { _Pragma("unroll") for (int n = 0; n < 2; ++n) _Pragma("unroll") for (int k = 0; k < 2; ++k) dst[n][k] = *(const LAS bf16x8*)(lds + PG8_SB(b, h) + boff + n * 2048 + k * 1024); } while (0)
; #define PG8_MMA(ai, bj, At, Bt) do { __builtin_amdgcn_s_setprio(1); _Pragma("unroll") for (int m = 0; m < 4; ++m) _Pragma("unroll") for (int n = 0; n < 2; ++n) _Pragma("unroll") for (int k = 0; k < 2; ++k) \
;         acc[ai][bj][m][n] = __builtin_amdgcn_mfma_f32_16x16x32_bf16(Bt[n][k], At[m][k], acc[ai][bj][m][n], 0, 0, 0); __builtin_amdgcn_s_setprio(0); } while (0)
; #define PG8_WAIT_V(n) asm volatile("s_waitcnt vmcnt(" #n ")" ::: "memory")
; #define PG8_WAIT_L(n) asm volatile("s_waitcnt lgkmcnt(" #n ")" ::: "memory")
; #define PG8_BAR __builtin_amdgcn_s_barrier()
; #define PG8_SCHED __builtin_amdgcn_sched_barrier(0)
; template <class Epi>
; __device__ __forceinline__ void gemm_phase(LAS unsigned char* lds, const Gemm g, const StaticOrder& S, const Epi& E) {
;     ...
;             PG8_WAIT_V(8); PG8_WAIT_L(0); PG8_BAR; PG8_MMA(1, 0, At, B0); PG8_MMA(1, 1, At, B1); PG8_BAR; PG8_SCHED;
;             PG8_LDB(B0, 1, 0); PG8_LDB(B1, 1, 1); PG8_SCHED; PG8_LDA(At, 1, 0); PG8_STAGE(PG8_SA(0, 1), a2 + hstepA, voffA);
;             PG8_WAIT_V(8); PG8_WAIT_L(0); PG8_BAR; PG8_MMA(0, 0, At, B0); PG8_MMA(0, 1, At, B1); PG8_BAR; PG8_SCHED;
	s_setprio 1
	s_waitcnt lgkmcnt(0)
	v_mfma_f32_16x16x32_bf16 v[60:63], v[152:155], v[184:187], v[60:63]
	v_mfma_f32_16x16x32_bf16 v[52:55], v[160:163], v[184:187], v[52:55]
	v_mfma_f32_16x16x32_bf16 v[56:59], v[168:171], v[184:187], v[56:59]
	v_mfma_f32_16x16x32_bf16 v[48:51], v[176:179], v[184:187], v[48:51]
	v_mfma_f32_16x16x32_bf16 v[32:35], v[176:179], v[192:195], v[32:35]
	v_mfma_f32_16x16x32_bf16 v[40:43], v[168:171], v[192:195], v[40:43]
	v_mfma_f32_16x16x32_bf16 v[36:39], v[160:163], v[192:195], v[36:39]
	v_mfma_f32_16x16x32_bf16 v[44:47], v[152:155], v[192:195], v[44:47]
	v_mfma_f32_16x16x32_bf16 v[28:31], v[152:155], v[200:203], v[28:31]
	v_mfma_f32_16x16x32_bf16 v[20:23], v[160:163], v[200:203], v[20:23]
	v_mfma_f32_16x16x32_bf16 v[24:27], v[168:171], v[200:203], v[24:27]
	v_mfma_f32_16x16x32_bf16 v[16:19], v[176:179], v[200:203], v[16:19]
	v_mfma_f32_16x16x32_bf16 v[0:3], v[176:179], v[212:215], v[0:3]
	v_mfma_f32_16x16x32_bf16 v[8:11], v[168:171], v[212:215], v[8:11]
	v_mfma_f32_16x16x32_bf16 v[4:7], v[160:163], v[212:215], v[4:7]
	v_mfma_f32_16x16x32_bf16 v[12:15], v[152:155], v[212:215], v[12:15]
	s_setprio 0
	s_setprio 1
	v_mfma_f32_16x16x32_bf16 v[60:63], v[156:159], v[188:191], v[60:63]
	v_mfma_f32_16x16x32_bf16 v[52:55], v[164:167], v[188:191], v[52:55]
	v_mfma_f32_16x16x32_bf16 v[56:59], v[172:175], v[188:191], v[56:59]
	v_mfma_f32_16x16x32_bf16 v[48:51], v[180:183], v[188:191], v[48:51]
	v_mfma_f32_16x16x32_bf16 v[32:35], v[180:183], v[196:199], v[32:35]
	v_mfma_f32_16x16x32_bf16 v[40:43], v[172:175], v[196:199], v[40:43]
	v_mfma_f32_16x16x32_bf16 v[36:39], v[164:167], v[196:199], v[36:39]
	v_mfma_f32_16x16x32_bf16 v[44:47], v[156:159], v[196:199], v[44:47]
	v_mfma_f32_16x16x32_bf16 v[28:31], v[156:159], v[208:211], v[28:31]
	v_mfma_f32_16x16x32_bf16 v[20:23], v[164:167], v[208:211], v[20:23]
	v_mfma_f32_16x16x32_bf16 v[24:27], v[172:175], v[208:211], v[24:27]
	v_mfma_f32_16x16x32_bf16 v[16:19], v[180:183], v[208:211], v[16:19]
	v_mfma_f32_16x16x32_bf16 v[0:3], v[180:183], v[216:219], v[0:3]
	v_mfma_f32_16x16x32_bf16 v[8:11], v[172:175], v[216:219], v[8:11]
	v_mfma_f32_16x16x32_bf16 v[4:7], v[164:167], v[216:219], v[4:7]
	v_mfma_f32_16x16x32_bf16 v[12:15], v[156:159], v[216:219], v[12:15]
	s_setprio 0
	s_barrier
	s_add_i32 s65, 0, 0x18000
	v_add_u32_e32 v151, s65, v146
	s_add_i32 s66, 0, 0x1c000
	ds_read_b128 v[152:155], v151
	ds_read_b128 v[156:159], v151 offset:1024
	ds_read_b128 v[160:163], v151 offset:2048
	ds_read_b128 v[164:167], v151 offset:3072
	v_add_u32_e32 v151, s66, v146
	ds_read_b128 v[168:171], v151
	ds_read_b128 v[172:175], v151 offset:1024
	ds_read_b128 v[176:179], v151 offset:2048
	ds_read_b128 v[180:183], v151 offset:3072
	s_add_u32 s30, s30, 0x80000
	s_addc_u32 s31, s31, 0
	s_mov_b32 m0, s46
	v_lshl_add_u64 v[230:231], s[30:31], 0, v[134:135]
	ds_read_b128 v[184:187], v150 offset:32768
	ds_read_b128 v[188:191], v150 offset:33792
	ds_read_b128 v[192:195], v150 offset:34816
	ds_read_b128 v[196:199], v150 offset:35840
	ds_read_b128 v[200:203], v150 offset:36864
	ds_read_b128 v[208:211], v150 offset:37888
	ds_read_b128 v[212:215], v150 offset:38912
	ds_read_b128 v[216:219], v150 offset:39936
	global_load_lds_dwordx4 v[230:231], off
	v_lshl_add_u64 v[230:231], s[30:31], 0, v[130:131]
	s_mov_b32 m0, s47
	s_nop 0
	global_load_lds_dwordx4 v[230:231], off
	s_waitcnt vmcnt(8)
	s_waitcnt lgkmcnt(0)
	s_barrier
	s_setprio 1
	s_waitcnt lgkmcnt(0)
	v_mfma_f32_16x16x32_bf16 v[120:123], v[152:155], v[184:187], v[120:123]
	v_mfma_f32_16x16x32_bf16 v[116:119], v[160:163], v[184:187], v[116:119]
	v_mfma_f32_16x16x32_bf16 v[124:127], v[168:171], v[184:187], v[124:127]
	v_mfma_f32_16x16x32_bf16 v[112:115], v[176:179], v[184:187], v[112:115]
	v_mfma_f32_16x16x32_bf16 v[96:99], v[176:179], v[192:195], v[96:99]
	v_mfma_f32_16x16x32_bf16 v[104:107], v[168:171], v[192:195], v[104:107]
	v_mfma_f32_16x16x32_bf16 v[100:103], v[160:163], v[192:195], v[100:103]
	v_mfma_f32_16x16x32_bf16 v[108:111], v[152:155], v[192:195], v[108:111]
	v_mfma_f32_16x16x32_bf16 v[92:95], v[152:155], v[200:203], v[92:95]
	v_mfma_f32_16x16x32_bf16 v[84:87], v[160:163], v[200:203], v[84:87]
	v_mfma_f32_16x16x32_bf16 v[88:91], v[168:171], v[200:203], v[88:91]
	v_mfma_f32_16x16x32_bf16 v[80:83], v[176:179], v[200:203], v[80:83]
	v_mfma_f32_16x16x32_bf16 v[64:67], v[176:179], v[212:215], v[64:67]
	v_mfma_f32_16x16x32_bf16 v[72:75], v[168:171], v[212:215], v[72:75]
	v_mfma_f32_16x16x32_bf16 v[68:71], v[160:163], v[212:215], v[68:71]
	v_mfma_f32_16x16x32_bf16 v[76:79], v[152:155], v[212:215], v[76:79]
	s_setprio 0
	s_setprio 1
	v_mfma_f32_16x16x32_bf16 v[120:123], v[156:159], v[188:191], v[120:123]
	v_mfma_f32_16x16x32_bf16 v[116:119], v[164:167], v[188:191], v[116:119]
	v_mfma_f32_16x16x32_bf16 v[124:127], v[172:175], v[188:191], v[124:127]
	v_mfma_f32_16x16x32_bf16 v[112:115], v[180:183], v[188:191], v[112:115]
	v_mfma_f32_16x16x32_bf16 v[96:99], v[180:183], v[196:199], v[96:99]
	v_mfma_f32_16x16x32_bf16 v[104:107], v[172:175], v[196:199], v[104:107]
	v_mfma_f32_16x16x32_bf16 v[100:103], v[164:167], v[196:199], v[100:103]
	v_mfma_f32_16x16x32_bf16 v[108:111], v[156:159], v[196:199], v[108:111]
	v_mfma_f32_16x16x32_bf16 v[92:95], v[156:159], v[208:211], v[92:95]
	v_mfma_f32_16x16x32_bf16 v[84:87], v[164:167], v[208:211], v[84:87]
	v_mfma_f32_16x16x32_bf16 v[88:91], v[172:175], v[208:211], v[88:91]
	v_mfma_f32_16x16x32_bf16 v[80:83], v[180:183], v[208:211], v[80:83]
	v_mfma_f32_16x16x32_bf16 v[64:67], v[180:183], v[216:219], v[64:67]
	v_mfma_f32_16x16x32_bf16 v[72:75], v[172:175], v[216:219], v[72:75]
	v_mfma_f32_16x16x32_bf16 v[68:71], v[164:167], v[216:219], v[68:71]
	v_mfma_f32_16x16x32_bf16 v[76:79], v[156:159], v[216:219], v[76:79]
	s_setprio 0
	s_barrier
; #define PG8_STAGE(bufoff, gbase, voff) do { _Pragma("unroll") for (int _i = 0; _i < 2; ++_i) \
;         __builtin_amdgcn_global_load_lds((const unsigned*)((const char*)(gbase) + (voff)[_i]), (LAS unsigned*)(lds + (bufoff) + ldsw + _i * 8192), 16, 0, 0); } while (0)
; #define PG8_LDA(dst, b, h) do { _Pragma("unroll") for (int m = 0; m < 4; ++m) _Pragma("unroll") for (int k = 0; k < 2; ++k) dst[m][k] = *(const LAS bf16x8*)(lds + PG8_SA(b, h) + aoff + m * 2048 + k * 1024); } while (0)
; #define PG8_MMA(ai, bj, At, Bt) do { __builtin_amdgcn_s_setprio(1); _Pragma("unroll") for (int m = 0; m < 4; ++m) _Pragma("unroll") for (int n = 0; n < 2; ++n) _Pragma("unroll") for (int k = 0; k < 2; ++k) \
;         acc[ai][bj][m][n] = __builtin_amdgcn_mfma_f32_16x16x32_bf16(Bt[n][k], At[m][k], acc[ai][bj][m][n], 0, 0, 0); __builtin_amdgcn_s_setprio(0); } while (0)
; #define PG8_WAIT_V(n) asm volatile("s_waitcnt vmcnt(" #n ")" ::: "memory")
; #define PG8_WAIT_L(n) asm volatile("s_waitcnt lgkmcnt(" #n ")" ::: "memory")
; #define PG8_BAR __builtin_amdgcn_s_barrier()
; #define PG8_SCHED __builtin_amdgcn_sched_barrier(0)
; template <class Epi>
; __device__ __forceinline__ void gemm_phase(LAS unsigned char* lds, const Gemm g, const StaticOrder& S, const Epi& E) {
;     ...
;             PG8_LDA(At, 1, 1); PG8_STAGE(PG8_SB(1, 0), b3, voffB); PG8_STAGE(PG8_SB(1, 1), b3 + hstepB, voffB); PG8_STAGE(PG8_SA(1, 0), a3, voffA);
;             PG8_WAIT_V(8); PG8_WAIT_L(0); PG8_BAR; PG8_MMA(1, 0, At, B0); PG8_MMA(1, 1, At, B1); PG8_BAR; PG8_SCHED;
;         }
	s_add_i32 s30, s65, s33
	v_lshl_add_u64 v[220:221], v[220:221], 0, s[8:9]
	s_mov_b32 m0, s30
	ds_read_b128 v[184:187], v150 offset:49152
	ds_read_b128 v[188:191], v150 offset:50176
	ds_read_b128 v[192:195], v150 offset:51200
	ds_read_b128 v[196:199], v150 offset:52224
	ds_read_b128 v[200:203], v150 offset:53248
	ds_read_b128 v[208:211], v150 offset:54272
	ds_read_b128 v[212:215], v150 offset:55296
	ds_read_b128 v[216:219], v150 offset:56320
	global_load_lds_dwordx4 v[220:221], off
	s_add_i32 m0, s30, 0x2000
	s_add_u32 s26, s26, 0x80080
	v_lshl_add_u64 v[220:221], v[222:223], 0, s[8:9]
	s_addc_u32 s27, s27, 0
	s_add_i32 s30, s66, s33
	global_load_lds_dwordx4 v[220:221], off
	v_lshl_add_u64 v[220:221], s[26:27], 0, v[132:133]
	s_mov_b32 m0, s30
	s_nop 0
	global_load_lds_dwordx4 v[220:221], off
	v_lshl_add_u64 v[220:221], s[26:27], 0, v[128:129]
	s_add_i32 m0, s30, 0x2000
	s_nop 0
	global_load_lds_dwordx4 v[220:221], off
	v_lshl_add_u64 v[220:221], v[224:225], 0, s[8:9]
	s_mov_b32 m0, s52
	s_nop 0
	global_load_lds_dwordx4 v[220:221], off
	v_lshl_add_u64 v[220:221], v[226:227], 0, s[8:9]
	s_mov_b32 m0, s53
	s_nop 0
	global_load_lds_dwordx4 v[220:221], off
	s_waitcnt vmcnt(8)
	s_waitcnt lgkmcnt(0)
	s_barrier
	s_setprio 1
	s_waitcnt lgkmcnt(0)
	v_mfma_f32_16x16x32_bf16 v[60:63], v[152:155], v[184:187], v[60:63]
	v_mfma_f32_16x16x32_bf16 v[52:55], v[160:163], v[184:187], v[52:55]
	v_mfma_f32_16x16x32_bf16 v[56:59], v[168:171], v[184:187], v[56:59]
	v_mfma_f32_16x16x32_bf16 v[48:51], v[176:179], v[184:187], v[48:51]
	v_mfma_f32_16x16x32_bf16 v[32:35], v[176:179], v[192:195], v[32:35]
	v_mfma_f32_16x16x32_bf16 v[40:43], v[168:171], v[192:195], v[40:43]
	v_mfma_f32_16x16x32_bf16 v[36:39], v[160:163], v[192:195], v[36:39]
	v_mfma_f32_16x16x32_bf16 v[44:47], v[152:155], v[192:195], v[44:47]
	v_mfma_f32_16x16x32_bf16 v[28:31], v[152:155], v[200:203], v[28:31]
	v_mfma_f32_16x16x32_bf16 v[20:23], v[160:163], v[200:203], v[20:23]
	v_mfma_f32_16x16x32_bf16 v[24:27], v[168:171], v[200:203], v[24:27]
	v_mfma_f32_16x16x32_bf16 v[16:19], v[176:179], v[200:203], v[16:19]
	v_mfma_f32_16x16x32_bf16 v[0:3], v[176:179], v[212:215], v[0:3]
	v_mfma_f32_16x16x32_bf16 v[8:11], v[168:171], v[212:215], v[8:11]
	v_mfma_f32_16x16x32_bf16 v[4:7], v[160:163], v[212:215], v[4:7]
	v_mfma_f32_16x16x32_bf16 v[12:15], v[152:155], v[212:215], v[12:15]
	s_setprio 0
	s_setprio 1
	v_mfma_f32_16x16x32_bf16 v[60:63], v[156:159], v[188:191], v[60:63]
	v_mfma_f32_16x16x32_bf16 v[52:55], v[164:167], v[188:191], v[52:55]
	v_mfma_f32_16x16x32_bf16 v[56:59], v[172:175], v[188:191], v[56:59]
	v_mfma_f32_16x16x32_bf16 v[48:51], v[180:183], v[188:191], v[48:51]
	v_mfma_f32_16x16x32_bf16 v[32:35], v[180:183], v[196:199], v[32:35]
	v_mfma_f32_16x16x32_bf16 v[40:43], v[172:175], v[196:199], v[40:43]
	v_mfma_f32_16x16x32_bf16 v[36:39], v[164:167], v[196:199], v[36:39]
	v_mfma_f32_16x16x32_bf16 v[44:47], v[156:159], v[196:199], v[44:47]
	v_mfma_f32_16x16x32_bf16 v[28:31], v[156:159], v[208:211], v[28:31]
	v_mfma_f32_16x16x32_bf16 v[20:23], v[164:167], v[208:211], v[20:23]
	v_mfma_f32_16x16x32_bf16 v[24:27], v[172:175], v[208:211], v[24:27]
	v_mfma_f32_16x16x32_bf16 v[16:19], v[180:183], v[208:211], v[16:19]
	v_mfma_f32_16x16x32_bf16 v[0:3], v[180:183], v[216:219], v[0:3]
	v_mfma_f32_16x16x32_bf16 v[8:11], v[172:175], v[216:219], v[8:11]
	v_mfma_f32_16x16x32_bf16 v[4:7], v[164:167], v[216:219], v[4:7]
	v_mfma_f32_16x16x32_bf16 v[12:15], v[156:159], v[216:219], v[12:15]
	s_setprio 0
	s_barrier
	s_add_u32 s24, s24, 0x100
	s_addc_u32 s25, s25, 0
	s_add_u32 s62, s62, 0x100
	s_addc_u32 s63, s63, 0
	s_cmp_ge_i32 s64, s49
	s_mov_b32 s26, s64
	s_cbranch_scc0 .LBB0_245

; #define PG8_STAGE(bufoff, gbase, voff) do { _Pragma("unroll") for (int _i = 0; _i < 2; ++_i) \
;         __builtin_amdgcn_global_load_lds((const unsigned*)((const char*)(gbase) + (voff)[_i]), (LAS unsigned*)(lds + (bufoff) + ldsw + _i * 8192), 16, 0, 0); } while (0)
; #define PG8_LDA(dst, b, h) do { _Pragma("unroll") for (int m = 0; m < 4; ++m) _Pragma("unroll") for (int k = 0; k < 2; ++k) dst[m][k] = *(const LAS bf16x8*)(lds + PG8_SA(b, h) + aoff + m * 2048 + k * 1024); } while (0)
; #define PG8_LDB(dst, b, h) do { _Pragma("unroll") for (int n = 0; n < 2; ++n) _Pragma("unroll") for (int k = 0; k < 2; ++k) dst[n][k] = *(const LAS bf16x8*)(lds + PG8_SB(b, h) + boff + n * 2048 + k * 1024); } while (0)
; #define PG8_MMA(ai, bj, At, Bt) do { __builtin_amdgcn_s_setprio(1); _Pragma("unroll") for (int m = 0; m < 4; ++m) _Pragma("unroll") for (int n = 0; n < 2; ++n) _Pragma("unroll") for (int k = 0; k < 2; ++k) \
;         acc[ai][bj][m][n] = __builtin_amdgcn_mfma_f32_16x16x32_bf16(Bt[n][k], At[m][k], acc[ai][bj][m][n], 0, 0, 0); __builtin_amdgcn_s_setprio(0); } while (0)
; #define PG8_WAIT_V(n) asm volatile("s_waitcnt vmcnt(" #n ")" ::: "memory")
; #define PG8_WAIT_L(n) asm volatile("s_waitcnt lgkmcnt(" #n ")" ::: "memory")
; #define PG8_BAR __builtin_amdgcn_s_barrier()
; #define PG8_SCHED __builtin_amdgcn_sched_barrier(0)
; template <class Epi>
; __device__ __forceinline__ void gemm_phase(LAS unsigned char* lds, const Gemm g, const StaticOrder& S, const Epi& E) {
;     ...
;         for (int t = 0; t < nt; t += 2) {
;             const bool last = (t == nt - 2);
;             const char* a1 = cA + (size_t)(t + 1) * kstep;
;             const char* a2 = last ? nA : cA + (size_t)(t + 2) * kstep; const char* b2 = last ? nB : cB + (size_t)(t + 2) * kstep;
;             const char* a3 = a2 + kstep; const char* b3 = b2 + kstep;
;             PG8_LDB(B0, 0, 0); PG8_LDB(B1, 0, 1); PG8_SCHED; PG8_LDA(At, 0, 0); PG8_STAGE(PG8_SA(1, 1), a1 + hstepA, voffA);
;             PG8_WAIT_V(8); PG8_WAIT_L(0); PG8_BAR; PG8_MMA(0, 0, At, B0); PG8_MMA(0, 1, At, B1); PG8_BAR; PG8_SCHED;
;             PG8_LDA(At, 0, 1); PG8_STAGE(PG8_SB(0, 0), b2, voffB); PG8_STAGE(PG8_SB(0, 1), b2 + hstepB, voffB); PG8_STAGE(PG8_SA(0, 0), a2, voffA);
;             PG8_WAIT_V(8); PG8_WAIT_L(0); PG8_BAR; PG8_MMA(1, 0, At, B0); PG8_MMA(1, 1, At, B1); PG8_BAR; PG8_SCHED;
.LBB0_445:
	ds_read_b128 v[148:151], v218
	ds_read_b128 v[152:155], v218 offset:1024
	ds_read_b128 v[156:159], v218 offset:2048
	ds_read_b128 v[160:163], v218 offset:3072
	ds_read_b128 v[164:167], v219
	ds_read_b128 v[168:171], v219 offset:1024
	ds_read_b128 v[172:175], v219 offset:2048
	ds_read_b128 v[176:179], v219 offset:3072
	s_add_i32 s65, s34, 2
	s_add_u32 s30, s4, 0x100
	s_addc_u32 s31, s5, 0
	s_cmp_eq_u32 s49, s34
	s_cselect_b32 s34, s26, s1
	s_cselect_b32 s37, s11, s31
	s_cselect_b32 s36, s10, s30
	s_cselect_b32 s35, s27, s64
	v_lshl_add_u64 v[216:217], s[4:5], 0, v[140:141]
	s_add_i32 m0, s41, 0xc000
	ds_read_b128 v[180:183], v220
	ds_read_b128 v[184:187], v220 offset:1024
	ds_read_b128 v[188:191], v220 offset:2048
	ds_read_b128 v[192:195], v220 offset:3072
	ds_read_b128 v[196:199], v220 offset:4096
	ds_read_b128 v[200:203], v220 offset:5120
	ds_read_b128 v[208:211], v220 offset:6144
	ds_read_b128 v[212:215], v220 offset:7168
	global_load_lds_dwordx4 v[216:217], off
	v_lshl_add_u64 v[216:217], s[4:5], 0, v[142:143]
	s_add_i32 m0, s41, 0xe000
	s_nop 0
	global_load_lds_dwordx4 v[216:217], off
	s_waitcnt vmcnt(8)
	s_waitcnt lgkmcnt(0)
	s_barrier
	s_setprio 1
	s_waitcnt lgkmcnt(0)
	v_mfma_f32_16x16x32_bf16 v[124:127], v[148:151], v[180:183], v[124:127]
	v_mfma_f32_16x16x32_bf16 v[120:123], v[156:159], v[180:183], v[120:123]
	v_mfma_f32_16x16x32_bf16 v[108:111], v[164:167], v[180:183], v[108:111]
	v_mfma_f32_16x16x32_bf16 v[100:103], v[172:175], v[180:183], v[100:103]
	v_mfma_f32_16x16x32_bf16 v[84:87], v[172:175], v[188:191], v[84:87]
	v_mfma_f32_16x16x32_bf16 v[92:95], v[164:167], v[188:191], v[92:95]
	v_mfma_f32_16x16x32_bf16 v[112:115], v[156:159], v[188:191], v[112:115]
	v_mfma_f32_16x16x32_bf16 v[116:119], v[148:151], v[188:191], v[116:119]
	v_mfma_f32_16x16x32_bf16 v[104:107], v[148:151], v[196:199], v[104:107]
	v_mfma_f32_16x16x32_bf16 v[96:99], v[156:159], v[196:199], v[96:99]
	v_mfma_f32_16x16x32_bf16 v[76:79], v[164:167], v[196:199], v[76:79]
	v_mfma_f32_16x16x32_bf16 v[72:75], v[172:175], v[196:199], v[72:75]
	v_mfma_f32_16x16x32_bf16 v[64:67], v[172:175], v[208:211], v[64:67]
	v_mfma_f32_16x16x32_bf16 v[68:71], v[164:167], v[208:211], v[68:71]
	v_mfma_f32_16x16x32_bf16 v[80:83], v[156:159], v[208:211], v[80:83]
	v_mfma_f32_16x16x32_bf16 v[88:91], v[148:151], v[208:211], v[88:91]
	s_setprio 0
	s_setprio 1
	v_mfma_f32_16x16x32_bf16 v[124:127], v[152:155], v[184:187], v[124:127]
	v_mfma_f32_16x16x32_bf16 v[120:123], v[160:163], v[184:187], v[120:123]
	v_mfma_f32_16x16x32_bf16 v[108:111], v[168:171], v[184:187], v[108:111]
	v_mfma_f32_16x16x32_bf16 v[100:103], v[176:179], v[184:187], v[100:103]
	v_mfma_f32_16x16x32_bf16 v[84:87], v[176:179], v[192:195], v[84:87]
	v_mfma_f32_16x16x32_bf16 v[92:95], v[168:171], v[192:195], v[92:95]
	v_mfma_f32_16x16x32_bf16 v[112:115], v[160:163], v[192:195], v[112:115]
	v_mfma_f32_16x16x32_bf16 v[116:119], v[152:155], v[192:195], v[116:119]
	v_mfma_f32_16x16x32_bf16 v[104:107], v[152:155], v[200:203], v[104:107]
	v_mfma_f32_16x16x32_bf16 v[96:99], v[160:163], v[200:203], v[96:99]
	v_mfma_f32_16x16x32_bf16 v[76:79], v[168:171], v[200:203], v[76:79]
	v_mfma_f32_16x16x32_bf16 v[72:75], v[176:179], v[200:203], v[72:75]
	v_mfma_f32_16x16x32_bf16 v[64:67], v[176:179], v[212:215], v[64:67]
	v_mfma_f32_16x16x32_bf16 v[68:71], v[168:171], v[212:215], v[68:71]
	v_mfma_f32_16x16x32_bf16 v[80:83], v[160:163], v[212:215], v[80:83]
	v_mfma_f32_16x16x32_bf16 v[88:91], v[152:155], v[212:215], v[88:91]
	s_setprio 0
	s_barrier
	s_add_i32 s4, s54, s40
	v_lshl_add_u64 v[216:217], s[34:35], 0, v[130:131]
	s_mov_b32 m0, s4
	ds_read_b128 v[180:183], v220 offset:16384
	ds_read_b128 v[184:187], v220 offset:17408
	ds_read_b128 v[188:191], v220 offset:18432
	ds_read_b128 v[192:195], v220 offset:19456
	ds_read_b128 v[196:199], v220 offset:20480
	ds_read_b128 v[200:203], v220 offset:21504
	ds_read_b128 v[208:211], v220 offset:22528
	ds_read_b128 v[212:215], v220 offset:23552
	global_load_lds_dwordx4 v[216:217], off
	s_add_i32 m0, s4, 0x2000
	s_add_u32 s4, s34, 0x158000
	v_lshl_add_u64 v[222:223], s[34:35], 0, v[134:135]
	s_addc_u32 s5, s35, 0
	s_add_i32 s66, s55, s40
	global_load_lds_dwordx4 v[222:223], off
	v_lshl_add_u64 v[224:225], s[4:5], 0, v[130:131]
	s_mov_b32 m0, s66
	v_lshl_add_u64 v[226:227], s[36:37], 0, v[132:133]
	global_load_lds_dwordx4 v[224:225], off
	v_lshl_add_u64 v[224:225], s[4:5], 0, v[134:135]
	s_add_i32 m0, s66, 0x2000
	s_nop 0
	global_load_lds_dwordx4 v[224:225], off
	v_lshl_add_u64 v[224:225], s[36:37], 0, v[128:129]
	s_mov_b32 m0, s41
	s_nop 0
	global_load_lds_dwordx4 v[224:225], off
	s_mov_b32 m0, s42
	s_nop 0
	global_load_lds_dwordx4 v[226:227], off
	s_waitcnt vmcnt(8)
	s_waitcnt lgkmcnt(0)
	s_barrier
; #define PG8_STAGE(bufoff, gbase, voff) do { _Pragma("unroll") for (int _i = 0; _i < 2; ++_i) \
;         __builtin_amdgcn_global_load_lds((const unsigned*)((const char*)(gbase) + (voff)[_i]), (LAS unsigned*)(lds + (bufoff) + ldsw + _i * 8192), 16, 0, 0); } while (0)
; #define PG8_LDA(dst, b, h) do { _Pragma("unroll") for (int m = 0; m < 4; ++m) _Pragma("unroll") for (int k = 0; k < 2; ++k) dst[m][k] = *(const LAS bf16x8*)(lds + PG8_SA(b, h) + aoff + m * 2048 + k * 1024); } while (0)
; #define PG8_LDB(dst, b, h) do { _Pragma("unroll") for (int n = 0; n < 2; ++n) _Pragma("unroll") for (int k = 0; k < 2; ++k) dst[n][k] = *(const LAS bf16x8*)(lds + PG8_SB(b, h) + boff + n * 2048 + k * 1024); } while (0)
; #define PG8_MMA(ai, bj, At, Bt) do { __builtin_amdgcn_s_setprio(1); _Pragma("unroll") for (int m = 0; m < 4; ++m) _Pragma("unroll") for (int n = 0; n < 2; ++n) _Pragma("unroll") for (int k = 0; k < 2; ++k) \
;         acc[ai][bj][m][n] = __builtin_amdgcn_mfma_f32_16x16x32_bf16(Bt[n][k], At[m][k], acc[ai][bj][m][n], 0, 0, 0); __builtin_amdgcn_s_setprio(0); } while (0)
; #define PG8_WAIT_V(n) asm volatile("s_waitcnt vmcnt(" #n ")" ::: "memory")
; #define PG8_WAIT_L(n) asm volatile("s_waitcnt lgkmcnt(" #n ")" ::: "memory")
; #define PG8_BAR __builtin_amdgcn_s_barrier()
; #define PG8_SCHED __builtin_amdgcn_sched_barrier(0)
; template <class Epi>
; __device__ __forceinline__ void gemm_phase(LAS unsigned char* lds, const Gemm g, const StaticOrder& S, const Epi& E) {
;     ...
;             PG8_WAIT_V(8); PG8_WAIT_L(0); PG8_BAR; PG8_MMA(1, 0, At, B0); PG8_MMA(1, 1, At, B1); PG8_BAR; PG8_SCHED;
;             PG8_LDB(B0, 1, 0); PG8_LDB(B1, 1, 1); PG8_SCHED; PG8_LDA(At, 1, 0); PG8_STAGE(PG8_SA(0, 1), a2 + hstepA, voffA);
;             PG8_WAIT_V(8); PG8_WAIT_L(0); PG8_BAR; PG8_MMA(0, 0, At, B0); PG8_MMA(0, 1, At, B1); PG8_BAR; PG8_SCHED;
	s_setprio 1
	s_waitcnt lgkmcnt(0)
	v_mfma_f32_16x16x32_bf16 v[60:63], v[148:151], v[180:183], v[60:63]
	v_mfma_f32_16x16x32_bf16 v[56:59], v[156:159], v[180:183], v[56:59]
	v_mfma_f32_16x16x32_bf16 v[44:47], v[164:167], v[180:183], v[44:47]
	v_mfma_f32_16x16x32_bf16 v[36:39], v[172:175], v[180:183], v[36:39]
	v_mfma_f32_16x16x32_bf16 v[20:23], v[172:175], v[188:191], v[20:23]
	v_mfma_f32_16x16x32_bf16 v[28:31], v[164:167], v[188:191], v[28:31]
	v_mfma_f32_16x16x32_bf16 v[48:51], v[156:159], v[188:191], v[48:51]
	v_mfma_f32_16x16x32_bf16 v[52:55], v[148:151], v[188:191], v[52:55]
	v_mfma_f32_16x16x32_bf16 v[40:43], v[148:151], v[196:199], v[40:43]
	v_mfma_f32_16x16x32_bf16 v[32:35], v[156:159], v[196:199], v[32:35]
	v_mfma_f32_16x16x32_bf16 v[12:15], v[164:167], v[196:199], v[12:15]
	v_mfma_f32_16x16x32_bf16 v[8:11], v[172:175], v[196:199], v[8:11]
	v_mfma_f32_16x16x32_bf16 v[0:3], v[172:175], v[208:211], v[0:3]
	v_mfma_f32_16x16x32_bf16 v[4:7], v[164:167], v[208:211], v[4:7]
	v_mfma_f32_16x16x32_bf16 v[16:19], v[156:159], v[208:211], v[16:19]
	v_mfma_f32_16x16x32_bf16 v[24:27], v[148:151], v[208:211], v[24:27]
	s_setprio 0
	s_setprio 1
	v_mfma_f32_16x16x32_bf16 v[60:63], v[152:155], v[184:187], v[60:63]
	v_mfma_f32_16x16x32_bf16 v[56:59], v[160:163], v[184:187], v[56:59]
	v_mfma_f32_16x16x32_bf16 v[44:47], v[168:171], v[184:187], v[44:47]
	v_mfma_f32_16x16x32_bf16 v[36:39], v[176:179], v[184:187], v[36:39]
	v_mfma_f32_16x16x32_bf16 v[20:23], v[176:179], v[192:195], v[20:23]
	v_mfma_f32_16x16x32_bf16 v[28:31], v[168:171], v[192:195], v[28:31]
	v_mfma_f32_16x16x32_bf16 v[48:51], v[160:163], v[192:195], v[48:51]
	v_mfma_f32_16x16x32_bf16 v[52:55], v[152:155], v[192:195], v[52:55]
	v_mfma_f32_16x16x32_bf16 v[40:43], v[152:155], v[200:203], v[40:43]
	v_mfma_f32_16x16x32_bf16 v[32:35], v[160:163], v[200:203], v[32:35]
	v_mfma_f32_16x16x32_bf16 v[12:15], v[168:171], v[200:203], v[12:15]
	v_mfma_f32_16x16x32_bf16 v[8:11], v[176:179], v[200:203], v[8:11]
	v_mfma_f32_16x16x32_bf16 v[0:3], v[176:179], v[212:215], v[0:3]
	v_mfma_f32_16x16x32_bf16 v[4:7], v[168:171], v[212:215], v[4:7]
	v_mfma_f32_16x16x32_bf16 v[16:19], v[160:163], v[212:215], v[16:19]
	v_mfma_f32_16x16x32_bf16 v[24:27], v[152:155], v[212:215], v[24:27]
	s_setprio 0
	s_barrier
	s_add_i32 s66, 0, 0x18000
	s_add_i32 s67, 0, 0x1c000
	v_add_u32_e32 v160, s66, v207
	v_add_u32_e32 v176, s67, v207
	ds_read_b128 v[148:151], v160
	ds_read_b128 v[152:155], v160 offset:1024
	ds_read_b128 v[156:159], v160 offset:2048
	ds_read_b128 v[160:163], v160 offset:3072
	ds_read_b128 v[164:167], v176
	ds_read_b128 v[168:171], v176 offset:1024
	ds_read_b128 v[172:175], v176 offset:2048
	ds_read_b128 v[176:179], v176 offset:3072
	s_add_u32 s4, s36, 0x158000
	s_addc_u32 s5, s37, 0
	s_mov_b32 m0, s43
	v_lshl_add_u64 v[230:231], s[4:5], 0, v[128:129]
	ds_read_b128 v[180:183], v220 offset:32768
	ds_read_b128 v[184:187], v220 offset:33792
	ds_read_b128 v[188:191], v220 offset:34816
	ds_read_b128 v[192:195], v220 offset:35840
	ds_read_b128 v[196:199], v220 offset:36864
	ds_read_b128 v[200:203], v220 offset:37888
	ds_read_b128 v[208:211], v220 offset:38912
	ds_read_b128 v[212:215], v220 offset:39936
	global_load_lds_dwordx4 v[230:231], off
	v_lshl_add_u64 v[230:231], s[4:5], 0, v[132:133]
	s_mov_b32 m0, s44
	s_nop 0
	global_load_lds_dwordx4 v[230:231], off
	s_waitcnt vmcnt(8)
	s_waitcnt lgkmcnt(0)
	s_barrier
	s_setprio 1
	s_waitcnt lgkmcnt(0)
	v_mfma_f32_16x16x32_bf16 v[124:127], v[148:151], v[180:183], v[124:127]
	v_mfma_f32_16x16x32_bf16 v[120:123], v[156:159], v[180:183], v[120:123]
	v_mfma_f32_16x16x32_bf16 v[108:111], v[164:167], v[180:183], v[108:111]
	v_mfma_f32_16x16x32_bf16 v[100:103], v[172:175], v[180:183], v[100:103]
	v_mfma_f32_16x16x32_bf16 v[84:87], v[172:175], v[188:191], v[84:87]
	v_mfma_f32_16x16x32_bf16 v[92:95], v[164:167], v[188:191], v[92:95]
	v_mfma_f32_16x16x32_bf16 v[112:115], v[156:159], v[188:191], v[112:115]
	v_mfma_f32_16x16x32_bf16 v[116:119], v[148:151], v[188:191], v[116:119]
	v_mfma_f32_16x16x32_bf16 v[104:107], v[148:151], v[196:199], v[104:107]
	v_mfma_f32_16x16x32_bf16 v[96:99], v[156:159], v[196:199], v[96:99]
	v_mfma_f32_16x16x32_bf16 v[76:79], v[164:167], v[196:199], v[76:79]
	v_mfma_f32_16x16x32_bf16 v[72:75], v[172:175], v[196:199], v[72:75]
	v_mfma_f32_16x16x32_bf16 v[64:67], v[172:175], v[208:211], v[64:67]
	v_mfma_f32_16x16x32_bf16 v[68:71], v[164:167], v[208:211], v[68:71]
	v_mfma_f32_16x16x32_bf16 v[80:83], v[156:159], v[208:211], v[80:83]
	v_mfma_f32_16x16x32_bf16 v[88:91], v[148:151], v[208:211], v[88:91]
	s_setprio 0
	s_setprio 1
	v_mfma_f32_16x16x32_bf16 v[124:127], v[152:155], v[184:187], v[124:127]
	v_mfma_f32_16x16x32_bf16 v[120:123], v[160:163], v[184:187], v[120:123]
	v_mfma_f32_16x16x32_bf16 v[108:111], v[168:171], v[184:187], v[108:111]
	v_mfma_f32_16x16x32_bf16 v[100:103], v[176:179], v[184:187], v[100:103]
	v_mfma_f32_16x16x32_bf16 v[84:87], v[176:179], v[192:195], v[84:87]
	v_mfma_f32_16x16x32_bf16 v[92:95], v[168:171], v[192:195], v[92:95]
	v_mfma_f32_16x16x32_bf16 v[112:115], v[160:163], v[192:195], v[112:115]
	v_mfma_f32_16x16x32_bf16 v[116:119], v[152:155], v[192:195], v[116:119]
	v_mfma_f32_16x16x32_bf16 v[104:107], v[152:155], v[200:203], v[104:107]
	v_mfma_f32_16x16x32_bf16 v[96:99], v[160:163], v[200:203], v[96:99]
	v_mfma_f32_16x16x32_bf16 v[76:79], v[168:171], v[200:203], v[76:79]
	v_mfma_f32_16x16x32_bf16 v[72:75], v[176:179], v[200:203], v[72:75]
	v_mfma_f32_16x16x32_bf16 v[64:67], v[176:179], v[212:215], v[64:67]
	v_mfma_f32_16x16x32_bf16 v[68:71], v[168:171], v[212:215], v[68:71]
	v_mfma_f32_16x16x32_bf16 v[80:83], v[160:163], v[212:215], v[80:83]
	v_mfma_f32_16x16x32_bf16 v[88:91], v[152:155], v[212:215], v[88:91]
	s_setprio 0
	s_barrier
; #define PG8_STAGE(bufoff, gbase, voff) do { _Pragma("unroll") for (int _i = 0; _i < 2; ++_i) \
;         __builtin_amdgcn_global_load_lds((const unsigned*)((const char*)(gbase) + (voff)[_i]), (LAS unsigned*)(lds + (bufoff) + ldsw + _i * 8192), 16, 0, 0); } while (0)
; #define PG8_LDA(dst, b, h) do { _Pragma("unroll") for (int m = 0; m < 4; ++m) _Pragma("unroll") for (int k = 0; k < 2; ++k) dst[m][k] = *(const LAS bf16x8*)(lds + PG8_SA(b, h) + aoff + m * 2048 + k * 1024); } while (0)
; #define PG8_MMA(ai, bj, At, Bt) do { __builtin_amdgcn_s_setprio(1); _Pragma("unroll") for (int m = 0; m < 4; ++m) _Pragma("unroll") for (int n = 0; n < 2; ++n) _Pragma("unroll") for (int k = 0; k < 2; ++k) \
;         acc[ai][bj][m][n] = __builtin_amdgcn_mfma_f32_16x16x32_bf16(Bt[n][k], At[m][k], acc[ai][bj][m][n], 0, 0, 0); __builtin_amdgcn_s_setprio(0); } while (0)
; #define PG8_WAIT_V(n) asm volatile("s_waitcnt vmcnt(" #n ")" ::: "memory")
; #define PG8_WAIT_L(n) asm volatile("s_waitcnt lgkmcnt(" #n ")" ::: "memory")
; #define PG8_BAR __builtin_amdgcn_s_barrier()
; #define PG8_SCHED __builtin_amdgcn_sched_barrier(0)
; template <class Epi>
; __device__ __forceinline__ void gemm_phase(LAS unsigned char* lds, const Gemm g, const StaticOrder& S, const Epi& E) {
;     ...
;             PG8_LDA(At, 1, 1); PG8_STAGE(PG8_SB(1, 0), b3, voffB); PG8_STAGE(PG8_SB(1, 1), b3 + hstepB, voffB); PG8_STAGE(PG8_SA(1, 0), a3, voffA);
;             PG8_WAIT_V(8); PG8_WAIT_L(0); PG8_BAR; PG8_MMA(1, 0, At, B0); PG8_MMA(1, 1, At, B1); PG8_BAR; PG8_SCHED;
;         }
	s_add_i32 s4, s66, s40
	v_lshl_add_u64 v[216:217], v[216:217], 0, s[16:17]
	s_mov_b32 m0, s4
	ds_read_b128 v[180:183], v220 offset:49152
	ds_read_b128 v[184:187], v220 offset:50176
	ds_read_b128 v[188:191], v220 offset:51200
	ds_read_b128 v[192:195], v220 offset:52224
	ds_read_b128 v[196:199], v220 offset:53248
	ds_read_b128 v[200:203], v220 offset:54272
	ds_read_b128 v[208:211], v220 offset:55296
	ds_read_b128 v[212:215], v220 offset:56320
	global_load_lds_dwordx4 v[216:217], off
	s_add_i32 m0, s4, 0x2000
	s_add_u32 s4, s34, 0x158080
	v_lshl_add_u64 v[216:217], v[222:223], 0, s[16:17]
	s_addc_u32 s5, s35, 0
	s_add_i32 s34, s67, s40
	global_load_lds_dwordx4 v[216:217], off
	v_lshl_add_u64 v[216:217], s[4:5], 0, v[130:131]
	s_mov_b32 m0, s34
	s_nop 0
	global_load_lds_dwordx4 v[216:217], off
	v_lshl_add_u64 v[216:217], s[4:5], 0, v[134:135]
	s_add_i32 m0, s34, 0x2000
	s_nop 0
	global_load_lds_dwordx4 v[216:217], off
	v_lshl_add_u64 v[216:217], v[224:225], 0, s[16:17]
	s_mov_b32 m0, s47
	s_nop 0
	global_load_lds_dwordx4 v[216:217], off
	v_lshl_add_u64 v[216:217], v[226:227], 0, s[16:17]
	s_mov_b32 m0, s48
	s_nop 0
	global_load_lds_dwordx4 v[216:217], off
	s_waitcnt vmcnt(8)
	s_waitcnt lgkmcnt(0)
	s_barrier
	s_setprio 1
	s_waitcnt lgkmcnt(0)
	v_mfma_f32_16x16x32_bf16 v[60:63], v[148:151], v[180:183], v[60:63]
	v_mfma_f32_16x16x32_bf16 v[56:59], v[156:159], v[180:183], v[56:59]
	v_mfma_f32_16x16x32_bf16 v[44:47], v[164:167], v[180:183], v[44:47]
	v_mfma_f32_16x16x32_bf16 v[36:39], v[172:175], v[180:183], v[36:39]
	v_mfma_f32_16x16x32_bf16 v[20:23], v[172:175], v[188:191], v[20:23]
	v_mfma_f32_16x16x32_bf16 v[28:31], v[164:167], v[188:191], v[28:31]
	v_mfma_f32_16x16x32_bf16 v[48:51], v[156:159], v[188:191], v[48:51]
	v_mfma_f32_16x16x32_bf16 v[52:55], v[148:151], v[188:191], v[52:55]
	v_mfma_f32_16x16x32_bf16 v[40:43], v[148:151], v[196:199], v[40:43]
	v_mfma_f32_16x16x32_bf16 v[32:35], v[156:159], v[196:199], v[32:35]
	v_mfma_f32_16x16x32_bf16 v[12:15], v[164:167], v[196:199], v[12:15]
	v_mfma_f32_16x16x32_bf16 v[8:11], v[172:175], v[196:199], v[8:11]
	v_mfma_f32_16x16x32_bf16 v[0:3], v[172:175], v[208:211], v[0:3]
	v_mfma_f32_16x16x32_bf16 v[4:7], v[164:167], v[208:211], v[4:7]
	v_mfma_f32_16x16x32_bf16 v[16:19], v[156:159], v[208:211], v[16:19]
	v_mfma_f32_16x16x32_bf16 v[24:27], v[148:151], v[208:211], v[24:27]
	s_setprio 0
	s_setprio 1
	v_mfma_f32_16x16x32_bf16 v[60:63], v[152:155], v[184:187], v[60:63]
	v_mfma_f32_16x16x32_bf16 v[56:59], v[160:163], v[184:187], v[56:59]
	v_mfma_f32_16x16x32_bf16 v[44:47], v[168:171], v[184:187], v[44:47]
	v_mfma_f32_16x16x32_bf16 v[36:39], v[176:179], v[184:187], v[36:39]
	v_mfma_f32_16x16x32_bf16 v[20:23], v[176:179], v[192:195], v[20:23]
	v_mfma_f32_16x16x32_bf16 v[28:31], v[168:171], v[192:195], v[28:31]
	v_mfma_f32_16x16x32_bf16 v[48:51], v[160:163], v[192:195], v[48:51]
	v_mfma_f32_16x16x32_bf16 v[52:55], v[152:155], v[192:195], v[52:55]
	v_mfma_f32_16x16x32_bf16 v[40:43], v[152:155], v[200:203], v[40:43]
	v_mfma_f32_16x16x32_bf16 v[32:35], v[160:163], v[200:203], v[32:35]
	v_mfma_f32_16x16x32_bf16 v[12:15], v[168:171], v[200:203], v[12:15]
	v_mfma_f32_16x16x32_bf16 v[8:11], v[176:179], v[200:203], v[8:11]
	v_mfma_f32_16x16x32_bf16 v[0:3], v[176:179], v[212:215], v[0:3]
	v_mfma_f32_16x16x32_bf16 v[4:7], v[168:171], v[212:215], v[4:7]
	v_mfma_f32_16x16x32_bf16 v[16:19], v[160:163], v[212:215], v[16:19]
	v_mfma_f32_16x16x32_bf16 v[24:27], v[152:155], v[212:215], v[24:27]
	s_setprio 0
	s_barrier
	s_add_u32 s1, s1, 0x100
	s_addc_u32 s64, s64, 0
	s_cmp_ge_i32 s65, s46
	s_mov_b64 s[4:5], s[30:31]
	s_mov_b32 s34, s65
	s_cbranch_scc0 .LBB0_445
	v_pk_mul_f32 v[164:165], v[126:127], 0.5 op_sel_hi:[1,0]
	v_pk_mul_f32 v[200:201], v[124:125], 0.5 op_sel_hi:[1,0]
	v_pk_mul_f32 v[202:203], v[122:123], 0.5 op_sel_hi:[1,0]
	v_pk_mul_f32 v[208:209], v[120:121], 0.5 op_sel_hi:[1,0]
	v_pk_mul_f32 v[210:211], v[110:111], 0.5 op_sel_hi:[1,0]
	v_pk_mul_f32 v[212:213], v[108:109], 0.5 op_sel_hi:[1,0]
	v_pk_mul_f32 v[214:215], v[102:103], 0.5 op_sel_hi:[1,0]
	v_pk_mul_f32 v[216:217], v[100:101], 0.5 op_sel_hi:[1,0]
	v_pk_mul_f32 v[188:189], v[118:119], 0.5 op_sel_hi:[1,0]
	v_pk_mul_f32 v[186:187], v[116:117], 0.5 op_sel_hi:[1,0]
	v_pk_mul_f32 v[184:185], v[114:115], 0.5 op_sel_hi:[1,0]
	v_pk_mul_f32 v[182:183], v[112:113], 0.5 op_sel_hi:[1,0]
	v_pk_mul_f32 v[196:197], v[94:95], 0.5 op_sel_hi:[1,0]
	v_pk_mul_f32 v[194:195], v[92:93], 0.5 op_sel_hi:[1,0]
	v_pk_mul_f32 v[192:193], v[86:87], 0.5 op_sel_hi:[1,0]
	v_pk_mul_f32 v[190:191], v[84:85], 0.5 op_sel_hi:[1,0]
	v_pk_mul_f32 v[166:167], v[106:107], 0.5 op_sel_hi:[1,0]
	v_pk_mul_f32 v[168:169], v[104:105], 0.5 op_sel_hi:[1,0]
	v_pk_mul_f32 v[170:171], v[98:99], 0.5 op_sel_hi:[1,0]
	v_pk_mul_f32 v[172:173], v[96:97], 0.5 op_sel_hi:[1,0]
	v_pk_mul_f32 v[174:175], v[78:79], 0.5 op_sel_hi:[1,0]
	v_pk_mul_f32 v[176:177], v[76:77], 0.5 op_sel_hi:[1,0]
	v_pk_mul_f32 v[178:179], v[74:75], 0.5 op_sel_hi:[1,0]
	v_pk_mul_f32 v[180:181], v[72:73], 0.5 op_sel_hi:[1,0]
	v_pk_mul_f32 v[154:155], v[90:91], 0.5 op_sel_hi:[1,0]
	v_pk_mul_f32 v[152:153], v[88:89], 0.5 op_sel_hi:[1,0]
	v_pk_mul_f32 v[150:151], v[82:83], 0.5 op_sel_hi:[1,0]
	v_pk_mul_f32 v[148:149], v[80:81], 0.5 op_sel_hi:[1,0]
	v_pk_mul_f32 v[162:163], v[70:71], 0.5 op_sel_hi:[1,0]
	v_pk_mul_f32 v[160:161], v[68:69], 0.5 op_sel_hi:[1,0]
	v_pk_mul_f32 v[158:159], v[66:67], 0.5 op_sel_hi:[1,0]
	v_pk_mul_f32 v[156:157], v[64:65], 0.5 op_sel_hi:[1,0]
	v_pk_mul_f32 v[112:113], v[62:63], 0.5 op_sel_hi:[1,0]
	v_pk_mul_f32 v[114:115], v[60:61], 0.5 op_sel_hi:[1,0]
	v_pk_mul_f32 v[116:117], v[58:59], 0.5 op_sel_hi:[1,0]
	v_pk_mul_f32 v[118:119], v[56:57], 0.5 op_sel_hi:[1,0]
	v_pk_mul_f32 v[120:121], v[46:47], 0.5 op_sel_hi:[1,0]
	v_pk_mul_f32 v[122:123], v[44:45], 0.5 op_sel_hi:[1,0]
	v_pk_mul_f32 v[124:125], v[38:39], 0.5 op_sel_hi:[1,0]
	v_pk_mul_f32 v[126:127], v[36:37], 0.5 op_sel_hi:[1,0]
	v_pk_mul_f32 v[102:103], v[54:55], 0.5 op_sel_hi:[1,0]
	v_pk_mul_f32 v[100:101], v[52:53], 0.5 op_sel_hi:[1,0]
	v_pk_mul_f32 v[98:99], v[50:51], 0.5 op_sel_hi:[1,0]
	v_pk_mul_f32 v[96:97], v[48:49], 0.5 op_sel_hi:[1,0]
	v_pk_mul_f32 v[110:111], v[30:31], 0.5 op_sel_hi:[1,0]
	v_pk_mul_f32 v[108:109], v[28:29], 0.5 op_sel_hi:[1,0]
	v_pk_mul_f32 v[106:107], v[22:23], 0.5 op_sel_hi:[1,0]
	v_pk_mul_f32 v[104:105], v[20:21], 0.5 op_sel_hi:[1,0]
	v_pk_mul_f32 v[86:87], v[42:43], 0.5 op_sel_hi:[1,0]
	v_pk_mul_f32 v[84:85], v[40:41], 0.5 op_sel_hi:[1,0]
	v_pk_mul_f32 v[82:83], v[34:35], 0.5 op_sel_hi:[1,0]
	v_pk_mul_f32 v[80:81], v[32:33], 0.5 op_sel_hi:[1,0]
	v_pk_mul_f32 v[94:95], v[14:15], 0.5 op_sel_hi:[1,0]
	v_pk_mul_f32 v[92:93], v[12:13], 0.5 op_sel_hi:[1,0]
	v_pk_mul_f32 v[90:91], v[10:11], 0.5 op_sel_hi:[1,0]
	v_pk_mul_f32 v[88:89], v[8:9], 0.5 op_sel_hi:[1,0]
	v_pk_mul_f32 v[70:71], v[26:27], 0.5 op_sel_hi:[1,0]
	v_pk_mul_f32 v[68:69], v[24:25], 0.5 op_sel_hi:[1,0]
	v_pk_mul_f32 v[66:67], v[18:19], 0.5 op_sel_hi:[1,0]
	v_pk_mul_f32 v[64:65], v[16:17], 0.5 op_sel_hi:[1,0]
	v_pk_mul_f32 v[78:79], v[6:7], 0.5 op_sel_hi:[1,0]
	v_pk_mul_f32 v[76:77], v[4:5], 0.5 op_sel_hi:[1,0]
	v_pk_mul_f32 v[74:75], v[2:3], 0.5 op_sel_hi:[1,0]
	v_pk_mul_f32 v[72:73], v[0:1], 0.5 op_sel_hi:[1,0]

; #define PG8_STAGE(bufoff, gbase, voff) do { _Pragma("unroll") for (int _i = 0; _i < 2; ++_i) \
;         __builtin_amdgcn_global_load_lds((const unsigned*)((const char*)(gbase) + (voff)[_i]), (LAS unsigned*)(lds + (bufoff) + ldsw + _i * 8192), 16, 0, 0); } while (0)
; #define PG8_LDA(dst, b, h) do { _Pragma("unroll") for (int m = 0; m < 4; ++m) _Pragma("unroll") for (int k = 0; k < 2; ++k) dst[m][k] = *(const LAS bf16x8*)(lds + PG8_SA(b, h) + aoff + m * 2048 + k * 1024); } while (0)
; #define PG8_LDB(dst, b, h) do { _Pragma("unroll") for (int n = 0; n < 2; ++n) _Pragma("unroll") for (int k = 0; k < 2; ++k) dst[n][k] = *(const LAS bf16x8*)(lds + PG8_SB(b, h) + boff + n * 2048 + k * 1024); } while (0)
; #define PG8_MMA(ai, bj, At, Bt) do { __builtin_amdgcn_s_setprio(1); _Pragma("unroll") for (int m = 0; m < 4; ++m) _Pragma("unroll") for (int n = 0; n < 2; ++n) _Pragma("unroll") for (int k = 0; k < 2; ++k) \
;         acc[ai][bj][m][n] = __builtin_amdgcn_mfma_f32_16x16x32_bf16(Bt[n][k], At[m][k], acc[ai][bj][m][n], 0, 0, 0); __builtin_amdgcn_s_setprio(0); } while (0)
; #define PG8_WAIT_V(n) asm volatile("s_waitcnt vmcnt(" #n ")" ::: "memory")
; #define PG8_WAIT_L(n) asm volatile("s_waitcnt lgkmcnt(" #n ")" ::: "memory")
; #define PG8_BAR __builtin_amdgcn_s_barrier()
; #define PG8_SCHED __builtin_amdgcn_sched_barrier(0)
; template <class Epi>
; __device__ __forceinline__ void gemm_phase(LAS unsigned char* lds, const Gemm g, const StaticOrder& S, const Epi& E) {
;     ...
;         for (int t = 0; t < nt; t += 2) {
;             const bool last = (t == nt - 2);
;             const char* a1 = cA + (size_t)(t + 1) * kstep;
;             const char* a2 = last ? nA : cA + (size_t)(t + 2) * kstep; const char* b2 = last ? nB : cB + (size_t)(t + 2) * kstep;
;             const char* a3 = a2 + kstep; const char* b3 = b2 + kstep;
;             PG8_LDB(B0, 0, 0); PG8_LDB(B1, 0, 1); PG8_SCHED; PG8_LDA(At, 0, 0); PG8_STAGE(PG8_SA(1, 1), a1 + hstepA, voffA);
;             PG8_WAIT_V(8); PG8_WAIT_L(0); PG8_BAR; PG8_MMA(0, 0, At, B0); PG8_MMA(0, 1, At, B1); PG8_BAR; PG8_SCHED;
;             PG8_LDA(At, 0, 1); PG8_STAGE(PG8_SB(0, 0), b2, voffB); PG8_STAGE(PG8_SB(0, 1), b2 + hstepB, voffB); PG8_STAGE(PG8_SA(0, 0), a2, voffA);
;             PG8_WAIT_V(8); PG8_WAIT_L(0); PG8_BAR; PG8_MMA(1, 0, At, B0); PG8_MMA(1, 1, At, B1); PG8_BAR; PG8_SCHED;
.LBB0_541:
	ds_read_b128 v[148:151], v155
	ds_read_b128 v[160:163], v155 offset:1024
	ds_read_b128 v[164:167], v155 offset:2048
	ds_read_b128 v[168:171], v155 offset:3072
	ds_read_b128 v[172:175], v156
	ds_read_b128 v[176:179], v156 offset:1024
	ds_read_b128 v[180:183], v156 offset:2048
	ds_read_b128 v[184:187], v156 offset:3072
	s_add_i32 s35, s26, 2
	s_add_u32 s27, s8, 0xfff80080
	s_addc_u32 s30, s9, -1
	s_cmp_eq_u32 s49, s26
	s_cselect_b32 s26, s21, s33
	s_cselect_b32 s31, s1, s30
	s_cselect_b32 s30, s5, s27
	s_cselect_b32 s27, s19, s34
	v_lshl_add_u64 v[224:225], s[8:9], 0, v[140:141]
	s_add_i32 m0, s39, 0xc000
	ds_read_b128 v[188:191], v157
	ds_read_b128 v[192:195], v157 offset:1024
	ds_read_b128 v[196:199], v157 offset:2048
	ds_read_b128 v[200:203], v157 offset:3072
	ds_read_b128 v[208:211], v157 offset:4096
	ds_read_b128 v[212:215], v157 offset:5120
	ds_read_b128 v[216:219], v157 offset:6144
	ds_read_b128 v[220:223], v157 offset:7168
	global_load_lds_dwordx4 v[224:225], off
	v_lshl_add_u64 v[224:225], s[8:9], 0, v[142:143]
	s_add_i32 m0, s39, 0xe000
	s_nop 0
	global_load_lds_dwordx4 v[224:225], off
	s_waitcnt vmcnt(8)
	s_waitcnt lgkmcnt(0)
	s_barrier
	s_setprio 1
	s_waitcnt lgkmcnt(0)
	v_mfma_f32_16x16x32_bf16 v[120:123], v[148:151], v[188:191], v[120:123]
	v_mfma_f32_16x16x32_bf16 v[124:127], v[164:167], v[188:191], v[124:127]
	v_mfma_f32_16x16x32_bf16 v[116:119], v[172:175], v[188:191], v[116:119]
	v_mfma_f32_16x16x32_bf16 v[112:115], v[180:183], v[188:191], v[112:115]
	v_mfma_f32_16x16x32_bf16 v[96:99], v[180:183], v[196:199], v[96:99]
	v_mfma_f32_16x16x32_bf16 v[100:103], v[172:175], v[196:199], v[100:103]
	v_mfma_f32_16x16x32_bf16 v[104:107], v[164:167], v[196:199], v[104:107]
	v_mfma_f32_16x16x32_bf16 v[108:111], v[148:151], v[196:199], v[108:111]
	v_mfma_f32_16x16x32_bf16 v[92:95], v[148:151], v[208:211], v[92:95]
	v_mfma_f32_16x16x32_bf16 v[88:91], v[164:167], v[208:211], v[88:91]
	v_mfma_f32_16x16x32_bf16 v[84:87], v[172:175], v[208:211], v[84:87]
	v_mfma_f32_16x16x32_bf16 v[80:83], v[180:183], v[208:211], v[80:83]
	v_mfma_f32_16x16x32_bf16 v[64:67], v[180:183], v[216:219], v[64:67]
	v_mfma_f32_16x16x32_bf16 v[68:71], v[172:175], v[216:219], v[68:71]
	v_mfma_f32_16x16x32_bf16 v[72:75], v[164:167], v[216:219], v[72:75]
	v_mfma_f32_16x16x32_bf16 v[76:79], v[148:151], v[216:219], v[76:79]
	s_setprio 0
	s_setprio 1
	v_mfma_f32_16x16x32_bf16 v[120:123], v[160:163], v[192:195], v[120:123]
	v_mfma_f32_16x16x32_bf16 v[124:127], v[168:171], v[192:195], v[124:127]
	v_mfma_f32_16x16x32_bf16 v[116:119], v[176:179], v[192:195], v[116:119]
	v_mfma_f32_16x16x32_bf16 v[112:115], v[184:187], v[192:195], v[112:115]
	v_mfma_f32_16x16x32_bf16 v[96:99], v[184:187], v[200:203], v[96:99]
	v_mfma_f32_16x16x32_bf16 v[100:103], v[176:179], v[200:203], v[100:103]
	v_mfma_f32_16x16x32_bf16 v[104:107], v[168:171], v[200:203], v[104:107]
	v_mfma_f32_16x16x32_bf16 v[108:111], v[160:163], v[200:203], v[108:111]
	v_mfma_f32_16x16x32_bf16 v[92:95], v[160:163], v[212:215], v[92:95]
	v_mfma_f32_16x16x32_bf16 v[88:91], v[168:171], v[212:215], v[88:91]
	v_mfma_f32_16x16x32_bf16 v[84:87], v[176:179], v[212:215], v[84:87]
	v_mfma_f32_16x16x32_bf16 v[80:83], v[184:187], v[212:215], v[80:83]
	v_mfma_f32_16x16x32_bf16 v[64:67], v[184:187], v[220:223], v[64:67]
	v_mfma_f32_16x16x32_bf16 v[68:71], v[176:179], v[220:223], v[68:71]
	v_mfma_f32_16x16x32_bf16 v[72:75], v[168:171], v[220:223], v[72:75]
	v_mfma_f32_16x16x32_bf16 v[76:79], v[160:163], v[220:223], v[76:79]
	s_setprio 0
	s_barrier
	s_add_i32 s58, s54, s38
	v_lshl_add_u64 v[224:225], s[26:27], 0, v[130:131]
	s_mov_b32 m0, s58
	ds_read_b128 v[188:191], v157 offset:16384
	ds_read_b128 v[192:195], v157 offset:17408
	ds_read_b128 v[196:199], v157 offset:18432
	ds_read_b128 v[200:203], v157 offset:19456
	ds_read_b128 v[208:211], v157 offset:20480
	ds_read_b128 v[212:215], v157 offset:21504
	ds_read_b128 v[216:219], v157 offset:22528
	ds_read_b128 v[220:223], v157 offset:23552
	global_load_lds_dwordx4 v[224:225], off
	s_add_i32 m0, s58, 0x2000
	s_add_u32 s58, s26, 0x80000
	v_lshl_add_u64 v[226:227], s[26:27], 0, v[134:135]
	s_addc_u32 s59, s27, 0
	s_add_i32 s60, s55, s38
	global_load_lds_dwordx4 v[226:227], off
	v_lshl_add_u64 v[230:231], s[58:59], 0, v[130:131]
	s_mov_b32 m0, s60
	v_lshl_add_u64 v[232:233], s[30:31], 0, v[132:133]
	global_load_lds_dwordx4 v[230:231], off
	v_lshl_add_u64 v[230:231], s[58:59], 0, v[134:135]
	s_add_i32 m0, s60, 0x2000
	s_nop 0
	global_load_lds_dwordx4 v[230:231], off
	v_lshl_add_u64 v[230:231], s[30:31], 0, v[128:129]
	s_mov_b32 m0, s39
	s_nop 0
	global_load_lds_dwordx4 v[230:231], off
	s_mov_b32 m0, s40
	s_nop 0
	global_load_lds_dwordx4 v[232:233], off
	s_waitcnt vmcnt(8)
	s_waitcnt lgkmcnt(0)
	s_barrier
; #define PG8_STAGE(bufoff, gbase, voff) do { _Pragma("unroll") for (int _i = 0; _i < 2; ++_i) \
;         __builtin_amdgcn_global_load_lds((const unsigned*)((const char*)(gbase) + (voff)[_i]), (LAS unsigned*)(lds + (bufoff) + ldsw + _i * 8192), 16, 0, 0); } while (0)
; #define PG8_LDA(dst, b, h) do { _Pragma("unroll") for (int m = 0; m < 4; ++m) _Pragma("unroll") for (int k = 0; k < 2; ++k) dst[m][k] = *(const LAS bf16x8*)(lds + PG8_SA(b, h) + aoff + m * 2048 + k * 1024); } while (0)
; #define PG8_LDB(dst, b, h) do { _Pragma("unroll") for (int n = 0; n < 2; ++n) _Pragma("unroll") for (int k = 0; k < 2; ++k) dst[n][k] = *(const LAS bf16x8*)(lds + PG8_SB(b, h) + boff + n * 2048 + k * 1024); } while (0)
; #define PG8_MMA(ai, bj, At, Bt) do { __builtin_amdgcn_s_setprio(1); _Pragma("unroll") for (int m = 0; m < 4; ++m) _Pragma("unroll") for (int n = 0; n < 2; ++n) _Pragma("unroll") for (int k = 0; k < 2; ++k) \
;         acc[ai][bj][m][n] = __builtin_amdgcn_mfma_f32_16x16x32_bf16(Bt[n][k], At[m][k], acc[ai][bj][m][n], 0, 0, 0); __builtin_amdgcn_s_setprio(0); } while (0)
; #define PG8_WAIT_V(n) asm volatile("s_waitcnt vmcnt(" #n ")" ::: "memory")
; #define PG8_WAIT_L(n) asm volatile("s_waitcnt lgkmcnt(" #n ")" ::: "memory")
; #define PG8_BAR __builtin_amdgcn_s_barrier()
; #define PG8_SCHED __builtin_amdgcn_sched_barrier(0)
; template <class Epi>
; __device__ __forceinline__ void gemm_phase(LAS unsigned char* lds, const Gemm g, const StaticOrder& S, const Epi& E) {
;     ...
;             PG8_WAIT_V(8); PG8_WAIT_L(0); PG8_BAR; PG8_MMA(1, 0, At, B0); PG8_MMA(1, 1, At, B1); PG8_BAR; PG8_SCHED;
;             PG8_LDB(B0, 1, 0); PG8_LDB(B1, 1, 1); PG8_SCHED; PG8_LDA(At, 1, 0); PG8_STAGE(PG8_SA(0, 1), a2 + hstepA, voffA);
;             PG8_WAIT_V(8); PG8_WAIT_L(0); PG8_BAR; PG8_MMA(0, 0, At, B0); PG8_MMA(0, 1, At, B1); PG8_BAR; PG8_SCHED;
	s_setprio 1
	s_waitcnt lgkmcnt(0)
	v_mfma_f32_16x16x32_bf16 v[60:63], v[148:151], v[188:191], v[60:63]
	v_mfma_f32_16x16x32_bf16 v[56:59], v[164:167], v[188:191], v[56:59]
	v_mfma_f32_16x16x32_bf16 v[52:55], v[172:175], v[188:191], v[52:55]
	v_mfma_f32_16x16x32_bf16 v[48:51], v[180:183], v[188:191], v[48:51]
	v_mfma_f32_16x16x32_bf16 v[32:35], v[180:183], v[196:199], v[32:35]
	v_mfma_f32_16x16x32_bf16 v[36:39], v[172:175], v[196:199], v[36:39]
	v_mfma_f32_16x16x32_bf16 v[40:43], v[164:167], v[196:199], v[40:43]
	v_mfma_f32_16x16x32_bf16 v[44:47], v[148:151], v[196:199], v[44:47]
	v_mfma_f32_16x16x32_bf16 v[28:31], v[148:151], v[208:211], v[28:31]
	v_mfma_f32_16x16x32_bf16 v[24:27], v[164:167], v[208:211], v[24:27]
	v_mfma_f32_16x16x32_bf16 v[20:23], v[172:175], v[208:211], v[20:23]
	v_mfma_f32_16x16x32_bf16 v[16:19], v[180:183], v[208:211], v[16:19]
	v_mfma_f32_16x16x32_bf16 v[0:3], v[180:183], v[216:219], v[0:3]
	v_mfma_f32_16x16x32_bf16 v[4:7], v[172:175], v[216:219], v[4:7]
	v_mfma_f32_16x16x32_bf16 v[8:11], v[164:167], v[216:219], v[8:11]
	v_mfma_f32_16x16x32_bf16 v[12:15], v[148:151], v[216:219], v[12:15]
	s_setprio 0
	s_setprio 1
	v_mfma_f32_16x16x32_bf16 v[60:63], v[160:163], v[192:195], v[60:63]
	v_mfma_f32_16x16x32_bf16 v[56:59], v[168:171], v[192:195], v[56:59]
	v_mfma_f32_16x16x32_bf16 v[52:55], v[176:179], v[192:195], v[52:55]
	v_mfma_f32_16x16x32_bf16 v[48:51], v[184:187], v[192:195], v[48:51]
	v_mfma_f32_16x16x32_bf16 v[32:35], v[184:187], v[200:203], v[32:35]
	v_mfma_f32_16x16x32_bf16 v[36:39], v[176:179], v[200:203], v[36:39]
	v_mfma_f32_16x16x32_bf16 v[40:43], v[168:171], v[200:203], v[40:43]
	v_mfma_f32_16x16x32_bf16 v[44:47], v[160:163], v[200:203], v[44:47]
	v_mfma_f32_16x16x32_bf16 v[28:31], v[160:163], v[212:215], v[28:31]
	v_mfma_f32_16x16x32_bf16 v[24:27], v[168:171], v[212:215], v[24:27]
	v_mfma_f32_16x16x32_bf16 v[20:23], v[176:179], v[212:215], v[20:23]
	v_mfma_f32_16x16x32_bf16 v[16:19], v[184:187], v[212:215], v[16:19]
	v_mfma_f32_16x16x32_bf16 v[0:3], v[184:187], v[220:223], v[0:3]
	v_mfma_f32_16x16x32_bf16 v[4:7], v[176:179], v[220:223], v[4:7]
	v_mfma_f32_16x16x32_bf16 v[8:11], v[168:171], v[220:223], v[8:11]
	v_mfma_f32_16x16x32_bf16 v[12:15], v[160:163], v[220:223], v[12:15]
	s_setprio 0
	s_barrier
	s_add_i32 s58, 0, 0x18000
	v_add_u32_e32 v136, s58, v154
	s_add_i32 s59, 0, 0x1c000
	ds_read_b128 v[148:151], v136
	ds_read_b128 v[160:163], v136 offset:1024
	ds_read_b128 v[164:167], v136 offset:2048
	ds_read_b128 v[168:171], v136 offset:3072
	v_add_u32_e32 v136, s59, v154
	ds_read_b128 v[172:175], v136
	ds_read_b128 v[176:179], v136 offset:1024
	ds_read_b128 v[180:183], v136 offset:2048
	ds_read_b128 v[184:187], v136 offset:3072
	s_add_u32 s30, s30, 0x80000
	s_addc_u32 s31, s31, 0
	s_mov_b32 m0, s41
	v_lshl_add_u64 v[234:235], s[30:31], 0, v[128:129]
	ds_read_b128 v[188:191], v157 offset:32768
	ds_read_b128 v[192:195], v157 offset:33792
	ds_read_b128 v[196:199], v157 offset:34816
	ds_read_b128 v[200:203], v157 offset:35840
	ds_read_b128 v[208:211], v157 offset:36864
	ds_read_b128 v[212:215], v157 offset:37888
	ds_read_b128 v[216:219], v157 offset:38912
	ds_read_b128 v[220:223], v157 offset:39936
	global_load_lds_dwordx4 v[234:235], off
	v_lshl_add_u64 v[234:235], s[30:31], 0, v[132:133]
	s_mov_b32 m0, s42
	s_nop 0
	global_load_lds_dwordx4 v[234:235], off
	s_waitcnt vmcnt(8)
	s_waitcnt lgkmcnt(0)
	s_barrier
	s_setprio 1
	s_waitcnt lgkmcnt(0)
	v_mfma_f32_16x16x32_bf16 v[120:123], v[148:151], v[188:191], v[120:123]
	v_mfma_f32_16x16x32_bf16 v[124:127], v[164:167], v[188:191], v[124:127]
	v_mfma_f32_16x16x32_bf16 v[116:119], v[172:175], v[188:191], v[116:119]
	v_mfma_f32_16x16x32_bf16 v[112:115], v[180:183], v[188:191], v[112:115]
	v_mfma_f32_16x16x32_bf16 v[96:99], v[180:183], v[196:199], v[96:99]
	v_mfma_f32_16x16x32_bf16 v[100:103], v[172:175], v[196:199], v[100:103]
	v_mfma_f32_16x16x32_bf16 v[104:107], v[164:167], v[196:199], v[104:107]
	v_mfma_f32_16x16x32_bf16 v[108:111], v[148:151], v[196:199], v[108:111]
	v_mfma_f32_16x16x32_bf16 v[92:95], v[148:151], v[208:211], v[92:95]
	v_mfma_f32_16x16x32_bf16 v[88:91], v[164:167], v[208:211], v[88:91]
	v_mfma_f32_16x16x32_bf16 v[84:87], v[172:175], v[208:211], v[84:87]
	v_mfma_f32_16x16x32_bf16 v[80:83], v[180:183], v[208:211], v[80:83]
	v_mfma_f32_16x16x32_bf16 v[64:67], v[180:183], v[216:219], v[64:67]
	v_mfma_f32_16x16x32_bf16 v[68:71], v[172:175], v[216:219], v[68:71]
	v_mfma_f32_16x16x32_bf16 v[72:75], v[164:167], v[216:219], v[72:75]
	v_mfma_f32_16x16x32_bf16 v[76:79], v[148:151], v[216:219], v[76:79]
	s_setprio 0
	s_setprio 1
	v_mfma_f32_16x16x32_bf16 v[120:123], v[160:163], v[192:195], v[120:123]
	v_mfma_f32_16x16x32_bf16 v[124:127], v[168:171], v[192:195], v[124:127]
	v_mfma_f32_16x16x32_bf16 v[116:119], v[176:179], v[192:195], v[116:119]
	v_mfma_f32_16x16x32_bf16 v[112:115], v[184:187], v[192:195], v[112:115]
	v_mfma_f32_16x16x32_bf16 v[96:99], v[184:187], v[200:203], v[96:99]
	v_mfma_f32_16x16x32_bf16 v[100:103], v[176:179], v[200:203], v[100:103]
	v_mfma_f32_16x16x32_bf16 v[104:107], v[168:171], v[200:203], v[104:107]
	v_mfma_f32_16x16x32_bf16 v[108:111], v[160:163], v[200:203], v[108:111]
	v_mfma_f32_16x16x32_bf16 v[92:95], v[160:163], v[212:215], v[92:95]
	v_mfma_f32_16x16x32_bf16 v[88:91], v[168:171], v[212:215], v[88:91]
	v_mfma_f32_16x16x32_bf16 v[84:87], v[176:179], v[212:215], v[84:87]
	v_mfma_f32_16x16x32_bf16 v[80:83], v[184:187], v[212:215], v[80:83]
	v_mfma_f32_16x16x32_bf16 v[64:67], v[184:187], v[220:223], v[64:67]
	v_mfma_f32_16x16x32_bf16 v[68:71], v[176:179], v[220:223], v[68:71]
	v_mfma_f32_16x16x32_bf16 v[72:75], v[168:171], v[220:223], v[72:75]
	v_mfma_f32_16x16x32_bf16 v[76:79], v[160:163], v[220:223], v[76:79]
	s_setprio 0
	s_barrier
; #define PG8_STAGE(bufoff, gbase, voff) do { _Pragma("unroll") for (int _i = 0; _i < 2; ++_i) \
;         __builtin_amdgcn_global_load_lds((const unsigned*)((const char*)(gbase) + (voff)[_i]), (LAS unsigned*)(lds + (bufoff) + ldsw + _i * 8192), 16, 0, 0); } while (0)
; #define PG8_LDA(dst, b, h) do { _Pragma("unroll") for (int m = 0; m < 4; ++m) _Pragma("unroll") for (int k = 0; k < 2; ++k) dst[m][k] = *(const LAS bf16x8*)(lds + PG8_SA(b, h) + aoff + m * 2048 + k * 1024); } while (0)
; #define PG8_MMA(ai, bj, At, Bt) do { __builtin_amdgcn_s_setprio(1); _Pragma("unroll") for (int m = 0; m < 4; ++m) _Pragma("unroll") for (int n = 0; n < 2; ++n) _Pragma("unroll") for (int k = 0; k < 2; ++k) \
;         acc[ai][bj][m][n] = __builtin_amdgcn_mfma_f32_16x16x32_bf16(Bt[n][k], At[m][k], acc[ai][bj][m][n], 0, 0, 0); __builtin_amdgcn_s_setprio(0); } while (0)
; #define PG8_WAIT_V(n) asm volatile("s_waitcnt vmcnt(" #n ")" ::: "memory")
; #define PG8_WAIT_L(n) asm volatile("s_waitcnt lgkmcnt(" #n ")" ::: "memory")
; #define PG8_BAR __builtin_amdgcn_s_barrier()
; #define PG8_SCHED __builtin_amdgcn_sched_barrier(0)
; template <class Epi>
; __device__ __forceinline__ void gemm_phase(LAS unsigned char* lds, const Gemm g, const StaticOrder& S, const Epi& E) {
;     ...
;             PG8_LDA(At, 1, 1); PG8_STAGE(PG8_SB(1, 0), b3, voffB); PG8_STAGE(PG8_SB(1, 1), b3 + hstepB, voffB); PG8_STAGE(PG8_SA(1, 0), a3, voffA);
;             PG8_WAIT_V(8); PG8_WAIT_L(0); PG8_BAR; PG8_MMA(1, 0, At, B0); PG8_MMA(1, 1, At, B1); PG8_BAR; PG8_SCHED;
;         }
	s_add_i32 s30, s58, s38
	v_lshl_add_u64 v[224:225], v[224:225], 0, s[12:13]
	s_mov_b32 m0, s30
	ds_read_b128 v[188:191], v157 offset:49152
	ds_read_b128 v[192:195], v157 offset:50176
	ds_read_b128 v[196:199], v157 offset:51200
	ds_read_b128 v[200:203], v157 offset:52224
	ds_read_b128 v[208:211], v157 offset:53248
	ds_read_b128 v[212:215], v157 offset:54272
	ds_read_b128 v[216:219], v157 offset:55296
	ds_read_b128 v[220:223], v157 offset:56320
	global_load_lds_dwordx4 v[224:225], off
	s_add_i32 m0, s30, 0x2000
	s_add_u32 s26, s26, 0x80080
	v_lshl_add_u64 v[224:225], v[226:227], 0, s[12:13]
	s_addc_u32 s27, s27, 0
	s_add_i32 s30, s59, s38
	global_load_lds_dwordx4 v[224:225], off
	v_lshl_add_u64 v[224:225], s[26:27], 0, v[130:131]
	s_mov_b32 m0, s30
	s_nop 0
	global_load_lds_dwordx4 v[224:225], off
	v_lshl_add_u64 v[224:225], s[26:27], 0, v[134:135]
	s_add_i32 m0, s30, 0x2000
	s_nop 0
	global_load_lds_dwordx4 v[224:225], off
	v_lshl_add_u64 v[224:225], v[230:231], 0, s[12:13]
	s_mov_b32 m0, s47
	s_nop 0
	global_load_lds_dwordx4 v[224:225], off
	v_lshl_add_u64 v[224:225], v[232:233], 0, s[12:13]
	s_mov_b32 m0, s48
	s_nop 0
	global_load_lds_dwordx4 v[224:225], off
	s_waitcnt vmcnt(8)
	s_waitcnt lgkmcnt(0)
	s_barrier
	s_setprio 1
	s_waitcnt lgkmcnt(0)
	v_mfma_f32_16x16x32_bf16 v[60:63], v[148:151], v[188:191], v[60:63]
	v_mfma_f32_16x16x32_bf16 v[56:59], v[164:167], v[188:191], v[56:59]
	v_mfma_f32_16x16x32_bf16 v[52:55], v[172:175], v[188:191], v[52:55]
	v_mfma_f32_16x16x32_bf16 v[48:51], v[180:183], v[188:191], v[48:51]
	v_mfma_f32_16x16x32_bf16 v[32:35], v[180:183], v[196:199], v[32:35]
	v_mfma_f32_16x16x32_bf16 v[36:39], v[172:175], v[196:199], v[36:39]
	v_mfma_f32_16x16x32_bf16 v[40:43], v[164:167], v[196:199], v[40:43]
	v_mfma_f32_16x16x32_bf16 v[44:47], v[148:151], v[196:199], v[44:47]
	v_mfma_f32_16x16x32_bf16 v[28:31], v[148:151], v[208:211], v[28:31]
	v_mfma_f32_16x16x32_bf16 v[24:27], v[164:167], v[208:211], v[24:27]
	v_mfma_f32_16x16x32_bf16 v[20:23], v[172:175], v[208:211], v[20:23]
	v_mfma_f32_16x16x32_bf16 v[16:19], v[180:183], v[208:211], v[16:19]
	v_mfma_f32_16x16x32_bf16 v[0:3], v[180:183], v[216:219], v[0:3]
	v_mfma_f32_16x16x32_bf16 v[4:7], v[172:175], v[216:219], v[4:7]
	v_mfma_f32_16x16x32_bf16 v[8:11], v[164:167], v[216:219], v[8:11]
	v_mfma_f32_16x16x32_bf16 v[12:15], v[148:151], v[216:219], v[12:15]
	s_setprio 0
	s_setprio 1
	v_mfma_f32_16x16x32_bf16 v[60:63], v[160:163], v[192:195], v[60:63]
	v_mfma_f32_16x16x32_bf16 v[56:59], v[168:171], v[192:195], v[56:59]
	v_mfma_f32_16x16x32_bf16 v[52:55], v[176:179], v[192:195], v[52:55]
	v_mfma_f32_16x16x32_bf16 v[48:51], v[184:187], v[192:195], v[48:51]
	v_mfma_f32_16x16x32_bf16 v[32:35], v[184:187], v[200:203], v[32:35]
	v_mfma_f32_16x16x32_bf16 v[36:39], v[176:179], v[200:203], v[36:39]
	v_mfma_f32_16x16x32_bf16 v[40:43], v[168:171], v[200:203], v[40:43]
	v_mfma_f32_16x16x32_bf16 v[44:47], v[160:163], v[200:203], v[44:47]
	v_mfma_f32_16x16x32_bf16 v[28:31], v[160:163], v[212:215], v[28:31]
	v_mfma_f32_16x16x32_bf16 v[24:27], v[168:171], v[212:215], v[24:27]
	v_mfma_f32_16x16x32_bf16 v[20:23], v[176:179], v[212:215], v[20:23]
	v_mfma_f32_16x16x32_bf16 v[16:19], v[184:187], v[212:215], v[16:19]
	v_mfma_f32_16x16x32_bf16 v[0:3], v[184:187], v[220:223], v[0:3]
	v_mfma_f32_16x16x32_bf16 v[4:7], v[176:179], v[220:223], v[4:7]
	v_mfma_f32_16x16x32_bf16 v[8:11], v[168:171], v[220:223], v[8:11]
	v_mfma_f32_16x16x32_bf16 v[12:15], v[160:163], v[220:223], v[12:15]
	s_setprio 0
	s_barrier
	s_add_u32 s8, s8, 0x100
	s_addc_u32 s9, s9, 0
	s_add_u32 s33, s33, 0x100
	s_addc_u32 s34, s34, 0
	s_cmp_ge_i32 s35, s44
	s_mov_b32 s26, s35
	s_cbranch_scc0 .LBB0_541

; #define PG8_STAGE(bufoff, gbase, voff) do { _Pragma("unroll") for (int _i = 0; _i < 2; ++_i) \
;         __builtin_amdgcn_global_load_lds((const unsigned*)((const char*)(gbase) + (voff)[_i]), (LAS unsigned*)(lds + (bufoff) + ldsw + _i * 8192), 16, 0, 0); } while (0)
; #define PG8_LDA(dst, b, h) do { _Pragma("unroll") for (int m = 0; m < 4; ++m) _Pragma("unroll") for (int k = 0; k < 2; ++k) dst[m][k] = *(const LAS bf16x8*)(lds + PG8_SA(b, h) + aoff + m * 2048 + k * 1024); } while (0)
; #define PG8_LDB(dst, b, h) do { _Pragma("unroll") for (int n = 0; n < 2; ++n) _Pragma("unroll") for (int k = 0; k < 2; ++k) dst[n][k] = *(const LAS bf16x8*)(lds + PG8_SB(b, h) + boff + n * 2048 + k * 1024); } while (0)
; #define PG8_MMA(ai, bj, At, Bt) do { __builtin_amdgcn_s_setprio(1); _Pragma("unroll") for (int m = 0; m < 4; ++m) _Pragma("unroll") for (int n = 0; n < 2; ++n) _Pragma("unroll") for (int k = 0; k < 2; ++k) \
;         acc[ai][bj][m][n] = __builtin_amdgcn_mfma_f32_16x16x32_bf16(Bt[n][k], At[m][k], acc[ai][bj][m][n], 0, 0, 0); __builtin_amdgcn_s_setprio(0); } while (0)
; #define PG8_WAIT_V(n) asm volatile("s_waitcnt vmcnt(" #n ")" ::: "memory")
; #define PG8_WAIT_L(n) asm volatile("s_waitcnt lgkmcnt(" #n ")" ::: "memory")
; #define PG8_BAR __builtin_amdgcn_s_barrier()
; #define PG8_SCHED __builtin_amdgcn_sched_barrier(0)
; template <class Epi>
; __device__ __forceinline__ void gemm_phase(LAS unsigned char* lds, const Gemm g, const StaticOrder& S, const Epi& E) {
;     ...
;             PG8_LDB(B0, 0, 0); PG8_LDB(B1, 0, 1); PG8_SCHED; PG8_LDA(At, 0, 0); PG8_STAGE(PG8_SA(1, 1), a1 + hstepA, voffA);
;             PG8_WAIT_V(8); PG8_WAIT_L(0); PG8_BAR; PG8_MMA(0, 0, At, B0); PG8_MMA(0, 1, At, B1); PG8_BAR; PG8_SCHED;
;             PG8_LDA(At, 0, 1); PG8_STAGE(PG8_SB(0, 0), b2, voffB); PG8_STAGE(PG8_SB(0, 1), b2 + hstepB, voffB); PG8_STAGE(PG8_SA(0, 0), a2, voffA);
;             PG8_WAIT_V(8); PG8_WAIT_L(0); PG8_BAR; PG8_MMA(1, 0, At, B0); PG8_MMA(1, 1, At, B1); PG8_BAR; PG8_SCHED;
;             PG8_LDB(B0, 1, 0); PG8_LDB(B1, 1, 1); PG8_SCHED; PG8_LDA(At, 1, 0); PG8_STAGE(PG8_SA(0, 1), a2 + hstepA, voffA);
;             PG8_WAIT_V(8); PG8_WAIT_L(0); PG8_BAR; PG8_MMA(0, 0, At, B0); PG8_MMA(0, 1, At, B1); PG8_BAR; PG8_SCHED;
.LBB0_685:
	ds_read_b128 v[88:91], v85
	ds_read_b128 v[92:95], v85 offset:1024
	ds_read_b128 v[96:99], v85 offset:2048
	ds_read_b128 v[100:103], v85 offset:3072
	s_add_i32 s61, s34, 2
	s_add_u32 s8, s30, 0x100
	s_addc_u32 s9, s31, 0
	s_cmp_eq_u32 s53, s34
	s_cselect_b32 s34, s25, s59
	s_cselect_b32 s37, s27, s9
	s_cselect_b32 s36, s26, s8
	s_cselect_b32 s35, s17, s60
	v_lshl_add_u64 v[136:137], s[30:31], 0, v[76:77]
	s_add_i32 m0, s40, 0xc000
	ds_read_b128 v[104:107], v86
	ds_read_b128 v[108:111], v86 offset:1024
	ds_read_b128 v[112:115], v86 offset:2048
	ds_read_b128 v[116:119], v86 offset:3072
	ds_read_b128 v[120:123], v86 offset:4096
	ds_read_b128 v[124:127], v86 offset:5120
	ds_read_b128 v[128:131], v86 offset:6144
	ds_read_b128 v[132:135], v86 offset:7168
	global_load_lds_dwordx4 v[136:137], off
	v_lshl_add_u64 v[136:137], s[30:31], 0, v[78:79]
	s_add_i32 m0, s40, 0xe000
	s_nop 0
	global_load_lds_dwordx4 v[136:137], off
	s_waitcnt vmcnt(8)
	s_waitcnt lgkmcnt(0)
	s_barrier
	s_setprio 1
	s_waitcnt lgkmcnt(0)
	v_mfma_f32_16x16x32_bf16 v[60:63], v[88:91], v[104:107], v[60:63]
	v_mfma_f32_16x16x32_bf16 v[56:59], v[96:99], v[104:107], v[56:59]
	v_mfma_f32_16x16x32_bf16 v[48:51], v[96:99], v[112:115], v[48:51]
	v_mfma_f32_16x16x32_bf16 v[52:55], v[88:91], v[112:115], v[52:55]
	v_mfma_f32_16x16x32_bf16 v[44:47], v[88:91], v[120:123], v[44:47]
	v_mfma_f32_16x16x32_bf16 v[40:43], v[96:99], v[120:123], v[40:43]
	v_mfma_f32_16x16x32_bf16 v[32:35], v[96:99], v[128:131], v[32:35]
	v_mfma_f32_16x16x32_bf16 v[36:39], v[88:91], v[128:131], v[36:39]
	v_mfma_f32_16x16x32_bf16 v[60:63], v[92:95], v[108:111], v[60:63]
	v_mfma_f32_16x16x32_bf16 v[56:59], v[100:103], v[108:111], v[56:59]
	v_mfma_f32_16x16x32_bf16 v[48:51], v[100:103], v[116:119], v[48:51]
	v_mfma_f32_16x16x32_bf16 v[52:55], v[92:95], v[116:119], v[52:55]
	v_mfma_f32_16x16x32_bf16 v[44:47], v[92:95], v[124:127], v[44:47]
	v_mfma_f32_16x16x32_bf16 v[40:43], v[100:103], v[124:127], v[40:43]
	v_mfma_f32_16x16x32_bf16 v[32:35], v[100:103], v[132:135], v[32:35]
	v_mfma_f32_16x16x32_bf16 v[36:39], v[92:95], v[132:135], v[36:39]
	s_setprio 0
	s_setprio 1
	s_setprio 0
	s_barrier
	s_add_i32 s30, s56, s39
	v_lshl_add_u64 v[136:137], s[34:35], 0, v[66:67]
	s_mov_b32 m0, s30
	ds_read_b128 v[104:107], v86 offset:16384
	ds_read_b128 v[108:111], v86 offset:17408
	ds_read_b128 v[112:115], v86 offset:18432
	ds_read_b128 v[116:119], v86 offset:19456
	ds_read_b128 v[120:123], v86 offset:20480
	ds_read_b128 v[124:127], v86 offset:21504
	ds_read_b128 v[128:131], v86 offset:22528
	ds_read_b128 v[132:135], v86 offset:23552
	global_load_lds_dwordx4 v[136:137], off
	s_add_i32 m0, s30, 0x2000
	s_add_u32 s30, s34, 0x10000
	v_lshl_add_u64 v[138:139], s[34:35], 0, v[70:71]
	s_addc_u32 s31, s35, 0
	global_load_lds_dwordx4 v[138:139], off
	v_lshl_add_u64 v[140:141], s[30:31], 0, v[66:67]
	s_mov_b32 m0, s41
	v_lshl_add_u64 v[142:143], s[36:37], 0, v[68:69]
	global_load_lds_dwordx4 v[140:141], off
	v_lshl_add_u64 v[140:141], s[30:31], 0, v[70:71]
	s_mov_b32 m0, s42
	s_nop 0
	global_load_lds_dwordx4 v[140:141], off
	v_lshl_add_u64 v[140:141], s[36:37], 0, v[64:65]
	s_mov_b32 m0, s40
	s_nop 0
	global_load_lds_dwordx4 v[140:141], off
	s_mov_b32 m0, s43
	s_nop 0
	global_load_lds_dwordx4 v[142:143], off
	s_waitcnt vmcnt(8)
	s_waitcnt lgkmcnt(0)
	s_barrier
	s_setprio 1
	s_waitcnt lgkmcnt(0)
	v_mfma_f32_16x16x32_bf16 v[28:31], v[88:91], v[104:107], v[28:31]
	v_mfma_f32_16x16x32_bf16 v[24:27], v[96:99], v[104:107], v[24:27]
	v_mfma_f32_16x16x32_bf16 v[16:19], v[96:99], v[112:115], v[16:19]
	v_mfma_f32_16x16x32_bf16 v[20:23], v[88:91], v[112:115], v[20:23]
	v_mfma_f32_16x16x32_bf16 v[12:15], v[88:91], v[120:123], v[12:15]
	v_mfma_f32_16x16x32_bf16 v[8:11], v[96:99], v[120:123], v[8:11]
	v_mfma_f32_16x16x32_bf16 v[0:3], v[96:99], v[128:131], v[0:3]
	v_mfma_f32_16x16x32_bf16 v[4:7], v[88:91], v[128:131], v[4:7]
	v_mfma_f32_16x16x32_bf16 v[28:31], v[92:95], v[108:111], v[28:31]
	v_mfma_f32_16x16x32_bf16 v[24:27], v[100:103], v[108:111], v[24:27]
	v_mfma_f32_16x16x32_bf16 v[16:19], v[100:103], v[116:119], v[16:19]
	v_mfma_f32_16x16x32_bf16 v[20:23], v[92:95], v[116:119], v[20:23]
	v_mfma_f32_16x16x32_bf16 v[12:15], v[92:95], v[124:127], v[12:15]
	v_mfma_f32_16x16x32_bf16 v[8:11], v[100:103], v[124:127], v[8:11]
	v_mfma_f32_16x16x32_bf16 v[0:3], v[100:103], v[132:135], v[0:3]
	v_mfma_f32_16x16x32_bf16 v[4:7], v[92:95], v[132:135], v[4:7]
	s_setprio 0
	s_setprio 1
	s_setprio 0
	s_barrier
; #define PG8_STAGE(bufoff, gbase, voff) do { _Pragma("unroll") for (int _i = 0; _i < 2; ++_i) \
;         __builtin_amdgcn_global_load_lds((const unsigned*)((const char*)(gbase) + (voff)[_i]), (LAS unsigned*)(lds + (bufoff) + ldsw + _i * 8192), 16, 0, 0); } while (0)
; #define PG8_LDA(dst, b, h) do { _Pragma("unroll") for (int m = 0; m < 4; ++m) _Pragma("unroll") for (int k = 0; k < 2; ++k) dst[m][k] = *(const LAS bf16x8*)(lds + PG8_SA(b, h) + aoff + m * 2048 + k * 1024); } while (0)
; #define PG8_MMA(ai, bj, At, Bt) do { __builtin_amdgcn_s_setprio(1); _Pragma("unroll") for (int m = 0; m < 4; ++m) _Pragma("unroll") for (int n = 0; n < 2; ++n) _Pragma("unroll") for (int k = 0; k < 2; ++k) \
;         acc[ai][bj][m][n] = __builtin_amdgcn_mfma_f32_16x16x32_bf16(Bt[n][k], At[m][k], acc[ai][bj][m][n], 0, 0, 0); __builtin_amdgcn_s_setprio(0); } while (0)
; #define PG8_WAIT_V(n) asm volatile("s_waitcnt vmcnt(" #n ")" ::: "memory")
; #define PG8_WAIT_L(n) asm volatile("s_waitcnt lgkmcnt(" #n ")" ::: "memory")
; #define PG8_BAR __builtin_amdgcn_s_barrier()
; #define PG8_SCHED __builtin_amdgcn_sched_barrier(0)
; template <class Epi>
; __device__ __forceinline__ void gemm_phase(LAS unsigned char* lds, const Gemm g, const StaticOrder& S, const Epi& E) {
;     ...
;             PG8_WAIT_V(8); PG8_WAIT_L(0); PG8_BAR; PG8_MMA(0, 0, At, B0); PG8_MMA(0, 1, At, B1); PG8_BAR; PG8_SCHED;
;             PG8_LDA(At, 1, 1); PG8_STAGE(PG8_SB(1, 0), b3, voffB); PG8_STAGE(PG8_SB(1, 1), b3 + hstepB, voffB); PG8_STAGE(PG8_SA(1, 0), a3, voffA);
;             PG8_WAIT_V(8); PG8_WAIT_L(0); PG8_BAR; PG8_MMA(1, 0, At, B0); PG8_MMA(1, 1, At, B1); PG8_BAR; PG8_SCHED;
;         }
	s_add_i32 s62, 0, 0x18000
	v_add_u32_e32 v87, s62, v84
	ds_read_b128 v[88:91], v87
	ds_read_b128 v[92:95], v87 offset:1024
	ds_read_b128 v[96:99], v87 offset:2048
	ds_read_b128 v[100:103], v87 offset:3072
	s_add_u32 s30, s36, 0x18000
	s_addc_u32 s31, s37, 0
	s_mov_b32 m0, s44
	v_lshl_add_u64 v[144:145], s[30:31], 0, v[64:65]
	ds_read_b128 v[104:107], v86 offset:32768
	ds_read_b128 v[108:111], v86 offset:33792
	ds_read_b128 v[112:115], v86 offset:34816
	ds_read_b128 v[116:119], v86 offset:35840
	ds_read_b128 v[120:123], v86 offset:36864
	ds_read_b128 v[124:127], v86 offset:37888
	ds_read_b128 v[128:131], v86 offset:38912
	ds_read_b128 v[132:135], v86 offset:39936
	global_load_lds_dwordx4 v[144:145], off
	v_lshl_add_u64 v[144:145], s[30:31], 0, v[68:69]
	s_mov_b32 m0, s45
	s_nop 0
	global_load_lds_dwordx4 v[144:145], off
	s_waitcnt vmcnt(8)
	s_waitcnt lgkmcnt(0)
	s_barrier
	s_setprio 1
	s_waitcnt lgkmcnt(0)
	v_mfma_f32_16x16x32_bf16 v[60:63], v[88:91], v[104:107], v[60:63]
	v_mfma_f32_16x16x32_bf16 v[56:59], v[96:99], v[104:107], v[56:59]
	v_mfma_f32_16x16x32_bf16 v[48:51], v[96:99], v[112:115], v[48:51]
	v_mfma_f32_16x16x32_bf16 v[52:55], v[88:91], v[112:115], v[52:55]
	v_mfma_f32_16x16x32_bf16 v[44:47], v[88:91], v[120:123], v[44:47]
	v_mfma_f32_16x16x32_bf16 v[40:43], v[96:99], v[120:123], v[40:43]
	v_mfma_f32_16x16x32_bf16 v[32:35], v[96:99], v[128:131], v[32:35]
	v_mfma_f32_16x16x32_bf16 v[36:39], v[88:91], v[128:131], v[36:39]
	v_mfma_f32_16x16x32_bf16 v[60:63], v[92:95], v[108:111], v[60:63]
	v_mfma_f32_16x16x32_bf16 v[56:59], v[100:103], v[108:111], v[56:59]
	v_mfma_f32_16x16x32_bf16 v[48:51], v[100:103], v[116:119], v[48:51]
	v_mfma_f32_16x16x32_bf16 v[52:55], v[92:95], v[116:119], v[52:55]
	v_mfma_f32_16x16x32_bf16 v[44:47], v[92:95], v[124:127], v[44:47]
	v_mfma_f32_16x16x32_bf16 v[40:43], v[100:103], v[124:127], v[40:43]
	v_mfma_f32_16x16x32_bf16 v[32:35], v[100:103], v[132:135], v[32:35]
	v_mfma_f32_16x16x32_bf16 v[36:39], v[92:95], v[132:135], v[36:39]
	s_setprio 0
	s_setprio 1
	s_setprio 0
	s_barrier
	s_add_i32 s30, s62, s39
	v_lshl_add_u64 v[136:137], v[136:137], 0, s[10:11]
	s_mov_b32 m0, s30
	ds_read_b128 v[104:107], v86 offset:49152
	ds_read_b128 v[108:111], v86 offset:50176
	ds_read_b128 v[112:115], v86 offset:51200
	ds_read_b128 v[116:119], v86 offset:52224
	ds_read_b128 v[120:123], v86 offset:53248
	ds_read_b128 v[124:127], v86 offset:54272
	ds_read_b128 v[128:131], v86 offset:55296
	ds_read_b128 v[132:135], v86 offset:56320
	global_load_lds_dwordx4 v[136:137], off
	s_add_i32 m0, s30, 0x2000
	s_add_u32 s30, s34, 0x10080
	v_lshl_add_u64 v[136:137], v[138:139], 0, s[10:11]
	s_addc_u32 s31, s35, 0
	global_load_lds_dwordx4 v[136:137], off
	v_lshl_add_u64 v[136:137], s[30:31], 0, v[66:67]
	s_mov_b32 m0, s49
	s_nop 0
	global_load_lds_dwordx4 v[136:137], off
	v_lshl_add_u64 v[136:137], s[30:31], 0, v[70:71]
	s_mov_b32 m0, s52
	s_nop 0
	global_load_lds_dwordx4 v[136:137], off
	v_lshl_add_u64 v[136:137], v[140:141], 0, s[10:11]
	s_mov_b32 m0, s47
	s_nop 0
	global_load_lds_dwordx4 v[136:137], off
	v_lshl_add_u64 v[136:137], v[142:143], 0, s[10:11]
	s_mov_b32 m0, s48
	s_nop 0
	global_load_lds_dwordx4 v[136:137], off
	s_waitcnt vmcnt(8)
	s_waitcnt lgkmcnt(0)
	s_barrier
	s_setprio 1
	s_waitcnt lgkmcnt(0)
	v_mfma_f32_16x16x32_bf16 v[28:31], v[88:91], v[104:107], v[28:31]
	v_mfma_f32_16x16x32_bf16 v[24:27], v[96:99], v[104:107], v[24:27]
	v_mfma_f32_16x16x32_bf16 v[16:19], v[96:99], v[112:115], v[16:19]
	v_mfma_f32_16x16x32_bf16 v[20:23], v[88:91], v[112:115], v[20:23]
	v_mfma_f32_16x16x32_bf16 v[12:15], v[88:91], v[120:123], v[12:15]
	v_mfma_f32_16x16x32_bf16 v[8:11], v[96:99], v[120:123], v[8:11]
	v_mfma_f32_16x16x32_bf16 v[0:3], v[96:99], v[128:131], v[0:3]
	v_mfma_f32_16x16x32_bf16 v[4:7], v[88:91], v[128:131], v[4:7]
	v_mfma_f32_16x16x32_bf16 v[28:31], v[92:95], v[108:111], v[28:31]
	v_mfma_f32_16x16x32_bf16 v[24:27], v[100:103], v[108:111], v[24:27]
	v_mfma_f32_16x16x32_bf16 v[16:19], v[100:103], v[116:119], v[16:19]
	v_mfma_f32_16x16x32_bf16 v[20:23], v[92:95], v[116:119], v[20:23]
	v_mfma_f32_16x16x32_bf16 v[12:15], v[92:95], v[124:127], v[12:15]
	v_mfma_f32_16x16x32_bf16 v[8:11], v[100:103], v[124:127], v[8:11]
	v_mfma_f32_16x16x32_bf16 v[0:3], v[100:103], v[132:135], v[0:3]
	v_mfma_f32_16x16x32_bf16 v[4:7], v[92:95], v[132:135], v[4:7]
	s_setprio 0
	s_setprio 1
	s_setprio 0
	s_barrier
	s_add_u32 s59, s59, 0x100
	s_addc_u32 s60, s60, 0
	s_cmp_ge_i32 s61, s46
	s_mov_b64 s[30:31], s[8:9]
	s_mov_b32 s34, s61
	s_cbranch_scc0 .LBB0_685

; #define PG8_STAGE(bufoff, gbase, voff) do { _Pragma("unroll") for (int _i = 0; _i < 2; ++_i) \
;         __builtin_amdgcn_global_load_lds((const unsigned*)((const char*)(gbase) + (voff)[_i]), (LAS unsigned*)(lds + (bufoff) + ldsw + _i * 8192), 16, 0, 0); } while (0)
; #define PG8_LDA(dst, b, h) do { _Pragma("unroll") for (int m = 0; m < 4; ++m) _Pragma("unroll") for (int k = 0; k < 2; ++k) dst[m][k] = *(const LAS bf16x8*)(lds + PG8_SA(b, h) + aoff + m * 2048 + k * 1024); } while (0)
; #define PG8_LDB(dst, b, h) do { _Pragma("unroll") for (int n = 0; n < 2; ++n) _Pragma("unroll") for (int k = 0; k < 2; ++k) dst[n][k] = *(const LAS bf16x8*)(lds + PG8_SB(b, h) + boff + n * 2048 + k * 1024); } while (0)
; #define PG8_MMA(ai, bj, At, Bt) do { __builtin_amdgcn_s_setprio(1); _Pragma("unroll") for (int m = 0; m < 4; ++m) _Pragma("unroll") for (int n = 0; n < 2; ++n) _Pragma("unroll") for (int k = 0; k < 2; ++k) \
;         acc[ai][bj][m][n] = __builtin_amdgcn_mfma_f32_16x16x32_bf16(Bt[n][k], At[m][k], acc[ai][bj][m][n], 0, 0, 0); __builtin_amdgcn_s_setprio(0); } while (0)
; #define PG8_WAIT_V(n) asm volatile("s_waitcnt vmcnt(" #n ")" ::: "memory")
; #define PG8_WAIT_L(n) asm volatile("s_waitcnt lgkmcnt(" #n ")" ::: "memory")
; #define PG8_BAR __builtin_amdgcn_s_barrier()
; #define PG8_SCHED __builtin_amdgcn_sched_barrier(0)
; template <class Epi>
; __device__ __forceinline__ void gemm_phase(LAS unsigned char* lds, const Gemm g, const StaticOrder& S, const Epi& E) {
;     ...
;             PG8_LDB(B0, 0, 0); PG8_LDB(B1, 0, 1); PG8_SCHED; PG8_LDA(At, 0, 0); PG8_STAGE(PG8_SA(1, 1), a1 + hstepA, voffA);
;             PG8_WAIT_V(8); PG8_WAIT_L(0); PG8_BAR; PG8_MMA(0, 0, At, B0); PG8_MMA(0, 1, At, B1); PG8_BAR; PG8_SCHED;
;             PG8_LDA(At, 0, 1); PG8_STAGE(PG8_SB(0, 0), b2, voffB); PG8_STAGE(PG8_SB(0, 1), b2 + hstepB, voffB); PG8_STAGE(PG8_SA(0, 0), a2, voffA);
;             PG8_WAIT_V(8); PG8_WAIT_L(0); PG8_BAR; PG8_MMA(1, 0, At, B0); PG8_MMA(1, 1, At, B1); PG8_BAR; PG8_SCHED;
.LBB0_834:
	ds_read_b128 v[156:159], v152
	ds_read_b128 v[160:163], v152 offset:1024
	ds_read_b128 v[164:167], v152 offset:2048
	ds_read_b128 v[168:171], v152 offset:3072
	ds_read_b128 v[172:175], v153
	ds_read_b128 v[176:179], v153 offset:1024
	ds_read_b128 v[180:183], v153 offset:2048
	ds_read_b128 v[184:187], v153 offset:3072
	s_add_i32 s49, s22, 2
	s_add_u32 s4, s0, 0x100
	s_addc_u32 s5, s1, 0
	s_cmp_eq_u32 s40, s22
	s_cselect_b32 s22, s20, s47
	s_cselect_b32 s25, s11, s5
	s_cselect_b32 s24, s10, s4
	s_cselect_b32 s23, s21, s48
	v_lshl_add_u64 v[224:225], s[0:1], 0, v[138:139]
	s_add_i32 m0, s29, 0xc000
	ds_read_b128 v[188:191], v154
	ds_read_b128 v[192:195], v154 offset:1024
	ds_read_b128 v[196:199], v154 offset:2048
	ds_read_b128 v[200:203], v154 offset:3072
	ds_read_b128 v[208:211], v154 offset:4096
	ds_read_b128 v[212:215], v154 offset:5120
	ds_read_b128 v[216:219], v154 offset:6144
	ds_read_b128 v[220:223], v154 offset:7168
	global_load_lds_dwordx4 v[224:225], off
	v_lshl_add_u64 v[224:225], s[0:1], 0, v[140:141]
	s_add_i32 m0, s29, 0xe000
	s_nop 0
	global_load_lds_dwordx4 v[224:225], off
	s_waitcnt vmcnt(8)
	s_waitcnt lgkmcnt(0)
	s_barrier
	s_setprio 1
	s_waitcnt lgkmcnt(0)
	v_mfma_f32_16x16x32_bf16 v[124:127], v[156:159], v[188:191], v[124:127]
	v_mfma_f32_16x16x32_bf16 v[120:123], v[164:167], v[188:191], v[120:123]
	v_mfma_f32_16x16x32_bf16 v[116:119], v[172:175], v[188:191], v[116:119]
	v_mfma_f32_16x16x32_bf16 v[112:115], v[180:183], v[188:191], v[112:115]
	v_mfma_f32_16x16x32_bf16 v[96:99], v[180:183], v[196:199], v[96:99]
	v_mfma_f32_16x16x32_bf16 v[100:103], v[172:175], v[196:199], v[100:103]
	v_mfma_f32_16x16x32_bf16 v[104:107], v[164:167], v[196:199], v[104:107]
	v_mfma_f32_16x16x32_bf16 v[108:111], v[156:159], v[196:199], v[108:111]
	v_mfma_f32_16x16x32_bf16 v[92:95], v[156:159], v[208:211], v[92:95]
	v_mfma_f32_16x16x32_bf16 v[88:91], v[164:167], v[208:211], v[88:91]
	v_mfma_f32_16x16x32_bf16 v[84:87], v[172:175], v[208:211], v[84:87]
	v_mfma_f32_16x16x32_bf16 v[80:83], v[180:183], v[208:211], v[80:83]
	v_mfma_f32_16x16x32_bf16 v[64:67], v[180:183], v[216:219], v[64:67]
	v_mfma_f32_16x16x32_bf16 v[68:71], v[172:175], v[216:219], v[68:71]
	v_mfma_f32_16x16x32_bf16 v[72:75], v[164:167], v[216:219], v[72:75]
	v_mfma_f32_16x16x32_bf16 v[76:79], v[156:159], v[216:219], v[76:79]
	s_setprio 0
	s_setprio 1
	v_mfma_f32_16x16x32_bf16 v[124:127], v[160:163], v[192:195], v[124:127]
	v_mfma_f32_16x16x32_bf16 v[120:123], v[168:171], v[192:195], v[120:123]
	v_mfma_f32_16x16x32_bf16 v[116:119], v[176:179], v[192:195], v[116:119]
	v_mfma_f32_16x16x32_bf16 v[112:115], v[184:187], v[192:195], v[112:115]
	v_mfma_f32_16x16x32_bf16 v[96:99], v[184:187], v[200:203], v[96:99]
	v_mfma_f32_16x16x32_bf16 v[100:103], v[176:179], v[200:203], v[100:103]
	v_mfma_f32_16x16x32_bf16 v[104:107], v[168:171], v[200:203], v[104:107]
	v_mfma_f32_16x16x32_bf16 v[108:111], v[160:163], v[200:203], v[108:111]
	v_mfma_f32_16x16x32_bf16 v[92:95], v[160:163], v[212:215], v[92:95]
	v_mfma_f32_16x16x32_bf16 v[88:91], v[168:171], v[212:215], v[88:91]
	v_mfma_f32_16x16x32_bf16 v[84:87], v[176:179], v[212:215], v[84:87]
	v_mfma_f32_16x16x32_bf16 v[80:83], v[184:187], v[212:215], v[80:83]
	v_mfma_f32_16x16x32_bf16 v[64:67], v[184:187], v[220:223], v[64:67]
	v_mfma_f32_16x16x32_bf16 v[68:71], v[176:179], v[220:223], v[68:71]
	v_mfma_f32_16x16x32_bf16 v[72:75], v[168:171], v[220:223], v[72:75]
	v_mfma_f32_16x16x32_bf16 v[76:79], v[160:163], v[220:223], v[76:79]
	s_setprio 0
	s_barrier
	s_add_i32 s0, s43, s28
	v_lshl_add_u64 v[224:225], s[22:23], 0, v[130:131]
	s_mov_b32 m0, s0
	ds_read_b128 v[188:191], v154 offset:16384
	ds_read_b128 v[192:195], v154 offset:17408
	ds_read_b128 v[196:199], v154 offset:18432
	ds_read_b128 v[200:203], v154 offset:19456
	ds_read_b128 v[208:211], v154 offset:20480
	ds_read_b128 v[212:215], v154 offset:21504
	ds_read_b128 v[216:219], v154 offset:22528
	ds_read_b128 v[220:223], v154 offset:23552
	global_load_lds_dwordx4 v[224:225], off
	s_add_i32 m0, s0, 0x2000
	s_add_u32 s0, s22, 0x18000
	v_lshl_add_u64 v[226:227], s[22:23], 0, v[134:135]
	s_addc_u32 s1, s23, 0
	s_add_i32 s50, s44, s28
	global_load_lds_dwordx4 v[226:227], off
	v_lshl_add_u64 v[230:231], s[0:1], 0, v[130:131]
	s_mov_b32 m0, s50
	v_lshl_add_u64 v[232:233], s[24:25], 0, v[132:133]
	global_load_lds_dwordx4 v[230:231], off
	v_lshl_add_u64 v[230:231], s[0:1], 0, v[134:135]
	s_add_i32 m0, s50, 0x2000
	s_nop 0
	global_load_lds_dwordx4 v[230:231], off
	v_lshl_add_u64 v[230:231], s[24:25], 0, v[128:129]
	s_mov_b32 m0, s29
	s_nop 0
	global_load_lds_dwordx4 v[230:231], off
	s_mov_b32 m0, s30
	s_nop 0
	global_load_lds_dwordx4 v[232:233], off
	s_waitcnt vmcnt(8)
	s_waitcnt lgkmcnt(0)
	s_barrier
; #define PG8_STAGE(bufoff, gbase, voff) do { _Pragma("unroll") for (int _i = 0; _i < 2; ++_i) \
;         __builtin_amdgcn_global_load_lds((const unsigned*)((const char*)(gbase) + (voff)[_i]), (LAS unsigned*)(lds + (bufoff) + ldsw + _i * 8192), 16, 0, 0); } while (0)
; #define PG8_LDA(dst, b, h) do { _Pragma("unroll") for (int m = 0; m < 4; ++m) _Pragma("unroll") for (int k = 0; k < 2; ++k) dst[m][k] = *(const LAS bf16x8*)(lds + PG8_SA(b, h) + aoff + m * 2048 + k * 1024); } while (0)
; #define PG8_LDB(dst, b, h) do { _Pragma("unroll") for (int n = 0; n < 2; ++n) _Pragma("unroll") for (int k = 0; k < 2; ++k) dst[n][k] = *(const LAS bf16x8*)(lds + PG8_SB(b, h) + boff + n * 2048 + k * 1024); } while (0)
; #define PG8_MMA(ai, bj, At, Bt) do { __builtin_amdgcn_s_setprio(1); _Pragma("unroll") for (int m = 0; m < 4; ++m) _Pragma("unroll") for (int n = 0; n < 2; ++n) _Pragma("unroll") for (int k = 0; k < 2; ++k) \
;         acc[ai][bj][m][n] = __builtin_amdgcn_mfma_f32_16x16x32_bf16(Bt[n][k], At[m][k], acc[ai][bj][m][n], 0, 0, 0); __builtin_amdgcn_s_setprio(0); } while (0)
; #define PG8_WAIT_V(n) asm volatile("s_waitcnt vmcnt(" #n ")" ::: "memory")
; #define PG8_WAIT_L(n) asm volatile("s_waitcnt lgkmcnt(" #n ")" ::: "memory")
; #define PG8_BAR __builtin_amdgcn_s_barrier()
; #define PG8_SCHED __builtin_amdgcn_sched_barrier(0)
; template <class Epi>
; __device__ __forceinline__ void gemm_phase(LAS unsigned char* lds, const Gemm g, const StaticOrder& S, const Epi& E) {
;     ...
;             PG8_WAIT_V(8); PG8_WAIT_L(0); PG8_BAR; PG8_MMA(1, 0, At, B0); PG8_MMA(1, 1, At, B1); PG8_BAR; PG8_SCHED;
;             PG8_LDB(B0, 1, 0); PG8_LDB(B1, 1, 1); PG8_SCHED; PG8_LDA(At, 1, 0); PG8_STAGE(PG8_SA(0, 1), a2 + hstepA, voffA);
;             PG8_WAIT_V(8); PG8_WAIT_L(0); PG8_BAR; PG8_MMA(0, 0, At, B0); PG8_MMA(0, 1, At, B1); PG8_BAR; PG8_SCHED;
	s_setprio 1
	s_waitcnt lgkmcnt(0)
	v_mfma_f32_16x16x32_bf16 v[60:63], v[156:159], v[188:191], v[60:63]
	v_mfma_f32_16x16x32_bf16 v[56:59], v[164:167], v[188:191], v[56:59]
	v_mfma_f32_16x16x32_bf16 v[52:55], v[172:175], v[188:191], v[52:55]
	v_mfma_f32_16x16x32_bf16 v[48:51], v[180:183], v[188:191], v[48:51]
	v_mfma_f32_16x16x32_bf16 v[32:35], v[180:183], v[196:199], v[32:35]
	v_mfma_f32_16x16x32_bf16 v[36:39], v[172:175], v[196:199], v[36:39]
	v_mfma_f32_16x16x32_bf16 v[40:43], v[164:167], v[196:199], v[40:43]
	v_mfma_f32_16x16x32_bf16 v[44:47], v[156:159], v[196:199], v[44:47]
	v_mfma_f32_16x16x32_bf16 v[28:31], v[156:159], v[208:211], v[28:31]
	v_mfma_f32_16x16x32_bf16 v[24:27], v[164:167], v[208:211], v[24:27]
	v_mfma_f32_16x16x32_bf16 v[20:23], v[172:175], v[208:211], v[20:23]
	v_mfma_f32_16x16x32_bf16 v[16:19], v[180:183], v[208:211], v[16:19]
	v_mfma_f32_16x16x32_bf16 v[0:3], v[180:183], v[216:219], v[0:3]
	v_mfma_f32_16x16x32_bf16 v[4:7], v[172:175], v[216:219], v[4:7]
	v_mfma_f32_16x16x32_bf16 v[8:11], v[164:167], v[216:219], v[8:11]
	v_mfma_f32_16x16x32_bf16 v[12:15], v[156:159], v[216:219], v[12:15]
	s_setprio 0
	s_setprio 1
	v_mfma_f32_16x16x32_bf16 v[60:63], v[160:163], v[192:195], v[60:63]
	v_mfma_f32_16x16x32_bf16 v[56:59], v[168:171], v[192:195], v[56:59]
	v_mfma_f32_16x16x32_bf16 v[52:55], v[176:179], v[192:195], v[52:55]
	v_mfma_f32_16x16x32_bf16 v[48:51], v[184:187], v[192:195], v[48:51]
	v_mfma_f32_16x16x32_bf16 v[32:35], v[184:187], v[200:203], v[32:35]
	v_mfma_f32_16x16x32_bf16 v[36:39], v[176:179], v[200:203], v[36:39]
	v_mfma_f32_16x16x32_bf16 v[40:43], v[168:171], v[200:203], v[40:43]
	v_mfma_f32_16x16x32_bf16 v[44:47], v[160:163], v[200:203], v[44:47]
	v_mfma_f32_16x16x32_bf16 v[28:31], v[160:163], v[212:215], v[28:31]
	v_mfma_f32_16x16x32_bf16 v[24:27], v[168:171], v[212:215], v[24:27]
	v_mfma_f32_16x16x32_bf16 v[20:23], v[176:179], v[212:215], v[20:23]
	v_mfma_f32_16x16x32_bf16 v[16:19], v[184:187], v[212:215], v[16:19]
	v_mfma_f32_16x16x32_bf16 v[0:3], v[184:187], v[220:223], v[0:3]
	v_mfma_f32_16x16x32_bf16 v[4:7], v[176:179], v[220:223], v[4:7]
	v_mfma_f32_16x16x32_bf16 v[8:11], v[168:171], v[220:223], v[8:11]
	v_mfma_f32_16x16x32_bf16 v[12:15], v[160:163], v[220:223], v[12:15]
	s_setprio 0
	s_barrier
	s_add_i32 s50, 0, 0x18000
	v_add_u32_e32 v136, s50, v149
	s_add_i32 s51, 0, 0x1c000
	ds_read_b128 v[156:159], v136
	ds_read_b128 v[160:163], v136 offset:1024
	ds_read_b128 v[164:167], v136 offset:2048
	ds_read_b128 v[168:171], v136 offset:3072
	v_add_u32_e32 v136, s51, v149
	ds_read_b128 v[172:175], v136
	ds_read_b128 v[176:179], v136 offset:1024
	ds_read_b128 v[180:183], v136 offset:2048
	ds_read_b128 v[184:187], v136 offset:3072
	s_add_u32 s0, s24, 0x18000
	s_addc_u32 s1, s25, 0
	s_mov_b32 m0, s31
	v_lshl_add_u64 v[234:235], s[0:1], 0, v[128:129]
	ds_read_b128 v[188:191], v154 offset:32768
	ds_read_b128 v[192:195], v154 offset:33792
	ds_read_b128 v[196:199], v154 offset:34816
	ds_read_b128 v[200:203], v154 offset:35840
	ds_read_b128 v[208:211], v154 offset:36864
	ds_read_b128 v[212:215], v154 offset:37888
	ds_read_b128 v[216:219], v154 offset:38912
	ds_read_b128 v[220:223], v154 offset:39936
	global_load_lds_dwordx4 v[234:235], off
	v_lshl_add_u64 v[234:235], s[0:1], 0, v[132:133]
	s_mov_b32 m0, s34
	s_nop 0
	global_load_lds_dwordx4 v[234:235], off
	s_waitcnt vmcnt(8)
	s_waitcnt lgkmcnt(0)
	s_barrier
	s_setprio 1
	s_waitcnt lgkmcnt(0)
	v_mfma_f32_16x16x32_bf16 v[124:127], v[156:159], v[188:191], v[124:127]
	v_mfma_f32_16x16x32_bf16 v[120:123], v[164:167], v[188:191], v[120:123]
	v_mfma_f32_16x16x32_bf16 v[116:119], v[172:175], v[188:191], v[116:119]
	v_mfma_f32_16x16x32_bf16 v[112:115], v[180:183], v[188:191], v[112:115]
	v_mfma_f32_16x16x32_bf16 v[96:99], v[180:183], v[196:199], v[96:99]
	v_mfma_f32_16x16x32_bf16 v[100:103], v[172:175], v[196:199], v[100:103]
	v_mfma_f32_16x16x32_bf16 v[104:107], v[164:167], v[196:199], v[104:107]
	v_mfma_f32_16x16x32_bf16 v[108:111], v[156:159], v[196:199], v[108:111]
	v_mfma_f32_16x16x32_bf16 v[92:95], v[156:159], v[208:211], v[92:95]
	v_mfma_f32_16x16x32_bf16 v[88:91], v[164:167], v[208:211], v[88:91]
	v_mfma_f32_16x16x32_bf16 v[84:87], v[172:175], v[208:211], v[84:87]
	v_mfma_f32_16x16x32_bf16 v[80:83], v[180:183], v[208:211], v[80:83]
	v_mfma_f32_16x16x32_bf16 v[64:67], v[180:183], v[216:219], v[64:67]
	v_mfma_f32_16x16x32_bf16 v[68:71], v[172:175], v[216:219], v[68:71]
	v_mfma_f32_16x16x32_bf16 v[72:75], v[164:167], v[216:219], v[72:75]
	v_mfma_f32_16x16x32_bf16 v[76:79], v[156:159], v[216:219], v[76:79]
	s_setprio 0
	s_setprio 1
	v_mfma_f32_16x16x32_bf16 v[124:127], v[160:163], v[192:195], v[124:127]
	v_mfma_f32_16x16x32_bf16 v[120:123], v[168:171], v[192:195], v[120:123]
	v_mfma_f32_16x16x32_bf16 v[116:119], v[176:179], v[192:195], v[116:119]
	v_mfma_f32_16x16x32_bf16 v[112:115], v[184:187], v[192:195], v[112:115]
	v_mfma_f32_16x16x32_bf16 v[96:99], v[184:187], v[200:203], v[96:99]
	v_mfma_f32_16x16x32_bf16 v[100:103], v[176:179], v[200:203], v[100:103]
	v_mfma_f32_16x16x32_bf16 v[104:107], v[168:171], v[200:203], v[104:107]
	v_mfma_f32_16x16x32_bf16 v[108:111], v[160:163], v[200:203], v[108:111]
	v_mfma_f32_16x16x32_bf16 v[92:95], v[160:163], v[212:215], v[92:95]
	v_mfma_f32_16x16x32_bf16 v[88:91], v[168:171], v[212:215], v[88:91]
	v_mfma_f32_16x16x32_bf16 v[84:87], v[176:179], v[212:215], v[84:87]
	v_mfma_f32_16x16x32_bf16 v[80:83], v[184:187], v[212:215], v[80:83]
	v_mfma_f32_16x16x32_bf16 v[64:67], v[184:187], v[220:223], v[64:67]
	v_mfma_f32_16x16x32_bf16 v[68:71], v[176:179], v[220:223], v[68:71]
	v_mfma_f32_16x16x32_bf16 v[72:75], v[168:171], v[220:223], v[72:75]
	v_mfma_f32_16x16x32_bf16 v[76:79], v[160:163], v[220:223], v[76:79]
	s_setprio 0
	s_barrier
; #define PG8_STAGE(bufoff, gbase, voff) do { _Pragma("unroll") for (int _i = 0; _i < 2; ++_i) \
;         __builtin_amdgcn_global_load_lds((const unsigned*)((const char*)(gbase) + (voff)[_i]), (LAS unsigned*)(lds + (bufoff) + ldsw + _i * 8192), 16, 0, 0); } while (0)
; #define PG8_LDA(dst, b, h) do { _Pragma("unroll") for (int m = 0; m < 4; ++m) _Pragma("unroll") for (int k = 0; k < 2; ++k) dst[m][k] = *(const LAS bf16x8*)(lds + PG8_SA(b, h) + aoff + m * 2048 + k * 1024); } while (0)
; #define PG8_MMA(ai, bj, At, Bt) do { __builtin_amdgcn_s_setprio(1); _Pragma("unroll") for (int m = 0; m < 4; ++m) _Pragma("unroll") for (int n = 0; n < 2; ++n) _Pragma("unroll") for (int k = 0; k < 2; ++k) \
;         acc[ai][bj][m][n] = __builtin_amdgcn_mfma_f32_16x16x32_bf16(Bt[n][k], At[m][k], acc[ai][bj][m][n], 0, 0, 0); __builtin_amdgcn_s_setprio(0); } while (0)
; #define PG8_WAIT_V(n) asm volatile("s_waitcnt vmcnt(" #n ")" ::: "memory")
; #define PG8_WAIT_L(n) asm volatile("s_waitcnt lgkmcnt(" #n ")" ::: "memory")
; #define PG8_BAR __builtin_amdgcn_s_barrier()
; #define PG8_SCHED __builtin_amdgcn_sched_barrier(0)
; template <class Epi>
; __device__ __forceinline__ void gemm_phase(LAS unsigned char* lds, const Gemm g, const StaticOrder& S, const Epi& E) {
;     ...
;         for (int t = 0; t < nt; t += 2) {
;     ...
;             PG8_LDA(At, 1, 1); PG8_STAGE(PG8_SB(1, 0), b3, voffB); PG8_STAGE(PG8_SB(1, 1), b3 + hstepB, voffB); PG8_STAGE(PG8_SA(1, 0), a3, voffA);
;             PG8_WAIT_V(8); PG8_WAIT_L(0); PG8_BAR; PG8_MMA(1, 0, At, B0); PG8_MMA(1, 1, At, B1); PG8_BAR; PG8_SCHED;
	s_add_i32 s0, s50, s28
	v_lshl_add_u64 v[224:225], v[224:225], 0, s[14:15]
	s_mov_b32 m0, s0
	ds_read_b128 v[188:191], v154 offset:49152
	ds_read_b128 v[192:195], v154 offset:50176
	ds_read_b128 v[196:199], v154 offset:51200
	ds_read_b128 v[200:203], v154 offset:52224
	ds_read_b128 v[208:211], v154 offset:53248
	ds_read_b128 v[212:215], v154 offset:54272
	ds_read_b128 v[216:219], v154 offset:55296
	ds_read_b128 v[220:223], v154 offset:56320
	global_load_lds_dwordx4 v[224:225], off
	s_add_i32 m0, s0, 0x2000
	s_add_u32 s0, s22, 0x18080
	v_lshl_add_u64 v[224:225], v[226:227], 0, s[14:15]
	s_addc_u32 s1, s23, 0
	s_add_i32 s22, s51, s28
	global_load_lds_dwordx4 v[224:225], off
	v_lshl_add_u64 v[224:225], s[0:1], 0, v[130:131]
	s_mov_b32 m0, s22
	s_nop 0
	global_load_lds_dwordx4 v[224:225], off
	v_lshl_add_u64 v[224:225], s[0:1], 0, v[134:135]
	s_add_i32 m0, s22, 0x2000
	s_nop 0
	global_load_lds_dwordx4 v[224:225], off
	v_lshl_add_u64 v[224:225], v[230:231], 0, s[14:15]
	s_mov_b32 m0, s38
	s_nop 0
	global_load_lds_dwordx4 v[224:225], off
	v_lshl_add_u64 v[224:225], v[232:233], 0, s[14:15]
	s_mov_b32 m0, s39
	s_nop 0
	global_load_lds_dwordx4 v[224:225], off
	s_waitcnt vmcnt(8)
	s_waitcnt lgkmcnt(0)
	s_barrier
	s_setprio 1
	s_waitcnt lgkmcnt(0)
	v_mfma_f32_16x16x32_bf16 v[60:63], v[156:159], v[188:191], v[60:63]
	v_mfma_f32_16x16x32_bf16 v[56:59], v[164:167], v[188:191], v[56:59]
	v_mfma_f32_16x16x32_bf16 v[52:55], v[172:175], v[188:191], v[52:55]
	v_mfma_f32_16x16x32_bf16 v[48:51], v[180:183], v[188:191], v[48:51]
	v_mfma_f32_16x16x32_bf16 v[32:35], v[180:183], v[196:199], v[32:35]
	v_mfma_f32_16x16x32_bf16 v[36:39], v[172:175], v[196:199], v[36:39]
	v_mfma_f32_16x16x32_bf16 v[40:43], v[164:167], v[196:199], v[40:43]
	v_mfma_f32_16x16x32_bf16 v[44:47], v[156:159], v[196:199], v[44:47]
	v_mfma_f32_16x16x32_bf16 v[28:31], v[156:159], v[208:211], v[28:31]
	v_mfma_f32_16x16x32_bf16 v[24:27], v[164:167], v[208:211], v[24:27]
	v_mfma_f32_16x16x32_bf16 v[20:23], v[172:175], v[208:211], v[20:23]
	v_mfma_f32_16x16x32_bf16 v[16:19], v[180:183], v[208:211], v[16:19]
	v_mfma_f32_16x16x32_bf16 v[0:3], v[180:183], v[216:219], v[0:3]
	v_mfma_f32_16x16x32_bf16 v[4:7], v[172:175], v[216:219], v[4:7]
	v_mfma_f32_16x16x32_bf16 v[8:11], v[164:167], v[216:219], v[8:11]
	v_mfma_f32_16x16x32_bf16 v[12:15], v[156:159], v[216:219], v[12:15]
	s_setprio 0
	s_setprio 1
	v_mfma_f32_16x16x32_bf16 v[60:63], v[160:163], v[192:195], v[60:63]
	v_mfma_f32_16x16x32_bf16 v[56:59], v[168:171], v[192:195], v[56:59]
	v_mfma_f32_16x16x32_bf16 v[52:55], v[176:179], v[192:195], v[52:55]
	v_mfma_f32_16x16x32_bf16 v[48:51], v[184:187], v[192:195], v[48:51]
	v_mfma_f32_16x16x32_bf16 v[32:35], v[184:187], v[200:203], v[32:35]
	v_mfma_f32_16x16x32_bf16 v[36:39], v[176:179], v[200:203], v[36:39]
	v_mfma_f32_16x16x32_bf16 v[40:43], v[168:171], v[200:203], v[40:43]
	v_mfma_f32_16x16x32_bf16 v[44:47], v[160:163], v[200:203], v[44:47]
	v_mfma_f32_16x16x32_bf16 v[28:31], v[160:163], v[212:215], v[28:31]
	v_mfma_f32_16x16x32_bf16 v[24:27], v[168:171], v[212:215], v[24:27]
	v_mfma_f32_16x16x32_bf16 v[20:23], v[176:179], v[212:215], v[20:23]
	v_mfma_f32_16x16x32_bf16 v[16:19], v[184:187], v[212:215], v[16:19]
	v_mfma_f32_16x16x32_bf16 v[0:3], v[184:187], v[220:223], v[0:3]
	v_mfma_f32_16x16x32_bf16 v[4:7], v[176:179], v[220:223], v[4:7]
	v_mfma_f32_16x16x32_bf16 v[8:11], v[168:171], v[220:223], v[8:11]
	v_mfma_f32_16x16x32_bf16 v[12:15], v[160:163], v[220:223], v[12:15]
	s_setprio 0
	s_barrier
	s_add_u32 s47, s47, 0x100
	s_addc_u32 s48, s48, 0
	s_cmp_ge_i32 s49, s36
	s_mov_b64 s[0:1], s[4:5]
	s_mov_b32 s22, s49
	s_cbranch_scc0 .LBB0_834

; #define PG8_STAGE(bufoff, gbase, voff) do { _Pragma("unroll") for (int _i = 0; _i < 2; ++_i) \
;         __builtin_amdgcn_global_load_lds((const unsigned*)((const char*)(gbase) + (voff)[_i]), (LAS unsigned*)(lds + (bufoff) + ldsw + _i * 8192), 16, 0, 0); } while (0)
; #define PG8_LDA(dst, b, h) do { _Pragma("unroll") for (int m = 0; m < 4; ++m) _Pragma("unroll") for (int k = 0; k < 2; ++k) dst[m][k] = *(const LAS bf16x8*)(lds + PG8_SA(b, h) + aoff + m * 2048 + k * 1024); } while (0)
; #define PG8_LDB(dst, b, h) do { _Pragma("unroll") for (int n = 0; n < 2; ++n) _Pragma("unroll") for (int k = 0; k < 2; ++k) dst[n][k] = *(const LAS bf16x8*)(lds + PG8_SB(b, h) + boff + n * 2048 + k * 1024); } while (0)
; #define PG8_MMA(ai, bj, At, Bt) do { __builtin_amdgcn_s_setprio(1); _Pragma("unroll") for (int m = 0; m < 4; ++m) _Pragma("unroll") for (int n = 0; n < 2; ++n) _Pragma("unroll") for (int k = 0; k < 2; ++k) \
;         acc[ai][bj][m][n] = __builtin_amdgcn_mfma_f32_16x16x32_bf16(Bt[n][k], At[m][k], acc[ai][bj][m][n], 0, 0, 0); __builtin_amdgcn_s_setprio(0); } while (0)
; #define PG8_WAIT_V(n) asm volatile("s_waitcnt vmcnt(" #n ")" ::: "memory")
; #define PG8_WAIT_L(n) asm volatile("s_waitcnt lgkmcnt(" #n ")" ::: "memory")
; #define PG8_BAR __builtin_amdgcn_s_barrier()
; #define PG8_SCHED __builtin_amdgcn_sched_barrier(0)
; template <class Epi>
; __device__ __forceinline__ void gemm_phase(LAS unsigned char* lds, const Gemm g, const StaticOrder& S, const Epi& E) {
;     ...
;         for (int t = 0; t < nt; t += 2) {
;             const bool last = (t == nt - 2);
;             const char* a1 = cA + (size_t)(t + 1) * kstep;
;             const char* a2 = last ? nA : cA + (size_t)(t + 2) * kstep; const char* b2 = last ? nB : cB + (size_t)(t + 2) * kstep;
;             const char* a3 = a2 + kstep; const char* b3 = b2 + kstep;
;             PG8_LDB(B0, 0, 0); PG8_LDB(B1, 0, 1); PG8_SCHED; PG8_LDA(At, 0, 0); PG8_STAGE(PG8_SA(1, 1), a1 + hstepA, voffA);
;             PG8_WAIT_V(8); PG8_WAIT_L(0); PG8_BAR; PG8_MMA(0, 0, At, B0); PG8_MMA(0, 1, At, B1); PG8_BAR; PG8_SCHED;
;             PG8_LDA(At, 0, 1); PG8_STAGE(PG8_SB(0, 0), b2, voffB); PG8_STAGE(PG8_SB(0, 1), b2 + hstepB, voffB); PG8_STAGE(PG8_SA(0, 0), a2, voffA);
;             PG8_WAIT_V(8); PG8_WAIT_L(0); PG8_BAR; PG8_MMA(1, 0, At, B0); PG8_MMA(1, 1, At, B1); PG8_BAR; PG8_SCHED;
.LBB0_912:
	ds_read_b128 v[96:99], v230
	ds_read_b128 v[100:103], v230 offset:1024
	ds_read_b128 v[104:107], v230 offset:2048
	ds_read_b128 v[116:119], v230 offset:3072
	ds_read_b128 v[120:123], v231
	ds_read_b128 v[124:127], v231 offset:1024
	ds_read_b128 v[136:139], v231 offset:2048
	ds_read_b128 v[148:151], v231 offset:3072
	s_add_i32 s56, s24, 2
	s_add_u32 s25, s4, 0xfffc0080
	s_addc_u32 s26, s5, -1
	s_cmp_eq_u32 s44, s24
	s_cselect_b32 s24, s53, s54
	s_cselect_b32 s27, s17, s26
	s_cselect_b32 s26, s19, s25
	s_cselect_b32 s25, s33, s55
	v_lshl_add_u64 v[192:193], s[4:5], 0, v[220:221]
	s_add_i32 m0, s31, 0xc000
	ds_read_b128 v[160:163], v232
	ds_read_b128 v[164:167], v232 offset:1024
	ds_read_b128 v[168:171], v232 offset:2048
	ds_read_b128 v[172:175], v232 offset:3072
	ds_read_b128 v[176:179], v232 offset:4096
	ds_read_b128 v[180:183], v232 offset:5120
	ds_read_b128 v[184:187], v232 offset:6144
	ds_read_b128 v[188:191], v232 offset:7168
	global_load_lds_dwordx4 v[192:193], off
	v_lshl_add_u64 v[192:193], s[4:5], 0, v[222:223]
	s_add_i32 m0, s31, 0xe000
	s_nop 0
	global_load_lds_dwordx4 v[192:193], off
	s_waitcnt vmcnt(8)
	s_waitcnt lgkmcnt(0)
	s_barrier
	s_setprio 1
	s_waitcnt lgkmcnt(0)
	v_mfma_f32_16x16x32_bf16 v[156:159], v[96:99], v[160:163], v[156:159]
	v_mfma_f32_16x16x32_bf16 v[152:155], v[104:107], v[160:163], v[152:155]
	v_mfma_f32_16x16x32_bf16 v[144:147], v[120:123], v[160:163], v[144:147]
	v_mfma_f32_16x16x32_bf16 v[140:143], v[136:139], v[160:163], v[140:143]
	v_mfma_f32_16x16x32_bf16 v[108:111], v[136:139], v[168:171], v[108:111]
	v_mfma_f32_16x16x32_bf16 v[112:115], v[120:123], v[168:171], v[112:115]
	v_mfma_f32_16x16x32_bf16 v[128:131], v[104:107], v[168:171], v[128:131]
	v_mfma_f32_16x16x32_bf16 v[132:135], v[96:99], v[168:171], v[132:135]
	v_mfma_f32_16x16x32_bf16 v[92:95], v[96:99], v[176:179], v[92:95]
	v_mfma_f32_16x16x32_bf16 v[88:91], v[104:107], v[176:179], v[88:91]
	v_mfma_f32_16x16x32_bf16 v[84:87], v[120:123], v[176:179], v[84:87]
	v_mfma_f32_16x16x32_bf16 v[80:83], v[136:139], v[176:179], v[80:83]
	v_mfma_f32_16x16x32_bf16 v[64:67], v[136:139], v[184:187], v[64:67]
	v_mfma_f32_16x16x32_bf16 v[68:71], v[120:123], v[184:187], v[68:71]
	v_mfma_f32_16x16x32_bf16 v[72:75], v[104:107], v[184:187], v[72:75]
	v_mfma_f32_16x16x32_bf16 v[76:79], v[96:99], v[184:187], v[76:79]
	s_setprio 0
	s_setprio 1
	v_mfma_f32_16x16x32_bf16 v[156:159], v[100:103], v[164:167], v[156:159]
	v_mfma_f32_16x16x32_bf16 v[152:155], v[116:119], v[164:167], v[152:155]
	v_mfma_f32_16x16x32_bf16 v[144:147], v[124:127], v[164:167], v[144:147]
	v_mfma_f32_16x16x32_bf16 v[140:143], v[148:151], v[164:167], v[140:143]
	v_mfma_f32_16x16x32_bf16 v[108:111], v[148:151], v[172:175], v[108:111]
	v_mfma_f32_16x16x32_bf16 v[112:115], v[124:127], v[172:175], v[112:115]
	v_mfma_f32_16x16x32_bf16 v[128:131], v[116:119], v[172:175], v[128:131]
	v_mfma_f32_16x16x32_bf16 v[132:135], v[100:103], v[172:175], v[132:135]
	v_mfma_f32_16x16x32_bf16 v[92:95], v[100:103], v[180:183], v[92:95]
	v_mfma_f32_16x16x32_bf16 v[88:91], v[116:119], v[180:183], v[88:91]
	v_mfma_f32_16x16x32_bf16 v[84:87], v[124:127], v[180:183], v[84:87]
	v_mfma_f32_16x16x32_bf16 v[80:83], v[148:151], v[180:183], v[80:83]
	v_mfma_f32_16x16x32_bf16 v[64:67], v[148:151], v[188:191], v[64:67]
	v_mfma_f32_16x16x32_bf16 v[68:71], v[124:127], v[188:191], v[68:71]
	v_mfma_f32_16x16x32_bf16 v[72:75], v[116:119], v[188:191], v[72:75]
	v_mfma_f32_16x16x32_bf16 v[76:79], v[100:103], v[188:191], v[76:79]
	s_setprio 0
	s_barrier
	s_add_i32 s57, s47, s30
	v_lshl_add_u64 v[192:193], s[24:25], 0, v[210:211]
	s_mov_b32 m0, s57
	ds_read_b128 v[160:163], v232 offset:16384
	ds_read_b128 v[164:167], v232 offset:17408
	ds_read_b128 v[168:171], v232 offset:18432
	ds_read_b128 v[172:175], v232 offset:19456
	ds_read_b128 v[176:179], v232 offset:20480
	ds_read_b128 v[180:183], v232 offset:21504
	ds_read_b128 v[184:187], v232 offset:22528
	ds_read_b128 v[188:191], v232 offset:23552
	global_load_lds_dwordx4 v[192:193], off
	s_add_i32 m0, s57, 0x2000
	s_add_u32 s58, s24, 0x40000
	v_lshl_add_u64 v[194:195], s[24:25], 0, v[214:215]
	s_addc_u32 s59, s25, 0
	s_add_i32 s57, s48, s30
	global_load_lds_dwordx4 v[194:195], off
	v_lshl_add_u64 v[196:197], s[58:59], 0, v[210:211]
	s_mov_b32 m0, s57
	v_lshl_add_u64 v[198:199], s[26:27], 0, v[212:213]
	global_load_lds_dwordx4 v[196:197], off
	v_lshl_add_u64 v[196:197], s[58:59], 0, v[214:215]
	s_add_i32 m0, s57, 0x2000
	s_nop 0
	global_load_lds_dwordx4 v[196:197], off
	v_lshl_add_u64 v[196:197], s[26:27], 0, v[208:209]
	s_mov_b32 m0, s31
	s_nop 0
	global_load_lds_dwordx4 v[196:197], off
	s_mov_b32 m0, s34
	s_nop 0
	global_load_lds_dwordx4 v[198:199], off
	s_waitcnt vmcnt(8)
	s_waitcnt lgkmcnt(0)
	s_barrier
; #define PG8_STAGE(bufoff, gbase, voff) do { _Pragma("unroll") for (int _i = 0; _i < 2; ++_i) \
;         __builtin_amdgcn_global_load_lds((const unsigned*)((const char*)(gbase) + (voff)[_i]), (LAS unsigned*)(lds + (bufoff) + ldsw + _i * 8192), 16, 0, 0); } while (0)
; #define PG8_LDA(dst, b, h) do { _Pragma("unroll") for (int m = 0; m < 4; ++m) _Pragma("unroll") for (int k = 0; k < 2; ++k) dst[m][k] = *(const LAS bf16x8*)(lds + PG8_SA(b, h) + aoff + m * 2048 + k * 1024); } while (0)
; #define PG8_LDB(dst, b, h) do { _Pragma("unroll") for (int n = 0; n < 2; ++n) _Pragma("unroll") for (int k = 0; k < 2; ++k) dst[n][k] = *(const LAS bf16x8*)(lds + PG8_SB(b, h) + boff + n * 2048 + k * 1024); } while (0)
; #define PG8_MMA(ai, bj, At, Bt) do { __builtin_amdgcn_s_setprio(1); _Pragma("unroll") for (int m = 0; m < 4; ++m) _Pragma("unroll") for (int n = 0; n < 2; ++n) _Pragma("unroll") for (int k = 0; k < 2; ++k) \
;         acc[ai][bj][m][n] = __builtin_amdgcn_mfma_f32_16x16x32_bf16(Bt[n][k], At[m][k], acc[ai][bj][m][n], 0, 0, 0); __builtin_amdgcn_s_setprio(0); } while (0)
; #define PG8_WAIT_V(n) asm volatile("s_waitcnt vmcnt(" #n ")" ::: "memory")
; #define PG8_WAIT_L(n) asm volatile("s_waitcnt lgkmcnt(" #n ")" ::: "memory")
; #define PG8_BAR __builtin_amdgcn_s_barrier()
; #define PG8_SCHED __builtin_amdgcn_sched_barrier(0)
; template <class Epi>
; __device__ __forceinline__ void gemm_phase(LAS unsigned char* lds, const Gemm g, const StaticOrder& S, const Epi& E) {
;     ...
;             PG8_WAIT_V(8); PG8_WAIT_L(0); PG8_BAR; PG8_MMA(1, 0, At, B0); PG8_MMA(1, 1, At, B1); PG8_BAR; PG8_SCHED;
;             PG8_LDB(B0, 1, 0); PG8_LDB(B1, 1, 1); PG8_SCHED; PG8_LDA(At, 1, 0); PG8_STAGE(PG8_SA(0, 1), a2 + hstepA, voffA);
;             PG8_WAIT_V(8); PG8_WAIT_L(0); PG8_BAR; PG8_MMA(0, 0, At, B0); PG8_MMA(0, 1, At, B1); PG8_BAR; PG8_SCHED;
	s_setprio 1
	s_waitcnt lgkmcnt(0)
	v_mfma_f32_16x16x32_bf16 v[60:63], v[96:99], v[160:163], v[60:63]
	v_mfma_f32_16x16x32_bf16 v[56:59], v[104:107], v[160:163], v[56:59]
	v_mfma_f32_16x16x32_bf16 v[52:55], v[120:123], v[160:163], v[52:55]
	v_mfma_f32_16x16x32_bf16 v[48:51], v[136:139], v[160:163], v[48:51]
	v_mfma_f32_16x16x32_bf16 v[32:35], v[136:139], v[168:171], v[32:35]
	v_mfma_f32_16x16x32_bf16 v[36:39], v[120:123], v[168:171], v[36:39]
	v_mfma_f32_16x16x32_bf16 v[40:43], v[104:107], v[168:171], v[40:43]
	v_mfma_f32_16x16x32_bf16 v[44:47], v[96:99], v[168:171], v[44:47]
	v_mfma_f32_16x16x32_bf16 v[28:31], v[96:99], v[176:179], v[28:31]
	v_mfma_f32_16x16x32_bf16 v[24:27], v[104:107], v[176:179], v[24:27]
	v_mfma_f32_16x16x32_bf16 v[20:23], v[120:123], v[176:179], v[20:23]
	v_mfma_f32_16x16x32_bf16 v[16:19], v[136:139], v[176:179], v[16:19]
	v_mfma_f32_16x16x32_bf16 v[0:3], v[136:139], v[184:187], v[0:3]
	v_mfma_f32_16x16x32_bf16 v[4:7], v[120:123], v[184:187], v[4:7]
	v_mfma_f32_16x16x32_bf16 v[8:11], v[104:107], v[184:187], v[8:11]
	v_mfma_f32_16x16x32_bf16 v[12:15], v[96:99], v[184:187], v[12:15]
	s_setprio 0
	s_setprio 1
	v_mfma_f32_16x16x32_bf16 v[60:63], v[100:103], v[164:167], v[60:63]
	v_mfma_f32_16x16x32_bf16 v[56:59], v[116:119], v[164:167], v[56:59]
	v_mfma_f32_16x16x32_bf16 v[52:55], v[124:127], v[164:167], v[52:55]
	v_mfma_f32_16x16x32_bf16 v[48:51], v[148:151], v[164:167], v[48:51]
	v_mfma_f32_16x16x32_bf16 v[32:35], v[148:151], v[172:175], v[32:35]
	v_mfma_f32_16x16x32_bf16 v[36:39], v[124:127], v[172:175], v[36:39]
	v_mfma_f32_16x16x32_bf16 v[40:43], v[116:119], v[172:175], v[40:43]
	v_mfma_f32_16x16x32_bf16 v[44:47], v[100:103], v[172:175], v[44:47]
	v_mfma_f32_16x16x32_bf16 v[28:31], v[100:103], v[180:183], v[28:31]
	v_mfma_f32_16x16x32_bf16 v[24:27], v[116:119], v[180:183], v[24:27]
	v_mfma_f32_16x16x32_bf16 v[20:23], v[124:127], v[180:183], v[20:23]
	v_mfma_f32_16x16x32_bf16 v[16:19], v[148:151], v[180:183], v[16:19]
	v_mfma_f32_16x16x32_bf16 v[0:3], v[148:151], v[188:191], v[0:3]
	v_mfma_f32_16x16x32_bf16 v[4:7], v[124:127], v[188:191], v[4:7]
	v_mfma_f32_16x16x32_bf16 v[8:11], v[116:119], v[188:191], v[8:11]
	v_mfma_f32_16x16x32_bf16 v[12:15], v[100:103], v[188:191], v[12:15]
	s_setprio 0
	s_barrier
	s_add_i32 s57, 0, 0x18000
	s_add_i32 s58, 0, 0x1c000
	v_add_u32_e32 v116, s57, v229
	v_add_u32_e32 v148, s58, v229
	ds_read_b128 v[96:99], v116
	ds_read_b128 v[100:103], v116 offset:1024
	ds_read_b128 v[104:107], v116 offset:2048
	ds_read_b128 v[116:119], v116 offset:3072
	ds_read_b128 v[120:123], v148
	ds_read_b128 v[124:127], v148 offset:1024
	ds_read_b128 v[136:139], v148 offset:2048
	ds_read_b128 v[148:151], v148 offset:3072
	s_add_u32 s26, s26, 0x40000
	s_addc_u32 s27, s27, 0
	s_mov_b32 m0, s35
	v_lshl_add_u64 v[200:201], s[26:27], 0, v[208:209]
	ds_read_b128 v[160:163], v232 offset:32768
	ds_read_b128 v[164:167], v232 offset:33792
	ds_read_b128 v[168:171], v232 offset:34816
	ds_read_b128 v[172:175], v232 offset:35840
	ds_read_b128 v[176:179], v232 offset:36864
	ds_read_b128 v[180:183], v232 offset:37888
	ds_read_b128 v[184:187], v232 offset:38912
	ds_read_b128 v[188:191], v232 offset:39936
	global_load_lds_dwordx4 v[200:201], off
	v_lshl_add_u64 v[200:201], s[26:27], 0, v[212:213]
	s_mov_b32 m0, s36
	s_nop 0
	global_load_lds_dwordx4 v[200:201], off
	s_waitcnt vmcnt(8)
	s_waitcnt lgkmcnt(0)
	s_barrier
	s_setprio 1
	s_waitcnt lgkmcnt(0)
	v_mfma_f32_16x16x32_bf16 v[156:159], v[96:99], v[160:163], v[156:159]
	v_mfma_f32_16x16x32_bf16 v[152:155], v[104:107], v[160:163], v[152:155]
	v_mfma_f32_16x16x32_bf16 v[144:147], v[120:123], v[160:163], v[144:147]
	v_mfma_f32_16x16x32_bf16 v[140:143], v[136:139], v[160:163], v[140:143]
	v_mfma_f32_16x16x32_bf16 v[108:111], v[136:139], v[168:171], v[108:111]
	v_mfma_f32_16x16x32_bf16 v[112:115], v[120:123], v[168:171], v[112:115]
	v_mfma_f32_16x16x32_bf16 v[128:131], v[104:107], v[168:171], v[128:131]
	v_mfma_f32_16x16x32_bf16 v[132:135], v[96:99], v[168:171], v[132:135]
	v_mfma_f32_16x16x32_bf16 v[92:95], v[96:99], v[176:179], v[92:95]
	v_mfma_f32_16x16x32_bf16 v[88:91], v[104:107], v[176:179], v[88:91]
	v_mfma_f32_16x16x32_bf16 v[84:87], v[120:123], v[176:179], v[84:87]
	v_mfma_f32_16x16x32_bf16 v[80:83], v[136:139], v[176:179], v[80:83]
	v_mfma_f32_16x16x32_bf16 v[64:67], v[136:139], v[184:187], v[64:67]
	v_mfma_f32_16x16x32_bf16 v[68:71], v[120:123], v[184:187], v[68:71]
	v_mfma_f32_16x16x32_bf16 v[72:75], v[104:107], v[184:187], v[72:75]
	v_mfma_f32_16x16x32_bf16 v[76:79], v[96:99], v[184:187], v[76:79]
	s_setprio 0
	s_setprio 1
	v_mfma_f32_16x16x32_bf16 v[156:159], v[100:103], v[164:167], v[156:159]
	v_mfma_f32_16x16x32_bf16 v[152:155], v[116:119], v[164:167], v[152:155]
	v_mfma_f32_16x16x32_bf16 v[144:147], v[124:127], v[164:167], v[144:147]
	v_mfma_f32_16x16x32_bf16 v[140:143], v[148:151], v[164:167], v[140:143]
	v_mfma_f32_16x16x32_bf16 v[108:111], v[148:151], v[172:175], v[108:111]
	v_mfma_f32_16x16x32_bf16 v[112:115], v[124:127], v[172:175], v[112:115]
	v_mfma_f32_16x16x32_bf16 v[128:131], v[116:119], v[172:175], v[128:131]
	v_mfma_f32_16x16x32_bf16 v[132:135], v[100:103], v[172:175], v[132:135]
	v_mfma_f32_16x16x32_bf16 v[92:95], v[100:103], v[180:183], v[92:95]
	v_mfma_f32_16x16x32_bf16 v[88:91], v[116:119], v[180:183], v[88:91]
	v_mfma_f32_16x16x32_bf16 v[84:87], v[124:127], v[180:183], v[84:87]
	v_mfma_f32_16x16x32_bf16 v[80:83], v[148:151], v[180:183], v[80:83]
	v_mfma_f32_16x16x32_bf16 v[64:67], v[148:151], v[188:191], v[64:67]
	v_mfma_f32_16x16x32_bf16 v[68:71], v[124:127], v[188:191], v[68:71]
	v_mfma_f32_16x16x32_bf16 v[72:75], v[116:119], v[188:191], v[72:75]
	v_mfma_f32_16x16x32_bf16 v[76:79], v[100:103], v[188:191], v[76:79]
	s_setprio 0
	s_barrier
; #define PG8_STAGE(bufoff, gbase, voff) do { _Pragma("unroll") for (int _i = 0; _i < 2; ++_i) \
;         __builtin_amdgcn_global_load_lds((const unsigned*)((const char*)(gbase) + (voff)[_i]), (LAS unsigned*)(lds + (bufoff) + ldsw + _i * 8192), 16, 0, 0); } while (0)
; #define PG8_LDA(dst, b, h) do { _Pragma("unroll") for (int m = 0; m < 4; ++m) _Pragma("unroll") for (int k = 0; k < 2; ++k) dst[m][k] = *(const LAS bf16x8*)(lds + PG8_SA(b, h) + aoff + m * 2048 + k * 1024); } while (0)
; #define PG8_MMA(ai, bj, At, Bt) do { __builtin_amdgcn_s_setprio(1); _Pragma("unroll") for (int m = 0; m < 4; ++m) _Pragma("unroll") for (int n = 0; n < 2; ++n) _Pragma("unroll") for (int k = 0; k < 2; ++k) \
;         acc[ai][bj][m][n] = __builtin_amdgcn_mfma_f32_16x16x32_bf16(Bt[n][k], At[m][k], acc[ai][bj][m][n], 0, 0, 0); __builtin_amdgcn_s_setprio(0); } while (0)
; #define PG8_WAIT_V(n) asm volatile("s_waitcnt vmcnt(" #n ")" ::: "memory")
; #define PG8_WAIT_L(n) asm volatile("s_waitcnt lgkmcnt(" #n ")" ::: "memory")
; #define PG8_BAR __builtin_amdgcn_s_barrier()
; #define PG8_SCHED __builtin_amdgcn_sched_barrier(0)
; template <class Epi>
; __device__ __forceinline__ void gemm_phase(LAS unsigned char* lds, const Gemm g, const StaticOrder& S, const Epi& E) {
;     ...
;         for (int t = 0; t < nt; t += 2) {
;     ...
;             PG8_LDA(At, 1, 1); PG8_STAGE(PG8_SB(1, 0), b3, voffB); PG8_STAGE(PG8_SB(1, 1), b3 + hstepB, voffB); PG8_STAGE(PG8_SA(1, 0), a3, voffA);
;             PG8_WAIT_V(8); PG8_WAIT_L(0); PG8_BAR; PG8_MMA(1, 0, At, B0); PG8_MMA(1, 1, At, B1); PG8_BAR; PG8_SCHED;
	s_add_i32 s26, s57, s30
	v_lshl_add_u64 v[192:193], v[192:193], 0, s[10:11]
	s_mov_b32 m0, s26
	ds_read_b128 v[160:163], v232 offset:49152
	ds_read_b128 v[164:167], v232 offset:50176
	ds_read_b128 v[168:171], v232 offset:51200
	ds_read_b128 v[172:175], v232 offset:52224
	ds_read_b128 v[176:179], v232 offset:53248
	ds_read_b128 v[180:183], v232 offset:54272
	ds_read_b128 v[184:187], v232 offset:55296
	ds_read_b128 v[188:191], v232 offset:56320
	global_load_lds_dwordx4 v[192:193], off
	s_add_i32 m0, s26, 0x2000
	s_add_u32 s24, s24, 0x40080
	v_lshl_add_u64 v[192:193], v[194:195], 0, s[10:11]
	s_addc_u32 s25, s25, 0
	s_add_i32 s26, s58, s30
	global_load_lds_dwordx4 v[192:193], off
	v_lshl_add_u64 v[192:193], s[24:25], 0, v[210:211]
	s_mov_b32 m0, s26
	s_nop 0
	global_load_lds_dwordx4 v[192:193], off
	v_lshl_add_u64 v[192:193], s[24:25], 0, v[214:215]
	s_add_i32 m0, s26, 0x2000
	s_nop 0
	global_load_lds_dwordx4 v[192:193], off
	v_lshl_add_u64 v[192:193], v[196:197], 0, s[10:11]
	s_mov_b32 m0, s40
	s_nop 0
	global_load_lds_dwordx4 v[192:193], off
	v_lshl_add_u64 v[192:193], v[198:199], 0, s[10:11]
	s_mov_b32 m0, s41
	s_nop 0
	global_load_lds_dwordx4 v[192:193], off
	s_waitcnt vmcnt(8)
	s_waitcnt lgkmcnt(0)
	s_barrier
	s_setprio 1
	s_waitcnt lgkmcnt(0)
	v_mfma_f32_16x16x32_bf16 v[60:63], v[96:99], v[160:163], v[60:63]
	v_mfma_f32_16x16x32_bf16 v[56:59], v[104:107], v[160:163], v[56:59]
	v_mfma_f32_16x16x32_bf16 v[52:55], v[120:123], v[160:163], v[52:55]
	v_mfma_f32_16x16x32_bf16 v[48:51], v[136:139], v[160:163], v[48:51]
	v_mfma_f32_16x16x32_bf16 v[32:35], v[136:139], v[168:171], v[32:35]
	v_mfma_f32_16x16x32_bf16 v[36:39], v[120:123], v[168:171], v[36:39]
	v_mfma_f32_16x16x32_bf16 v[40:43], v[104:107], v[168:171], v[40:43]
	v_mfma_f32_16x16x32_bf16 v[44:47], v[96:99], v[168:171], v[44:47]
	v_mfma_f32_16x16x32_bf16 v[28:31], v[96:99], v[176:179], v[28:31]
	v_mfma_f32_16x16x32_bf16 v[24:27], v[104:107], v[176:179], v[24:27]
	v_mfma_f32_16x16x32_bf16 v[20:23], v[120:123], v[176:179], v[20:23]
	v_mfma_f32_16x16x32_bf16 v[16:19], v[136:139], v[176:179], v[16:19]
	v_mfma_f32_16x16x32_bf16 v[0:3], v[136:139], v[184:187], v[0:3]
	v_mfma_f32_16x16x32_bf16 v[4:7], v[120:123], v[184:187], v[4:7]
	v_mfma_f32_16x16x32_bf16 v[8:11], v[104:107], v[184:187], v[8:11]
	v_mfma_f32_16x16x32_bf16 v[12:15], v[96:99], v[184:187], v[12:15]
	s_setprio 0
	s_setprio 1
	v_mfma_f32_16x16x32_bf16 v[60:63], v[100:103], v[164:167], v[60:63]
	v_mfma_f32_16x16x32_bf16 v[56:59], v[116:119], v[164:167], v[56:59]
	v_mfma_f32_16x16x32_bf16 v[52:55], v[124:127], v[164:167], v[52:55]
	v_mfma_f32_16x16x32_bf16 v[48:51], v[148:151], v[164:167], v[48:51]
	v_mfma_f32_16x16x32_bf16 v[32:35], v[148:151], v[172:175], v[32:35]
	v_mfma_f32_16x16x32_bf16 v[36:39], v[124:127], v[172:175], v[36:39]
	v_mfma_f32_16x16x32_bf16 v[40:43], v[116:119], v[172:175], v[40:43]
	v_mfma_f32_16x16x32_bf16 v[44:47], v[100:103], v[172:175], v[44:47]
	v_mfma_f32_16x16x32_bf16 v[28:31], v[100:103], v[180:183], v[28:31]
	v_mfma_f32_16x16x32_bf16 v[24:27], v[116:119], v[180:183], v[24:27]
	v_mfma_f32_16x16x32_bf16 v[20:23], v[124:127], v[180:183], v[20:23]
	v_mfma_f32_16x16x32_bf16 v[16:19], v[148:151], v[180:183], v[16:19]
	v_mfma_f32_16x16x32_bf16 v[0:3], v[148:151], v[188:191], v[0:3]
	v_mfma_f32_16x16x32_bf16 v[4:7], v[124:127], v[188:191], v[4:7]
	v_mfma_f32_16x16x32_bf16 v[8:11], v[116:119], v[188:191], v[8:11]
	v_mfma_f32_16x16x32_bf16 v[12:15], v[100:103], v[188:191], v[12:15]
	s_setprio 0
	s_barrier
	s_add_u32 s4, s4, 0x100
	s_addc_u32 s5, s5, 0
	s_add_u32 s54, s54, 0x100
	s_addc_u32 s55, s55, 0
	s_cmp_ge_i32 s56, s39
	s_mov_b32 s24, s56
	s_cbranch_scc0 .LBB0_912

; #define PG8_STAGE(bufoff, gbase, voff) do { _Pragma("unroll") for (int _i = 0; _i < 2; ++_i) \
;         __builtin_amdgcn_global_load_lds((const unsigned*)((const char*)(gbase) + (voff)[_i]), (LAS unsigned*)(lds + (bufoff) + ldsw + _i * 8192), 16, 0, 0); } while (0)
; #define PG8_LDA(dst, b, h) do { _Pragma("unroll") for (int m = 0; m < 4; ++m) _Pragma("unroll") for (int k = 0; k < 2; ++k) dst[m][k] = *(const LAS bf16x8*)(lds + PG8_SA(b, h) + aoff + m * 2048 + k * 1024); } while (0)
; #define PG8_LDB(dst, b, h) do { _Pragma("unroll") for (int n = 0; n < 2; ++n) _Pragma("unroll") for (int k = 0; k < 2; ++k) dst[n][k] = *(const LAS bf16x8*)(lds + PG8_SB(b, h) + boff + n * 2048 + k * 1024); } while (0)
; #define PG8_MMA(ai, bj, At, Bt) do { __builtin_amdgcn_s_setprio(1); _Pragma("unroll") for (int m = 0; m < 4; ++m) _Pragma("unroll") for (int n = 0; n < 2; ++n) _Pragma("unroll") for (int k = 0; k < 2; ++k) \
;         acc[ai][bj][m][n] = __builtin_amdgcn_mfma_f32_16x16x32_bf16(Bt[n][k], At[m][k], acc[ai][bj][m][n], 0, 0, 0); __builtin_amdgcn_s_setprio(0); } while (0)
; #define PG8_WAIT_V(n) asm volatile("s_waitcnt vmcnt(" #n ")" ::: "memory")
; #define PG8_WAIT_L(n) asm volatile("s_waitcnt lgkmcnt(" #n ")" ::: "memory")
; #define PG8_BAR __builtin_amdgcn_s_barrier()
; #define PG8_SCHED __builtin_amdgcn_sched_barrier(0)
; template <class Epi>
; __device__ __forceinline__ void gemm_phase(LAS unsigned char* lds, const Gemm g, const StaticOrder& S, const Epi& E) {
;     ...
;         for (int t = 0; t < nt; t += 2) {
;             const bool last = (t == nt - 2);
;             const char* a1 = cA + (size_t)(t + 1) * kstep;
;             const char* a2 = last ? nA : cA + (size_t)(t + 2) * kstep; const char* b2 = last ? nB : cB + (size_t)(t + 2) * kstep;
;             const char* a3 = a2 + kstep; const char* b3 = b2 + kstep;
;             PG8_LDB(B0, 0, 0); PG8_LDB(B1, 0, 1); PG8_SCHED; PG8_LDA(At, 0, 0); PG8_STAGE(PG8_SA(1, 1), a1 + hstepA, voffA);
;             PG8_WAIT_V(8); PG8_WAIT_L(0); PG8_BAR; PG8_MMA(0, 0, At, B0); PG8_MMA(0, 1, At, B1); PG8_BAR; PG8_SCHED;
;             PG8_LDA(At, 0, 1); PG8_STAGE(PG8_SB(0, 0), b2, voffB); PG8_STAGE(PG8_SB(0, 1), b2 + hstepB, voffB); PG8_STAGE(PG8_SA(0, 0), a2, voffA);
;             PG8_WAIT_V(8); PG8_WAIT_L(0); PG8_BAR; PG8_MMA(1, 0, At, B0); PG8_MMA(1, 1, At, B1); PG8_BAR; PG8_SCHED;
.LBB0_1046:
	ds_read_b128 v[128:131], v185
	ds_read_b128 v[132:135], v185 offset:1024
	ds_read_b128 v[136:139], v185 offset:2048
	ds_read_b128 v[140:143], v185 offset:3072
	ds_read_b128 v[144:147], v186
	ds_read_b128 v[148:151], v186 offset:1024
	ds_read_b128 v[152:155], v186 offset:2048
	ds_read_b128 v[156:159], v186 offset:3072
	s_add_i32 s73, s46, 2
	s_add_u32 s47, s12, 0xfff80080
	s_addc_u32 s48, s13, -1
	s_cmp_eq_u32 s62, s46
	s_cselect_b32 s46, s41, s71
	s_cselect_b32 s49, s1, s48
	s_cselect_b32 s48, s33, s47
	s_cselect_b32 s47, s39, s72
	v_lshl_add_u64 v[182:183], s[12:13], 0, v[174:175]
	s_add_i32 m0, s5, 0xc000
	ds_read_b128 v[190:193], v187
	ds_read_b128 v[194:197], v187 offset:1024
	ds_read_b128 v[198:201], v187 offset:2048
	ds_read_b128 v[208:211], v187 offset:3072
	ds_read_b128 v[212:215], v187 offset:4096
	ds_read_b128 v[216:219], v187 offset:5120
	ds_read_b128 v[220:223], v187 offset:6144
	ds_read_b128 v[224:227], v187 offset:7168
	global_load_lds_dwordx4 v[182:183], off
	v_lshl_add_u64 v[182:183], s[12:13], 0, v[176:177]
	s_add_i32 m0, s5, 0xe000
	s_nop 0
	global_load_lds_dwordx4 v[182:183], off
	s_waitcnt vmcnt(8)
	s_waitcnt lgkmcnt(0)
	s_barrier
	s_setprio 1
	s_waitcnt lgkmcnt(0)
	v_mfma_f32_16x16x32_bf16 v[120:123], v[128:131], v[190:193], v[120:123]
	v_mfma_f32_16x16x32_bf16 v[124:127], v[136:139], v[190:193], v[124:127]
	v_mfma_f32_16x16x32_bf16 v[116:119], v[144:147], v[190:193], v[116:119]
	v_mfma_f32_16x16x32_bf16 v[112:115], v[152:155], v[190:193], v[112:115]
	v_mfma_f32_16x16x32_bf16 v[96:99], v[152:155], v[198:201], v[96:99]
	v_mfma_f32_16x16x32_bf16 v[100:103], v[144:147], v[198:201], v[100:103]
	v_mfma_f32_16x16x32_bf16 v[104:107], v[136:139], v[198:201], v[104:107]
	v_mfma_f32_16x16x32_bf16 v[108:111], v[128:131], v[198:201], v[108:111]
	v_mfma_f32_16x16x32_bf16 v[92:95], v[128:131], v[212:215], v[92:95]
	v_mfma_f32_16x16x32_bf16 v[88:91], v[136:139], v[212:215], v[88:91]
	v_mfma_f32_16x16x32_bf16 v[84:87], v[144:147], v[212:215], v[84:87]
	v_mfma_f32_16x16x32_bf16 v[80:83], v[152:155], v[212:215], v[80:83]
	v_mfma_f32_16x16x32_bf16 v[64:67], v[152:155], v[220:223], v[64:67]
	v_mfma_f32_16x16x32_bf16 v[68:71], v[144:147], v[220:223], v[68:71]
	v_mfma_f32_16x16x32_bf16 v[72:75], v[136:139], v[220:223], v[72:75]
	v_mfma_f32_16x16x32_bf16 v[76:79], v[128:131], v[220:223], v[76:79]
	s_setprio 0
	s_setprio 1
	v_mfma_f32_16x16x32_bf16 v[120:123], v[132:135], v[194:197], v[120:123]
	v_mfma_f32_16x16x32_bf16 v[124:127], v[140:143], v[194:197], v[124:127]
	v_mfma_f32_16x16x32_bf16 v[116:119], v[148:151], v[194:197], v[116:119]
	v_mfma_f32_16x16x32_bf16 v[112:115], v[156:159], v[194:197], v[112:115]
	v_mfma_f32_16x16x32_bf16 v[96:99], v[156:159], v[208:211], v[96:99]
	v_mfma_f32_16x16x32_bf16 v[100:103], v[148:151], v[208:211], v[100:103]
	v_mfma_f32_16x16x32_bf16 v[104:107], v[140:143], v[208:211], v[104:107]
	v_mfma_f32_16x16x32_bf16 v[108:111], v[132:135], v[208:211], v[108:111]
	v_mfma_f32_16x16x32_bf16 v[92:95], v[132:135], v[216:219], v[92:95]
	v_mfma_f32_16x16x32_bf16 v[88:91], v[140:143], v[216:219], v[88:91]
	v_mfma_f32_16x16x32_bf16 v[84:87], v[148:151], v[216:219], v[84:87]
	v_mfma_f32_16x16x32_bf16 v[80:83], v[156:159], v[216:219], v[80:83]
	v_mfma_f32_16x16x32_bf16 v[64:67], v[156:159], v[224:227], v[64:67]
	v_mfma_f32_16x16x32_bf16 v[68:71], v[148:151], v[224:227], v[68:71]
	v_mfma_f32_16x16x32_bf16 v[72:75], v[140:143], v[224:227], v[72:75]
	v_mfma_f32_16x16x32_bf16 v[76:79], v[132:135], v[224:227], v[76:79]
	s_setprio 0
	s_barrier
	s_add_i32 s76, s65, s54
	v_lshl_add_u64 v[182:183], s[46:47], 0, v[162:163]
	s_mov_b32 m0, s76
	ds_read_b128 v[190:193], v187 offset:16384
	ds_read_b128 v[194:197], v187 offset:17408
	ds_read_b128 v[198:201], v187 offset:18432
	ds_read_b128 v[208:211], v187 offset:19456
	ds_read_b128 v[212:215], v187 offset:20480
	ds_read_b128 v[216:219], v187 offset:21504
	ds_read_b128 v[220:223], v187 offset:22528
	ds_read_b128 v[224:227], v187 offset:23552
	global_load_lds_dwordx4 v[182:183], off
	s_add_i32 m0, s76, 0x2000
	s_add_u32 s76, s46, 0x80000
	v_lshl_add_u64 v[202:203], s[46:47], 0, v[166:167]
	s_addc_u32 s77, s47, 0
	s_add_i32 s78, s66, s54
	global_load_lds_dwordx4 v[202:203], off
	v_lshl_add_u64 v[230:231], s[76:77], 0, v[162:163]
	s_mov_b32 m0, s78
	v_lshl_add_u64 v[232:233], s[48:49], 0, v[164:165]
	global_load_lds_dwordx4 v[230:231], off
	v_lshl_add_u64 v[230:231], s[76:77], 0, v[166:167]
	s_add_i32 m0, s78, 0x2000
	s_nop 0
	global_load_lds_dwordx4 v[230:231], off
	v_lshl_add_u64 v[230:231], s[48:49], 0, v[160:161]
	s_mov_b32 m0, s5
	s_nop 0
	global_load_lds_dwordx4 v[230:231], off
	s_mov_b32 m0, s55
	s_nop 0
	global_load_lds_dwordx4 v[232:233], off
	s_waitcnt vmcnt(8)
	s_waitcnt lgkmcnt(0)
	s_barrier
; #define PG8_STAGE(bufoff, gbase, voff) do { _Pragma("unroll") for (int _i = 0; _i < 2; ++_i) \
;         __builtin_amdgcn_global_load_lds((const unsigned*)((const char*)(gbase) + (voff)[_i]), (LAS unsigned*)(lds + (bufoff) + ldsw + _i * 8192), 16, 0, 0); } while (0)
; #define PG8_LDA(dst, b, h) do { _Pragma("unroll") for (int m = 0; m < 4; ++m) _Pragma("unroll") for (int k = 0; k < 2; ++k) dst[m][k] = *(const LAS bf16x8*)(lds + PG8_SA(b, h) + aoff + m * 2048 + k * 1024); } while (0)
; #define PG8_LDB(dst, b, h) do { _Pragma("unroll") for (int n = 0; n < 2; ++n) _Pragma("unroll") for (int k = 0; k < 2; ++k) dst[n][k] = *(const LAS bf16x8*)(lds + PG8_SB(b, h) + boff + n * 2048 + k * 1024); } while (0)
; #define PG8_MMA(ai, bj, At, Bt) do { __builtin_amdgcn_s_setprio(1); _Pragma("unroll") for (int m = 0; m < 4; ++m) _Pragma("unroll") for (int n = 0; n < 2; ++n) _Pragma("unroll") for (int k = 0; k < 2; ++k) \
;         acc[ai][bj][m][n] = __builtin_amdgcn_mfma_f32_16x16x32_bf16(Bt[n][k], At[m][k], acc[ai][bj][m][n], 0, 0, 0); __builtin_amdgcn_s_setprio(0); } while (0)
; #define PG8_WAIT_V(n) asm volatile("s_waitcnt vmcnt(" #n ")" ::: "memory")
; #define PG8_WAIT_L(n) asm volatile("s_waitcnt lgkmcnt(" #n ")" ::: "memory")
; #define PG8_BAR __builtin_amdgcn_s_barrier()
; #define PG8_SCHED __builtin_amdgcn_sched_barrier(0)
; template <class Epi>
; __device__ __forceinline__ void gemm_phase(LAS unsigned char* lds, const Gemm g, const StaticOrder& S, const Epi& E) {
;     ...
;             PG8_WAIT_V(8); PG8_WAIT_L(0); PG8_BAR; PG8_MMA(1, 0, At, B0); PG8_MMA(1, 1, At, B1); PG8_BAR; PG8_SCHED;
;             PG8_LDB(B0, 1, 0); PG8_LDB(B1, 1, 1); PG8_SCHED; PG8_LDA(At, 1, 0); PG8_STAGE(PG8_SA(0, 1), a2 + hstepA, voffA);
;             PG8_WAIT_V(8); PG8_WAIT_L(0); PG8_BAR; PG8_MMA(0, 0, At, B0); PG8_MMA(0, 1, At, B1); PG8_BAR; PG8_SCHED;
	s_setprio 1
	s_waitcnt lgkmcnt(0)
	v_mfma_f32_16x16x32_bf16 v[60:63], v[128:131], v[190:193], v[60:63]
	v_mfma_f32_16x16x32_bf16 v[56:59], v[136:139], v[190:193], v[56:59]
	v_mfma_f32_16x16x32_bf16 v[52:55], v[144:147], v[190:193], v[52:55]
	v_mfma_f32_16x16x32_bf16 v[48:51], v[152:155], v[190:193], v[48:51]
	v_mfma_f32_16x16x32_bf16 v[32:35], v[152:155], v[198:201], v[32:35]
	v_mfma_f32_16x16x32_bf16 v[36:39], v[144:147], v[198:201], v[36:39]
	v_mfma_f32_16x16x32_bf16 v[40:43], v[136:139], v[198:201], v[40:43]
	v_mfma_f32_16x16x32_bf16 v[44:47], v[128:131], v[198:201], v[44:47]
	v_mfma_f32_16x16x32_bf16 v[28:31], v[128:131], v[212:215], v[28:31]
	v_mfma_f32_16x16x32_bf16 v[24:27], v[136:139], v[212:215], v[24:27]
	v_mfma_f32_16x16x32_bf16 v[20:23], v[144:147], v[212:215], v[20:23]
	v_mfma_f32_16x16x32_bf16 v[16:19], v[152:155], v[212:215], v[16:19]
	v_mfma_f32_16x16x32_bf16 v[0:3], v[152:155], v[220:223], v[0:3]
	v_mfma_f32_16x16x32_bf16 v[4:7], v[144:147], v[220:223], v[4:7]
	v_mfma_f32_16x16x32_bf16 v[8:11], v[136:139], v[220:223], v[8:11]
	v_mfma_f32_16x16x32_bf16 v[12:15], v[128:131], v[220:223], v[12:15]
	s_setprio 0
	s_setprio 1
	v_mfma_f32_16x16x32_bf16 v[60:63], v[132:135], v[194:197], v[60:63]
	v_mfma_f32_16x16x32_bf16 v[56:59], v[140:143], v[194:197], v[56:59]
	v_mfma_f32_16x16x32_bf16 v[52:55], v[148:151], v[194:197], v[52:55]
	v_mfma_f32_16x16x32_bf16 v[48:51], v[156:159], v[194:197], v[48:51]
	v_mfma_f32_16x16x32_bf16 v[32:35], v[156:159], v[208:211], v[32:35]
	v_mfma_f32_16x16x32_bf16 v[36:39], v[148:151], v[208:211], v[36:39]
	v_mfma_f32_16x16x32_bf16 v[40:43], v[140:143], v[208:211], v[40:43]
	v_mfma_f32_16x16x32_bf16 v[44:47], v[132:135], v[208:211], v[44:47]
	v_mfma_f32_16x16x32_bf16 v[28:31], v[132:135], v[216:219], v[28:31]
	v_mfma_f32_16x16x32_bf16 v[24:27], v[140:143], v[216:219], v[24:27]
	v_mfma_f32_16x16x32_bf16 v[20:23], v[148:151], v[216:219], v[20:23]
	v_mfma_f32_16x16x32_bf16 v[16:19], v[156:159], v[216:219], v[16:19]
	v_mfma_f32_16x16x32_bf16 v[0:3], v[156:159], v[224:227], v[0:3]
	v_mfma_f32_16x16x32_bf16 v[4:7], v[148:151], v[224:227], v[4:7]
	v_mfma_f32_16x16x32_bf16 v[8:11], v[140:143], v[224:227], v[8:11]
	v_mfma_f32_16x16x32_bf16 v[12:15], v[132:135], v[224:227], v[12:15]
	s_setprio 0
	s_barrier
	s_add_i32 s76, 0, 0x18000
	s_add_i32 s77, 0, 0x1c000
	v_add_u32_e32 v140, s76, v184
	v_add_u32_e32 v156, s77, v184
	ds_read_b128 v[128:131], v140
	ds_read_b128 v[132:135], v140 offset:1024
	ds_read_b128 v[136:139], v140 offset:2048
	ds_read_b128 v[140:143], v140 offset:3072
	ds_read_b128 v[144:147], v156
	ds_read_b128 v[148:151], v156 offset:1024
	ds_read_b128 v[152:155], v156 offset:2048
	ds_read_b128 v[156:159], v156 offset:3072
	s_add_u32 s48, s48, 0x80000
	s_addc_u32 s49, s49, 0
	s_mov_b32 m0, s56
	v_lshl_add_u64 v[234:235], s[48:49], 0, v[160:161]
	ds_read_b128 v[190:193], v187 offset:32768
	ds_read_b128 v[194:197], v187 offset:33792
	ds_read_b128 v[198:201], v187 offset:34816
	ds_read_b128 v[208:211], v187 offset:35840
	ds_read_b128 v[212:215], v187 offset:36864
	ds_read_b128 v[216:219], v187 offset:37888
	ds_read_b128 v[220:223], v187 offset:38912
	ds_read_b128 v[224:227], v187 offset:39936
	global_load_lds_dwordx4 v[234:235], off
	v_lshl_add_u64 v[234:235], s[48:49], 0, v[164:165]
	s_mov_b32 m0, s57
	s_nop 0
	global_load_lds_dwordx4 v[234:235], off
	s_waitcnt vmcnt(8)
	s_waitcnt lgkmcnt(0)
	s_barrier
	s_setprio 1
	s_waitcnt lgkmcnt(0)
	v_mfma_f32_16x16x32_bf16 v[120:123], v[128:131], v[190:193], v[120:123]
	v_mfma_f32_16x16x32_bf16 v[124:127], v[136:139], v[190:193], v[124:127]
	v_mfma_f32_16x16x32_bf16 v[116:119], v[144:147], v[190:193], v[116:119]
	v_mfma_f32_16x16x32_bf16 v[112:115], v[152:155], v[190:193], v[112:115]
	v_mfma_f32_16x16x32_bf16 v[96:99], v[152:155], v[198:201], v[96:99]
	v_mfma_f32_16x16x32_bf16 v[100:103], v[144:147], v[198:201], v[100:103]
	v_mfma_f32_16x16x32_bf16 v[104:107], v[136:139], v[198:201], v[104:107]
	v_mfma_f32_16x16x32_bf16 v[108:111], v[128:131], v[198:201], v[108:111]
	v_mfma_f32_16x16x32_bf16 v[92:95], v[128:131], v[212:215], v[92:95]
	v_mfma_f32_16x16x32_bf16 v[88:91], v[136:139], v[212:215], v[88:91]
	v_mfma_f32_16x16x32_bf16 v[84:87], v[144:147], v[212:215], v[84:87]
	v_mfma_f32_16x16x32_bf16 v[80:83], v[152:155], v[212:215], v[80:83]
	v_mfma_f32_16x16x32_bf16 v[64:67], v[152:155], v[220:223], v[64:67]
	v_mfma_f32_16x16x32_bf16 v[68:71], v[144:147], v[220:223], v[68:71]
	v_mfma_f32_16x16x32_bf16 v[72:75], v[136:139], v[220:223], v[72:75]
	v_mfma_f32_16x16x32_bf16 v[76:79], v[128:131], v[220:223], v[76:79]
	s_setprio 0
	s_setprio 1
	v_mfma_f32_16x16x32_bf16 v[120:123], v[132:135], v[194:197], v[120:123]
	v_mfma_f32_16x16x32_bf16 v[124:127], v[140:143], v[194:197], v[124:127]
	v_mfma_f32_16x16x32_bf16 v[116:119], v[148:151], v[194:197], v[116:119]
	v_mfma_f32_16x16x32_bf16 v[112:115], v[156:159], v[194:197], v[112:115]
	v_mfma_f32_16x16x32_bf16 v[96:99], v[156:159], v[208:211], v[96:99]
	v_mfma_f32_16x16x32_bf16 v[100:103], v[148:151], v[208:211], v[100:103]
	v_mfma_f32_16x16x32_bf16 v[104:107], v[140:143], v[208:211], v[104:107]
	v_mfma_f32_16x16x32_bf16 v[108:111], v[132:135], v[208:211], v[108:111]
	v_mfma_f32_16x16x32_bf16 v[92:95], v[132:135], v[216:219], v[92:95]
	v_mfma_f32_16x16x32_bf16 v[88:91], v[140:143], v[216:219], v[88:91]
	v_mfma_f32_16x16x32_bf16 v[84:87], v[148:151], v[216:219], v[84:87]
	v_mfma_f32_16x16x32_bf16 v[80:83], v[156:159], v[216:219], v[80:83]
	v_mfma_f32_16x16x32_bf16 v[64:67], v[156:159], v[224:227], v[64:67]
	v_mfma_f32_16x16x32_bf16 v[68:71], v[148:151], v[224:227], v[68:71]
	v_mfma_f32_16x16x32_bf16 v[72:75], v[140:143], v[224:227], v[72:75]
	v_mfma_f32_16x16x32_bf16 v[76:79], v[132:135], v[224:227], v[76:79]
	s_setprio 0
	s_barrier
; #define PG8_STAGE(bufoff, gbase, voff) do { _Pragma("unroll") for (int _i = 0; _i < 2; ++_i) \
;         __builtin_amdgcn_global_load_lds((const unsigned*)((const char*)(gbase) + (voff)[_i]), (LAS unsigned*)(lds + (bufoff) + ldsw + _i * 8192), 16, 0, 0); } while (0)
; #define PG8_LDA(dst, b, h) do { _Pragma("unroll") for (int m = 0; m < 4; ++m) _Pragma("unroll") for (int k = 0; k < 2; ++k) dst[m][k] = *(const LAS bf16x8*)(lds + PG8_SA(b, h) + aoff + m * 2048 + k * 1024); } while (0)
; #define PG8_MMA(ai, bj, At, Bt) do { __builtin_amdgcn_s_setprio(1); _Pragma("unroll") for (int m = 0; m < 4; ++m) _Pragma("unroll") for (int n = 0; n < 2; ++n) _Pragma("unroll") for (int k = 0; k < 2; ++k) \
;         acc[ai][bj][m][n] = __builtin_amdgcn_mfma_f32_16x16x32_bf16(Bt[n][k], At[m][k], acc[ai][bj][m][n], 0, 0, 0); __builtin_amdgcn_s_setprio(0); } while (0)
; #define PG8_WAIT_V(n) asm volatile("s_waitcnt vmcnt(" #n ")" ::: "memory")
; #define PG8_WAIT_L(n) asm volatile("s_waitcnt lgkmcnt(" #n ")" ::: "memory")
; #define PG8_BAR __builtin_amdgcn_s_barrier()
; #define PG8_SCHED __builtin_amdgcn_sched_barrier(0)
; template <class Epi>
; __device__ __forceinline__ void gemm_phase(LAS unsigned char* lds, const Gemm g, const StaticOrder& S, const Epi& E) {
;     ...
;         for (int t = 0; t < nt; t += 2) {
;     ...
;             PG8_LDA(At, 1, 1); PG8_STAGE(PG8_SB(1, 0), b3, voffB); PG8_STAGE(PG8_SB(1, 1), b3 + hstepB, voffB); PG8_STAGE(PG8_SA(1, 0), a3, voffA);
;             PG8_WAIT_V(8); PG8_WAIT_L(0); PG8_BAR; PG8_MMA(1, 0, At, B0); PG8_MMA(1, 1, At, B1); PG8_BAR; PG8_SCHED;
	s_add_i32 s48, s76, s54
	v_lshl_add_u64 v[182:183], v[182:183], 0, s[16:17]
	s_mov_b32 m0, s48
	ds_read_b128 v[190:193], v187 offset:49152
	ds_read_b128 v[194:197], v187 offset:50176
	ds_read_b128 v[198:201], v187 offset:51200
	ds_read_b128 v[208:211], v187 offset:52224
	ds_read_b128 v[212:215], v187 offset:53248
	ds_read_b128 v[216:219], v187 offset:54272
	ds_read_b128 v[220:223], v187 offset:55296
	ds_read_b128 v[224:227], v187 offset:56320
	global_load_lds_dwordx4 v[182:183], off
	s_add_i32 m0, s48, 0x2000
	s_add_u32 s46, s46, 0x80080
	v_lshl_add_u64 v[182:183], v[202:203], 0, s[16:17]
	s_addc_u32 s47, s47, 0
	s_add_i32 s48, s77, s54
	global_load_lds_dwordx4 v[182:183], off
	v_lshl_add_u64 v[182:183], s[46:47], 0, v[162:163]
	s_mov_b32 m0, s48
	s_nop 0
	global_load_lds_dwordx4 v[182:183], off
	v_lshl_add_u64 v[182:183], s[46:47], 0, v[166:167]
	s_add_i32 m0, s48, 0x2000
	s_nop 0
	global_load_lds_dwordx4 v[182:183], off
	v_lshl_add_u64 v[182:183], v[230:231], 0, s[16:17]
	s_mov_b32 m0, s60
	s_nop 0
	global_load_lds_dwordx4 v[182:183], off
	v_lshl_add_u64 v[182:183], v[232:233], 0, s[16:17]
	s_mov_b32 m0, s61
	s_nop 0
	global_load_lds_dwordx4 v[182:183], off
	s_waitcnt vmcnt(8)
	s_waitcnt lgkmcnt(0)
	s_barrier
	s_setprio 1
	s_waitcnt lgkmcnt(0)
	v_mfma_f32_16x16x32_bf16 v[60:63], v[128:131], v[190:193], v[60:63]
	v_mfma_f32_16x16x32_bf16 v[56:59], v[136:139], v[190:193], v[56:59]
	v_mfma_f32_16x16x32_bf16 v[52:55], v[144:147], v[190:193], v[52:55]
	v_mfma_f32_16x16x32_bf16 v[48:51], v[152:155], v[190:193], v[48:51]
	v_mfma_f32_16x16x32_bf16 v[32:35], v[152:155], v[198:201], v[32:35]
	v_mfma_f32_16x16x32_bf16 v[36:39], v[144:147], v[198:201], v[36:39]
	v_mfma_f32_16x16x32_bf16 v[40:43], v[136:139], v[198:201], v[40:43]
	v_mfma_f32_16x16x32_bf16 v[44:47], v[128:131], v[198:201], v[44:47]
	v_mfma_f32_16x16x32_bf16 v[28:31], v[128:131], v[212:215], v[28:31]
	v_mfma_f32_16x16x32_bf16 v[24:27], v[136:139], v[212:215], v[24:27]
	v_mfma_f32_16x16x32_bf16 v[20:23], v[144:147], v[212:215], v[20:23]
	v_mfma_f32_16x16x32_bf16 v[16:19], v[152:155], v[212:215], v[16:19]
	v_mfma_f32_16x16x32_bf16 v[0:3], v[152:155], v[220:223], v[0:3]
	v_mfma_f32_16x16x32_bf16 v[4:7], v[144:147], v[220:223], v[4:7]
	v_mfma_f32_16x16x32_bf16 v[8:11], v[136:139], v[220:223], v[8:11]
	v_mfma_f32_16x16x32_bf16 v[12:15], v[128:131], v[220:223], v[12:15]
	s_setprio 0
	s_setprio 1
	v_mfma_f32_16x16x32_bf16 v[60:63], v[132:135], v[194:197], v[60:63]
	v_mfma_f32_16x16x32_bf16 v[56:59], v[140:143], v[194:197], v[56:59]
	v_mfma_f32_16x16x32_bf16 v[52:55], v[148:151], v[194:197], v[52:55]
	v_mfma_f32_16x16x32_bf16 v[48:51], v[156:159], v[194:197], v[48:51]
	v_mfma_f32_16x16x32_bf16 v[32:35], v[156:159], v[208:211], v[32:35]
	v_mfma_f32_16x16x32_bf16 v[36:39], v[148:151], v[208:211], v[36:39]
	v_mfma_f32_16x16x32_bf16 v[40:43], v[140:143], v[208:211], v[40:43]
	v_mfma_f32_16x16x32_bf16 v[44:47], v[132:135], v[208:211], v[44:47]
	v_mfma_f32_16x16x32_bf16 v[28:31], v[132:135], v[216:219], v[28:31]
	v_mfma_f32_16x16x32_bf16 v[24:27], v[140:143], v[216:219], v[24:27]
	v_mfma_f32_16x16x32_bf16 v[20:23], v[148:151], v[216:219], v[20:23]
	v_mfma_f32_16x16x32_bf16 v[16:19], v[156:159], v[216:219], v[16:19]
	v_mfma_f32_16x16x32_bf16 v[0:3], v[156:159], v[224:227], v[0:3]
	v_mfma_f32_16x16x32_bf16 v[4:7], v[148:151], v[224:227], v[4:7]
	v_mfma_f32_16x16x32_bf16 v[8:11], v[140:143], v[224:227], v[8:11]
	v_mfma_f32_16x16x32_bf16 v[12:15], v[132:135], v[224:227], v[12:15]
	s_setprio 0
	s_barrier
	s_add_u32 s12, s12, 0x100
	s_addc_u32 s13, s13, 0
	s_add_u32 s71, s71, 0x100
	s_addc_u32 s72, s72, 0
	s_cmp_ge_i32 s73, s59
	s_mov_b32 s46, s73
	s_cbranch_scc0 .LBB0_1046

; #define PG8_STAGE(bufoff, gbase, voff) do { _Pragma("unroll") for (int _i = 0; _i < 2; ++_i) \
;         __builtin_amdgcn_global_load_lds((const unsigned*)((const char*)(gbase) + (voff)[_i]), (LAS unsigned*)(lds + (bufoff) + ldsw + _i * 8192), 16, 0, 0); } while (0)
; #define PG8_LDA(dst, b, h) do { _Pragma("unroll") for (int m = 0; m < 4; ++m) _Pragma("unroll") for (int k = 0; k < 2; ++k) dst[m][k] = *(const LAS bf16x8*)(lds + PG8_SA(b, h) + aoff + m * 2048 + k * 1024); } while (0)
; #define PG8_LDB(dst, b, h) do { _Pragma("unroll") for (int n = 0; n < 2; ++n) _Pragma("unroll") for (int k = 0; k < 2; ++k) dst[n][k] = *(const LAS bf16x8*)(lds + PG8_SB(b, h) + boff + n * 2048 + k * 1024); } while (0)
; #define PG8_MMA(ai, bj, At, Bt) do { __builtin_amdgcn_s_setprio(1); _Pragma("unroll") for (int m = 0; m < 4; ++m) _Pragma("unroll") for (int n = 0; n < 2; ++n) _Pragma("unroll") for (int k = 0; k < 2; ++k) \
;         acc[ai][bj][m][n] = __builtin_amdgcn_mfma_f32_16x16x32_bf16(Bt[n][k], At[m][k], acc[ai][bj][m][n], 0, 0, 0); __builtin_amdgcn_s_setprio(0); } while (0)
; #define PG8_WAIT_V(n) asm volatile("s_waitcnt vmcnt(" #n ")" ::: "memory")
; #define PG8_WAIT_L(n) asm volatile("s_waitcnt lgkmcnt(" #n ")" ::: "memory")
; #define PG8_BAR __builtin_amdgcn_s_barrier()
; #define PG8_SCHED __builtin_amdgcn_sched_barrier(0)
; template <class Epi>
; __device__ __forceinline__ void gemm_phase(LAS unsigned char* lds, const Gemm g, const StaticOrder& S, const Epi& E) {
;     ...
;         for (int t = 0; t < nt; t += 2) {
;             const bool last = (t == nt - 2);
;             const char* a1 = cA + (size_t)(t + 1) * kstep;
;             const char* a2 = last ? nA : cA + (size_t)(t + 2) * kstep; const char* b2 = last ? nB : cB + (size_t)(t + 2) * kstep;
;             const char* a3 = a2 + kstep; const char* b3 = b2 + kstep;
;             PG8_LDB(B0, 0, 0); PG8_LDB(B1, 0, 1); PG8_SCHED; PG8_LDA(At, 0, 0); PG8_STAGE(PG8_SA(1, 1), a1 + hstepA, voffA);
;             PG8_WAIT_V(8); PG8_WAIT_L(0); PG8_BAR; PG8_MMA(0, 0, At, B0); PG8_MMA(0, 1, At, B1); PG8_BAR; PG8_SCHED;
;             PG8_LDA(At, 0, 1); PG8_STAGE(PG8_SB(0, 0), b2, voffB); PG8_STAGE(PG8_SB(0, 1), b2 + hstepB, voffB); PG8_STAGE(PG8_SA(0, 0), a2, voffA);
;             PG8_WAIT_V(8); PG8_WAIT_L(0); PG8_BAR; PG8_MMA(1, 0, At, B0); PG8_MMA(1, 1, At, B1); PG8_BAR; PG8_SCHED;
.LBB0_1131:
	ds_read_b128 v[164:167], v182
	ds_read_b128 v[168:171], v182 offset:1024
	ds_read_b128 v[172:175], v182 offset:2048
	ds_read_b128 v[176:179], v182 offset:3072
	ds_read_b128 v[186:189], v183
	ds_read_b128 v[190:193], v183 offset:1024
	ds_read_b128 v[194:197], v183 offset:2048
	ds_read_b128 v[198:201], v183 offset:3072
	s_add_i32 s22, s12, 2
	s_add_u32 s13, s10, 0xfff80080
	s_addc_u32 s14, s11, -1
	s_cmp_eq_u32 s58, s12
	s_cselect_b32 s12, s19, s20
	s_cselect_b32 s15, s16, s14
	s_cselect_b32 s14, s17, s13
	s_cselect_b32 s13, s18, s21
	v_lshl_add_u64 v[202:203], s[10:11], 0, v[140:141]
	s_add_i32 m0, s33, 0xc000
	ds_read_b128 v[208:211], v184
	ds_read_b128 v[212:215], v184 offset:1024
	ds_read_b128 v[216:219], v184 offset:2048
	ds_read_b128 v[220:223], v184 offset:3072
	ds_read_b128 v[224:227], v184 offset:4096
	ds_read_b128 v[230:233], v184 offset:5120
	ds_read_b128 v[234:237], v184 offset:6144
	ds_read_b128 v[238:241], v184 offset:7168
	global_load_lds_dwordx4 v[202:203], off
	v_lshl_add_u64 v[202:203], s[10:11], 0, v[142:143]
	s_add_i32 m0, s33, 0xe000
	s_nop 0
	global_load_lds_dwordx4 v[202:203], off
	s_waitcnt vmcnt(8)
	s_waitcnt lgkmcnt(0)
	s_barrier
	s_setprio 1
	s_waitcnt lgkmcnt(0)
	v_mfma_f32_16x16x32_bf16 v[120:123], v[164:167], v[208:211], v[120:123]
	v_mfma_f32_16x16x32_bf16 v[116:119], v[172:175], v[208:211], v[116:119]
	v_mfma_f32_16x16x32_bf16 v[124:127], v[186:189], v[208:211], v[124:127]
	v_mfma_f32_16x16x32_bf16 v[112:115], v[194:197], v[208:211], v[112:115]
	v_mfma_f32_16x16x32_bf16 v[96:99], v[194:197], v[216:219], v[96:99]
	v_mfma_f32_16x16x32_bf16 v[104:107], v[186:189], v[216:219], v[104:107]
	v_mfma_f32_16x16x32_bf16 v[100:103], v[172:175], v[216:219], v[100:103]
	v_mfma_f32_16x16x32_bf16 v[108:111], v[164:167], v[216:219], v[108:111]
	v_mfma_f32_16x16x32_bf16 v[92:95], v[164:167], v[224:227], v[92:95]
	v_mfma_f32_16x16x32_bf16 v[84:87], v[172:175], v[224:227], v[84:87]
	v_mfma_f32_16x16x32_bf16 v[88:91], v[186:189], v[224:227], v[88:91]
	v_mfma_f32_16x16x32_bf16 v[80:83], v[194:197], v[224:227], v[80:83]
	v_mfma_f32_16x16x32_bf16 v[64:67], v[194:197], v[234:237], v[64:67]
	v_mfma_f32_16x16x32_bf16 v[72:75], v[186:189], v[234:237], v[72:75]
	v_mfma_f32_16x16x32_bf16 v[68:71], v[172:175], v[234:237], v[68:71]
	v_mfma_f32_16x16x32_bf16 v[76:79], v[164:167], v[234:237], v[76:79]
	s_setprio 0
	s_setprio 1
	v_mfma_f32_16x16x32_bf16 v[120:123], v[168:171], v[212:215], v[120:123]
	v_mfma_f32_16x16x32_bf16 v[116:119], v[176:179], v[212:215], v[116:119]
	v_mfma_f32_16x16x32_bf16 v[124:127], v[190:193], v[212:215], v[124:127]
	v_mfma_f32_16x16x32_bf16 v[112:115], v[198:201], v[212:215], v[112:115]
	v_mfma_f32_16x16x32_bf16 v[96:99], v[198:201], v[220:223], v[96:99]
	v_mfma_f32_16x16x32_bf16 v[104:107], v[190:193], v[220:223], v[104:107]
	v_mfma_f32_16x16x32_bf16 v[100:103], v[176:179], v[220:223], v[100:103]
	v_mfma_f32_16x16x32_bf16 v[108:111], v[168:171], v[220:223], v[108:111]
	v_mfma_f32_16x16x32_bf16 v[92:95], v[168:171], v[230:233], v[92:95]
	v_mfma_f32_16x16x32_bf16 v[84:87], v[176:179], v[230:233], v[84:87]
	v_mfma_f32_16x16x32_bf16 v[88:91], v[190:193], v[230:233], v[88:91]
	v_mfma_f32_16x16x32_bf16 v[80:83], v[198:201], v[230:233], v[80:83]
	v_mfma_f32_16x16x32_bf16 v[64:67], v[198:201], v[238:241], v[64:67]
	v_mfma_f32_16x16x32_bf16 v[72:75], v[190:193], v[238:241], v[72:75]
	v_mfma_f32_16x16x32_bf16 v[68:71], v[176:179], v[238:241], v[68:71]
	v_mfma_f32_16x16x32_bf16 v[76:79], v[168:171], v[238:241], v[76:79]
	s_setprio 0
	s_barrier
	s_add_i32 s23, s62, s37
	v_lshl_add_u64 v[202:203], s[12:13], 0, v[132:133]
	s_mov_b32 m0, s23
	ds_read_b128 v[208:211], v184 offset:16384
	ds_read_b128 v[212:215], v184 offset:17408
	ds_read_b128 v[216:219], v184 offset:18432
	ds_read_b128 v[220:223], v184 offset:19456
	ds_read_b128 v[224:227], v184 offset:20480
	ds_read_b128 v[230:233], v184 offset:21504
	ds_read_b128 v[234:237], v184 offset:22528
	ds_read_b128 v[238:241], v184 offset:23552
	global_load_lds_dwordx4 v[202:203], off
	s_add_i32 m0, s23, 0x2000
	s_add_u32 s50, s12, 0x80000
	v_lshl_add_u64 v[242:243], s[12:13], 0, v[128:129]
	s_addc_u32 s51, s13, 0
	s_add_i32 s23, s63, s37
	global_load_lds_dwordx4 v[242:243], off
	v_lshl_add_u64 v[244:245], s[50:51], 0, v[132:133]
	s_mov_b32 m0, s23
	v_lshl_add_u64 v[246:247], s[14:15], 0, v[130:131]
	global_load_lds_dwordx4 v[244:245], off
	v_lshl_add_u64 v[244:245], s[50:51], 0, v[128:129]
	s_add_i32 m0, s23, 0x2000
	s_nop 0
	global_load_lds_dwordx4 v[244:245], off
	v_lshl_add_u64 v[244:245], s[14:15], 0, v[134:135]
	s_mov_b32 m0, s33
	s_nop 0
	global_load_lds_dwordx4 v[244:245], off
	s_mov_b32 m0, s52
	s_nop 0
	global_load_lds_dwordx4 v[246:247], off
	s_waitcnt vmcnt(8)
	s_waitcnt lgkmcnt(0)
	s_barrier
; #define PG8_STAGE(bufoff, gbase, voff) do { _Pragma("unroll") for (int _i = 0; _i < 2; ++_i) \
;         __builtin_amdgcn_global_load_lds((const unsigned*)((const char*)(gbase) + (voff)[_i]), (LAS unsigned*)(lds + (bufoff) + ldsw + _i * 8192), 16, 0, 0); } while (0)
; #define PG8_LDA(dst, b, h) do { _Pragma("unroll") for (int m = 0; m < 4; ++m) _Pragma("unroll") for (int k = 0; k < 2; ++k) dst[m][k] = *(const LAS bf16x8*)(lds + PG8_SA(b, h) + aoff + m * 2048 + k * 1024); } while (0)
; #define PG8_LDB(dst, b, h) do { _Pragma("unroll") for (int n = 0; n < 2; ++n) _Pragma("unroll") for (int k = 0; k < 2; ++k) dst[n][k] = *(const LAS bf16x8*)(lds + PG8_SB(b, h) + boff + n * 2048 + k * 1024); } while (0)
; #define PG8_MMA(ai, bj, At, Bt) do { __builtin_amdgcn_s_setprio(1); _Pragma("unroll") for (int m = 0; m < 4; ++m) _Pragma("unroll") for (int n = 0; n < 2; ++n) _Pragma("unroll") for (int k = 0; k < 2; ++k) \
;         acc[ai][bj][m][n] = __builtin_amdgcn_mfma_f32_16x16x32_bf16(Bt[n][k], At[m][k], acc[ai][bj][m][n], 0, 0, 0); __builtin_amdgcn_s_setprio(0); } while (0)
; #define PG8_WAIT_V(n) asm volatile("s_waitcnt vmcnt(" #n ")" ::: "memory")
; #define PG8_WAIT_L(n) asm volatile("s_waitcnt lgkmcnt(" #n ")" ::: "memory")
; #define PG8_BAR __builtin_amdgcn_s_barrier()
; #define PG8_SCHED __builtin_amdgcn_sched_barrier(0)
; template <class Epi>
; __device__ __forceinline__ void gemm_phase(LAS unsigned char* lds, const Gemm g, const StaticOrder& S, const Epi& E) {
;     ...
;             PG8_WAIT_V(8); PG8_WAIT_L(0); PG8_BAR; PG8_MMA(1, 0, At, B0); PG8_MMA(1, 1, At, B1); PG8_BAR; PG8_SCHED;
;             PG8_LDB(B0, 1, 0); PG8_LDB(B1, 1, 1); PG8_SCHED; PG8_LDA(At, 1, 0); PG8_STAGE(PG8_SA(0, 1), a2 + hstepA, voffA);
;             PG8_WAIT_V(8); PG8_WAIT_L(0); PG8_BAR; PG8_MMA(0, 0, At, B0); PG8_MMA(0, 1, At, B1); PG8_BAR; PG8_SCHED;
	s_setprio 1
	s_waitcnt lgkmcnt(0)
	v_mfma_f32_16x16x32_bf16 v[60:63], v[164:167], v[208:211], v[60:63]
	v_mfma_f32_16x16x32_bf16 v[52:55], v[172:175], v[208:211], v[52:55]
	v_mfma_f32_16x16x32_bf16 v[56:59], v[186:189], v[208:211], v[56:59]
	v_mfma_f32_16x16x32_bf16 v[48:51], v[194:197], v[208:211], v[48:51]
	v_mfma_f32_16x16x32_bf16 v[32:35], v[194:197], v[216:219], v[32:35]
	v_mfma_f32_16x16x32_bf16 v[40:43], v[186:189], v[216:219], v[40:43]
	v_mfma_f32_16x16x32_bf16 v[36:39], v[172:175], v[216:219], v[36:39]
	v_mfma_f32_16x16x32_bf16 v[44:47], v[164:167], v[216:219], v[44:47]
	v_mfma_f32_16x16x32_bf16 v[28:31], v[164:167], v[224:227], v[28:31]
	v_mfma_f32_16x16x32_bf16 v[20:23], v[172:175], v[224:227], v[20:23]
	v_mfma_f32_16x16x32_bf16 v[24:27], v[186:189], v[224:227], v[24:27]
	v_mfma_f32_16x16x32_bf16 v[16:19], v[194:197], v[224:227], v[16:19]
	v_mfma_f32_16x16x32_bf16 v[0:3], v[194:197], v[234:237], v[0:3]
	v_mfma_f32_16x16x32_bf16 v[8:11], v[186:189], v[234:237], v[8:11]
	v_mfma_f32_16x16x32_bf16 v[4:7], v[172:175], v[234:237], v[4:7]
	v_mfma_f32_16x16x32_bf16 v[12:15], v[164:167], v[234:237], v[12:15]
	s_setprio 0
	s_setprio 1
	v_mfma_f32_16x16x32_bf16 v[60:63], v[168:171], v[212:215], v[60:63]
	v_mfma_f32_16x16x32_bf16 v[52:55], v[176:179], v[212:215], v[52:55]
	v_mfma_f32_16x16x32_bf16 v[56:59], v[190:193], v[212:215], v[56:59]
	v_mfma_f32_16x16x32_bf16 v[48:51], v[198:201], v[212:215], v[48:51]
	v_mfma_f32_16x16x32_bf16 v[32:35], v[198:201], v[220:223], v[32:35]
	v_mfma_f32_16x16x32_bf16 v[40:43], v[190:193], v[220:223], v[40:43]
	v_mfma_f32_16x16x32_bf16 v[36:39], v[176:179], v[220:223], v[36:39]
	v_mfma_f32_16x16x32_bf16 v[44:47], v[168:171], v[220:223], v[44:47]
	v_mfma_f32_16x16x32_bf16 v[28:31], v[168:171], v[230:233], v[28:31]
	v_mfma_f32_16x16x32_bf16 v[20:23], v[176:179], v[230:233], v[20:23]
	v_mfma_f32_16x16x32_bf16 v[24:27], v[190:193], v[230:233], v[24:27]
	v_mfma_f32_16x16x32_bf16 v[16:19], v[198:201], v[230:233], v[16:19]
	v_mfma_f32_16x16x32_bf16 v[0:3], v[198:201], v[238:241], v[0:3]
	v_mfma_f32_16x16x32_bf16 v[8:11], v[190:193], v[238:241], v[8:11]
	v_mfma_f32_16x16x32_bf16 v[4:7], v[176:179], v[238:241], v[4:7]
	v_mfma_f32_16x16x32_bf16 v[12:15], v[168:171], v[238:241], v[12:15]
	s_setprio 0
	s_barrier
	s_add_i32 s23, 0, 0x18000
	s_add_i32 s25, 0, 0x1c000
	v_add_u32_e32 v176, s23, v180
	v_add_u32_e32 v185, s25, v180
	ds_read_b128 v[164:167], v176
	ds_read_b128 v[168:171], v176 offset:1024
	ds_read_b128 v[172:175], v176 offset:2048
	ds_read_b128 v[176:179], v176 offset:3072
	ds_read_b128 v[186:189], v185
	ds_read_b128 v[190:193], v185 offset:1024
	ds_read_b128 v[194:197], v185 offset:2048
	ds_read_b128 v[198:201], v185 offset:3072
	s_add_u32 s14, s14, 0x80000
	s_addc_u32 s15, s15, 0
	s_mov_b32 m0, s53
	v_lshl_add_u64 v[248:249], s[14:15], 0, v[134:135]
	ds_read_b128 v[208:211], v184 offset:32768
	ds_read_b128 v[212:215], v184 offset:33792
	ds_read_b128 v[216:219], v184 offset:34816
	ds_read_b128 v[220:223], v184 offset:35840
	ds_read_b128 v[224:227], v184 offset:36864
	ds_read_b128 v[230:233], v184 offset:37888
	ds_read_b128 v[234:237], v184 offset:38912
	ds_read_b128 v[238:241], v184 offset:39936
	global_load_lds_dwordx4 v[248:249], off
	v_lshl_add_u64 v[248:249], s[14:15], 0, v[130:131]
	s_mov_b32 m0, s54
	s_nop 0
	global_load_lds_dwordx4 v[248:249], off
	s_waitcnt vmcnt(8)
	s_waitcnt lgkmcnt(0)
	s_barrier
	s_setprio 1
	s_waitcnt lgkmcnt(0)
	v_mfma_f32_16x16x32_bf16 v[120:123], v[164:167], v[208:211], v[120:123]
	v_mfma_f32_16x16x32_bf16 v[116:119], v[172:175], v[208:211], v[116:119]
	v_mfma_f32_16x16x32_bf16 v[124:127], v[186:189], v[208:211], v[124:127]
	v_mfma_f32_16x16x32_bf16 v[112:115], v[194:197], v[208:211], v[112:115]
	v_mfma_f32_16x16x32_bf16 v[96:99], v[194:197], v[216:219], v[96:99]
	v_mfma_f32_16x16x32_bf16 v[104:107], v[186:189], v[216:219], v[104:107]
	v_mfma_f32_16x16x32_bf16 v[100:103], v[172:175], v[216:219], v[100:103]
	v_mfma_f32_16x16x32_bf16 v[108:111], v[164:167], v[216:219], v[108:111]
	v_mfma_f32_16x16x32_bf16 v[92:95], v[164:167], v[224:227], v[92:95]
	v_mfma_f32_16x16x32_bf16 v[84:87], v[172:175], v[224:227], v[84:87]
	v_mfma_f32_16x16x32_bf16 v[88:91], v[186:189], v[224:227], v[88:91]
	v_mfma_f32_16x16x32_bf16 v[80:83], v[194:197], v[224:227], v[80:83]
	v_mfma_f32_16x16x32_bf16 v[64:67], v[194:197], v[234:237], v[64:67]
	v_mfma_f32_16x16x32_bf16 v[72:75], v[186:189], v[234:237], v[72:75]
	v_mfma_f32_16x16x32_bf16 v[68:71], v[172:175], v[234:237], v[68:71]
	v_mfma_f32_16x16x32_bf16 v[76:79], v[164:167], v[234:237], v[76:79]
	s_setprio 0
	s_setprio 1
	v_mfma_f32_16x16x32_bf16 v[120:123], v[168:171], v[212:215], v[120:123]
	v_mfma_f32_16x16x32_bf16 v[116:119], v[176:179], v[212:215], v[116:119]
	v_mfma_f32_16x16x32_bf16 v[124:127], v[190:193], v[212:215], v[124:127]
	v_mfma_f32_16x16x32_bf16 v[112:115], v[198:201], v[212:215], v[112:115]
	v_mfma_f32_16x16x32_bf16 v[96:99], v[198:201], v[220:223], v[96:99]
	v_mfma_f32_16x16x32_bf16 v[104:107], v[190:193], v[220:223], v[104:107]
	v_mfma_f32_16x16x32_bf16 v[100:103], v[176:179], v[220:223], v[100:103]
	v_mfma_f32_16x16x32_bf16 v[108:111], v[168:171], v[220:223], v[108:111]
	v_mfma_f32_16x16x32_bf16 v[92:95], v[168:171], v[230:233], v[92:95]
	v_mfma_f32_16x16x32_bf16 v[84:87], v[176:179], v[230:233], v[84:87]
	v_mfma_f32_16x16x32_bf16 v[88:91], v[190:193], v[230:233], v[88:91]
	v_mfma_f32_16x16x32_bf16 v[80:83], v[198:201], v[230:233], v[80:83]
	v_mfma_f32_16x16x32_bf16 v[64:67], v[198:201], v[238:241], v[64:67]
	v_mfma_f32_16x16x32_bf16 v[72:75], v[190:193], v[238:241], v[72:75]
	v_mfma_f32_16x16x32_bf16 v[68:71], v[176:179], v[238:241], v[68:71]
	v_mfma_f32_16x16x32_bf16 v[76:79], v[168:171], v[238:241], v[76:79]
	s_setprio 0
	s_barrier
; #define PG8_STAGE(bufoff, gbase, voff) do { _Pragma("unroll") for (int _i = 0; _i < 2; ++_i) \
;         __builtin_amdgcn_global_load_lds((const unsigned*)((const char*)(gbase) + (voff)[_i]), (LAS unsigned*)(lds + (bufoff) + ldsw + _i * 8192), 16, 0, 0); } while (0)
; #define PG8_LDA(dst, b, h) do { _Pragma("unroll") for (int m = 0; m < 4; ++m) _Pragma("unroll") for (int k = 0; k < 2; ++k) dst[m][k] = *(const LAS bf16x8*)(lds + PG8_SA(b, h) + aoff + m * 2048 + k * 1024); } while (0)
; #define PG8_MMA(ai, bj, At, Bt) do { __builtin_amdgcn_s_setprio(1); _Pragma("unroll") for (int m = 0; m < 4; ++m) _Pragma("unroll") for (int n = 0; n < 2; ++n) _Pragma("unroll") for (int k = 0; k < 2; ++k) \
;         acc[ai][bj][m][n] = __builtin_amdgcn_mfma_f32_16x16x32_bf16(Bt[n][k], At[m][k], acc[ai][bj][m][n], 0, 0, 0); __builtin_amdgcn_s_setprio(0); } while (0)
; #define PG8_WAIT_V(n) asm volatile("s_waitcnt vmcnt(" #n ")" ::: "memory")
; #define PG8_WAIT_L(n) asm volatile("s_waitcnt lgkmcnt(" #n ")" ::: "memory")
; #define PG8_BAR __builtin_amdgcn_s_barrier()
; #define PG8_SCHED __builtin_amdgcn_sched_barrier(0)
; template <class Epi>
; __device__ __forceinline__ void gemm_phase(LAS unsigned char* lds, const Gemm g, const StaticOrder& S, const Epi& E) {
;     ...
;         for (int t = 0; t < nt; t += 2) {
;     ...
;             PG8_LDA(At, 1, 1); PG8_STAGE(PG8_SB(1, 0), b3, voffB); PG8_STAGE(PG8_SB(1, 1), b3 + hstepB, voffB); PG8_STAGE(PG8_SA(1, 0), a3, voffA);
;             PG8_WAIT_V(8); PG8_WAIT_L(0); PG8_BAR; PG8_MMA(1, 0, At, B0); PG8_MMA(1, 1, At, B1); PG8_BAR; PG8_SCHED;
	s_add_i32 s14, s23, s37
	v_lshl_add_u64 v[202:203], v[202:203], 0, s[4:5]
	s_mov_b32 m0, s14
	ds_read_b128 v[208:211], v184 offset:49152
	ds_read_b128 v[212:215], v184 offset:50176
	ds_read_b128 v[216:219], v184 offset:51200
	ds_read_b128 v[220:223], v184 offset:52224
	ds_read_b128 v[224:227], v184 offset:53248
	ds_read_b128 v[230:233], v184 offset:54272
	ds_read_b128 v[234:237], v184 offset:55296
	ds_read_b128 v[238:241], v184 offset:56320
	global_load_lds_dwordx4 v[202:203], off
	s_add_i32 m0, s14, 0x2000
	s_add_u32 s12, s12, 0x80080
	v_lshl_add_u64 v[202:203], v[242:243], 0, s[4:5]
	s_addc_u32 s13, s13, 0
	s_add_i32 s14, s25, s37
	global_load_lds_dwordx4 v[202:203], off
	v_lshl_add_u64 v[202:203], s[12:13], 0, v[132:133]
	s_mov_b32 m0, s14
	s_nop 0
	global_load_lds_dwordx4 v[202:203], off
	v_lshl_add_u64 v[202:203], s[12:13], 0, v[128:129]
	s_add_i32 m0, s14, 0x2000
	s_nop 0
	global_load_lds_dwordx4 v[202:203], off
	v_lshl_add_u64 v[202:203], v[244:245], 0, s[4:5]
	s_mov_b32 m0, s56
	s_nop 0
	global_load_lds_dwordx4 v[202:203], off
	v_lshl_add_u64 v[202:203], v[246:247], 0, s[4:5]
	s_mov_b32 m0, s57
	s_nop 0
	global_load_lds_dwordx4 v[202:203], off
	s_waitcnt vmcnt(8)
	s_waitcnt lgkmcnt(0)
	s_barrier
	s_setprio 1
	s_waitcnt lgkmcnt(0)
	v_mfma_f32_16x16x32_bf16 v[60:63], v[164:167], v[208:211], v[60:63]
	v_mfma_f32_16x16x32_bf16 v[52:55], v[172:175], v[208:211], v[52:55]
	v_mfma_f32_16x16x32_bf16 v[56:59], v[186:189], v[208:211], v[56:59]
	v_mfma_f32_16x16x32_bf16 v[48:51], v[194:197], v[208:211], v[48:51]
	v_mfma_f32_16x16x32_bf16 v[32:35], v[194:197], v[216:219], v[32:35]
	v_mfma_f32_16x16x32_bf16 v[40:43], v[186:189], v[216:219], v[40:43]
	v_mfma_f32_16x16x32_bf16 v[36:39], v[172:175], v[216:219], v[36:39]
	v_mfma_f32_16x16x32_bf16 v[44:47], v[164:167], v[216:219], v[44:47]
	v_mfma_f32_16x16x32_bf16 v[28:31], v[164:167], v[224:227], v[28:31]
	v_mfma_f32_16x16x32_bf16 v[20:23], v[172:175], v[224:227], v[20:23]
	v_mfma_f32_16x16x32_bf16 v[24:27], v[186:189], v[224:227], v[24:27]
	v_mfma_f32_16x16x32_bf16 v[16:19], v[194:197], v[224:227], v[16:19]
	v_mfma_f32_16x16x32_bf16 v[0:3], v[194:197], v[234:237], v[0:3]
	v_mfma_f32_16x16x32_bf16 v[8:11], v[186:189], v[234:237], v[8:11]
	v_mfma_f32_16x16x32_bf16 v[4:7], v[172:175], v[234:237], v[4:7]
	v_mfma_f32_16x16x32_bf16 v[12:15], v[164:167], v[234:237], v[12:15]
	s_setprio 0
	s_setprio 1
	v_mfma_f32_16x16x32_bf16 v[60:63], v[168:171], v[212:215], v[60:63]
	v_mfma_f32_16x16x32_bf16 v[52:55], v[176:179], v[212:215], v[52:55]
	v_mfma_f32_16x16x32_bf16 v[56:59], v[190:193], v[212:215], v[56:59]
	v_mfma_f32_16x16x32_bf16 v[48:51], v[198:201], v[212:215], v[48:51]
	v_mfma_f32_16x16x32_bf16 v[32:35], v[198:201], v[220:223], v[32:35]
	v_mfma_f32_16x16x32_bf16 v[40:43], v[190:193], v[220:223], v[40:43]
	v_mfma_f32_16x16x32_bf16 v[36:39], v[176:179], v[220:223], v[36:39]
	v_mfma_f32_16x16x32_bf16 v[44:47], v[168:171], v[220:223], v[44:47]
	v_mfma_f32_16x16x32_bf16 v[28:31], v[168:171], v[230:233], v[28:31]
	v_mfma_f32_16x16x32_bf16 v[20:23], v[176:179], v[230:233], v[20:23]
	v_mfma_f32_16x16x32_bf16 v[24:27], v[190:193], v[230:233], v[24:27]
	v_mfma_f32_16x16x32_bf16 v[16:19], v[198:201], v[230:233], v[16:19]
	v_mfma_f32_16x16x32_bf16 v[0:3], v[198:201], v[238:241], v[0:3]
	v_mfma_f32_16x16x32_bf16 v[8:11], v[190:193], v[238:241], v[8:11]
	v_mfma_f32_16x16x32_bf16 v[4:7], v[176:179], v[238:241], v[4:7]
	v_mfma_f32_16x16x32_bf16 v[12:15], v[168:171], v[238:241], v[12:15]
	s_setprio 0
	s_barrier
	s_add_u32 s10, s10, 0x100
	s_addc_u32 s11, s11, 0
	s_add_u32 s20, s20, 0x100
	s_addc_u32 s21, s21, 0
	s_cmp_ge_i32 s22, s55
	s_mov_b32 s12, s22
	s_cbranch_scc0 .LBB0_1131

; #define PG8_STAGE(bufoff, gbase, voff) do { _Pragma("unroll") for (int _i = 0; _i < 2; ++_i) \
;         __builtin_amdgcn_global_load_lds((const unsigned*)((const char*)(gbase) + (voff)[_i]), (LAS unsigned*)(lds + (bufoff) + ldsw + _i * 8192), 16, 0, 0); } while (0)
; #define PG8_LDA(dst, b, h) do { _Pragma("unroll") for (int m = 0; m < 4; ++m) _Pragma("unroll") for (int k = 0; k < 2; ++k) dst[m][k] = *(const LAS bf16x8*)(lds + PG8_SA(b, h) + aoff + m * 2048 + k * 1024); } while (0)
; #define PG8_LDB(dst, b, h) do { _Pragma("unroll") for (int n = 0; n < 2; ++n) _Pragma("unroll") for (int k = 0; k < 2; ++k) dst[n][k] = *(const LAS bf16x8*)(lds + PG8_SB(b, h) + boff + n * 2048 + k * 1024); } while (0)
; #define PG8_MMA(ai, bj, At, Bt) do { __builtin_amdgcn_s_setprio(1); _Pragma("unroll") for (int m = 0; m < 4; ++m) _Pragma("unroll") for (int n = 0; n < 2; ++n) _Pragma("unroll") for (int k = 0; k < 2; ++k) \
;         acc[ai][bj][m][n] = __builtin_amdgcn_mfma_f32_16x16x32_bf16(Bt[n][k], At[m][k], acc[ai][bj][m][n], 0, 0, 0); __builtin_amdgcn_s_setprio(0); } while (0)
; #define PG8_WAIT_V(n) asm volatile("s_waitcnt vmcnt(" #n ")" ::: "memory")
; #define PG8_WAIT_L(n) asm volatile("s_waitcnt lgkmcnt(" #n ")" ::: "memory")
; #define PG8_BAR __builtin_amdgcn_s_barrier()
; #define PG8_SCHED __builtin_amdgcn_sched_barrier(0)
; template <class Epi>
; __device__ __forceinline__ void gemm_phase(LAS unsigned char* lds, const Gemm g, const StaticOrder& S, const Epi& E) {
;     ...
;         for (int t = 0; t < nt; t += 2) {
;             const bool last = (t == nt - 2);
;             const char* a1 = cA + (size_t)(t + 1) * kstep;
;             const char* a2 = last ? nA : cA + (size_t)(t + 2) * kstep; const char* b2 = last ? nB : cB + (size_t)(t + 2) * kstep;
;             const char* a3 = a2 + kstep; const char* b3 = b2 + kstep;
;             PG8_LDB(B0, 0, 0); PG8_LDB(B1, 0, 1); PG8_SCHED; PG8_LDA(At, 0, 0); PG8_STAGE(PG8_SA(1, 1), a1 + hstepA, voffA);
;             PG8_WAIT_V(8); PG8_WAIT_L(0); PG8_BAR; PG8_MMA(0, 0, At, B0); PG8_MMA(0, 1, At, B1); PG8_BAR; PG8_SCHED;
;             PG8_LDA(At, 0, 1); PG8_STAGE(PG8_SB(0, 0), b2, voffB); PG8_STAGE(PG8_SB(0, 1), b2 + hstepB, voffB); PG8_STAGE(PG8_SA(0, 0), a2, voffA);
;             PG8_WAIT_V(8); PG8_WAIT_L(0); PG8_BAR; PG8_MMA(1, 0, At, B0); PG8_MMA(1, 1, At, B1); PG8_BAR; PG8_SCHED;
.LBB0_1161:
	ds_read_b128 v[152:155], v149
	ds_read_b128 v[156:159], v149 offset:1024
	ds_read_b128 v[160:163], v149 offset:2048
	ds_read_b128 v[164:167], v149 offset:3072
	ds_read_b128 v[168:171], v150
	ds_read_b128 v[172:175], v150 offset:1024
	ds_read_b128 v[176:179], v150 offset:2048
	ds_read_b128 v[180:183], v150 offset:3072
	s_add_i32 s83, s46, 2
	s_add_u32 s47, s44, 0xffff0080
	s_addc_u32 s48, s45, -1
	s_cmp_eq_u32 s65, s46
	s_cselect_b32 s46, s78, s79
	s_cselect_b32 s49, s35, s48
	s_cselect_b32 s48, s37, s47
	s_cselect_b32 s47, s39, s82
	v_lshl_add_u64 v[220:221], s[44:45], 0, v[140:141]
	s_add_i32 m0, s56, 0xc000
	ds_read_b128 v[184:187], v151
	ds_read_b128 v[188:191], v151 offset:1024
	ds_read_b128 v[192:195], v151 offset:2048
	ds_read_b128 v[196:199], v151 offset:3072
	ds_read_b128 v[200:203], v151 offset:4096
	ds_read_b128 v[208:211], v151 offset:5120
	ds_read_b128 v[212:215], v151 offset:6144
	ds_read_b128 v[216:219], v151 offset:7168
	global_load_lds_dwordx4 v[220:221], off
	v_lshl_add_u64 v[220:221], s[44:45], 0, v[142:143]
	s_add_i32 m0, s56, 0xe000
	s_nop 0
	global_load_lds_dwordx4 v[220:221], off
	s_waitcnt vmcnt(8)
	s_waitcnt lgkmcnt(0)
	s_barrier
	s_setprio 1
	s_waitcnt lgkmcnt(0)
	v_mfma_f32_16x16x32_bf16 v[120:123], v[152:155], v[184:187], v[120:123]
	v_mfma_f32_16x16x32_bf16 v[124:127], v[160:163], v[184:187], v[124:127]
	v_mfma_f32_16x16x32_bf16 v[116:119], v[168:171], v[184:187], v[116:119]
	v_mfma_f32_16x16x32_bf16 v[112:115], v[176:179], v[184:187], v[112:115]
	v_mfma_f32_16x16x32_bf16 v[96:99], v[176:179], v[192:195], v[96:99]
	v_mfma_f32_16x16x32_bf16 v[100:103], v[168:171], v[192:195], v[100:103]
	v_mfma_f32_16x16x32_bf16 v[104:107], v[160:163], v[192:195], v[104:107]
	v_mfma_f32_16x16x32_bf16 v[108:111], v[152:155], v[192:195], v[108:111]
	v_mfma_f32_16x16x32_bf16 v[92:95], v[152:155], v[200:203], v[92:95]
	v_mfma_f32_16x16x32_bf16 v[88:91], v[160:163], v[200:203], v[88:91]
	v_mfma_f32_16x16x32_bf16 v[84:87], v[168:171], v[200:203], v[84:87]
	v_mfma_f32_16x16x32_bf16 v[80:83], v[176:179], v[200:203], v[80:83]
	v_mfma_f32_16x16x32_bf16 v[64:67], v[176:179], v[212:215], v[64:67]
	v_mfma_f32_16x16x32_bf16 v[68:71], v[168:171], v[212:215], v[68:71]
	v_mfma_f32_16x16x32_bf16 v[72:75], v[160:163], v[212:215], v[72:75]
	v_mfma_f32_16x16x32_bf16 v[76:79], v[152:155], v[212:215], v[76:79]
	s_setprio 0
	s_setprio 1
	v_mfma_f32_16x16x32_bf16 v[120:123], v[156:159], v[188:191], v[120:123]
	v_mfma_f32_16x16x32_bf16 v[124:127], v[164:167], v[188:191], v[124:127]
	v_mfma_f32_16x16x32_bf16 v[116:119], v[172:175], v[188:191], v[116:119]
	v_mfma_f32_16x16x32_bf16 v[112:115], v[180:183], v[188:191], v[112:115]
	v_mfma_f32_16x16x32_bf16 v[96:99], v[180:183], v[196:199], v[96:99]
	v_mfma_f32_16x16x32_bf16 v[100:103], v[172:175], v[196:199], v[100:103]
	v_mfma_f32_16x16x32_bf16 v[104:107], v[164:167], v[196:199], v[104:107]
	v_mfma_f32_16x16x32_bf16 v[108:111], v[156:159], v[196:199], v[108:111]
	v_mfma_f32_16x16x32_bf16 v[92:95], v[156:159], v[208:211], v[92:95]
	v_mfma_f32_16x16x32_bf16 v[88:91], v[164:167], v[208:211], v[88:91]
	v_mfma_f32_16x16x32_bf16 v[84:87], v[172:175], v[208:211], v[84:87]
	v_mfma_f32_16x16x32_bf16 v[80:83], v[180:183], v[208:211], v[80:83]
	v_mfma_f32_16x16x32_bf16 v[64:67], v[180:183], v[216:219], v[64:67]
	v_mfma_f32_16x16x32_bf16 v[68:71], v[172:175], v[216:219], v[68:71]
	v_mfma_f32_16x16x32_bf16 v[72:75], v[164:167], v[216:219], v[72:75]
	v_mfma_f32_16x16x32_bf16 v[76:79], v[156:159], v[216:219], v[76:79]
	s_setprio 0
	s_barrier
	s_add_i32 s84, s67, s51
	v_lshl_add_u64 v[220:221], s[46:47], 0, v[130:131]
	s_mov_b32 m0, s84
	ds_read_b128 v[184:187], v151 offset:16384
	ds_read_b128 v[188:191], v151 offset:17408
	ds_read_b128 v[192:195], v151 offset:18432
	ds_read_b128 v[196:199], v151 offset:19456
	ds_read_b128 v[200:203], v151 offset:20480
	ds_read_b128 v[208:211], v151 offset:21504
	ds_read_b128 v[212:215], v151 offset:22528
	ds_read_b128 v[216:219], v151 offset:23552
	global_load_lds_dwordx4 v[220:221], off
	s_add_i32 m0, s84, 0x2000
	s_add_u32 s84, s46, 0x10000
	v_lshl_add_u64 v[222:223], s[46:47], 0, v[134:135]
	s_addc_u32 s85, s47, 0
	s_add_i32 s86, s68, s51
	global_load_lds_dwordx4 v[222:223], off
	v_lshl_add_u64 v[224:225], s[84:85], 0, v[130:131]
	s_mov_b32 m0, s86
	v_lshl_add_u64 v[226:227], s[48:49], 0, v[132:133]
	global_load_lds_dwordx4 v[224:225], off
	v_lshl_add_u64 v[224:225], s[84:85], 0, v[134:135]
	s_add_i32 m0, s86, 0x2000
	s_nop 0
	global_load_lds_dwordx4 v[224:225], off
	v_lshl_add_u64 v[224:225], s[48:49], 0, v[128:129]
	s_mov_b32 m0, s56
	s_nop 0
	global_load_lds_dwordx4 v[224:225], off
	s_mov_b32 m0, s57
	s_nop 0
	global_load_lds_dwordx4 v[226:227], off
	s_waitcnt vmcnt(8)
	s_waitcnt lgkmcnt(0)
	s_barrier
; #define PG8_STAGE(bufoff, gbase, voff) do { _Pragma("unroll") for (int _i = 0; _i < 2; ++_i) \
;         __builtin_amdgcn_global_load_lds((const unsigned*)((const char*)(gbase) + (voff)[_i]), (LAS unsigned*)(lds + (bufoff) + ldsw + _i * 8192), 16, 0, 0); } while (0)
; #define PG8_LDA(dst, b, h) do { _Pragma("unroll") for (int m = 0; m < 4; ++m) _Pragma("unroll") for (int k = 0; k < 2; ++k) dst[m][k] = *(const LAS bf16x8*)(lds + PG8_SA(b, h) + aoff + m * 2048 + k * 1024); } while (0)
; #define PG8_LDB(dst, b, h) do { _Pragma("unroll") for (int n = 0; n < 2; ++n) _Pragma("unroll") for (int k = 0; k < 2; ++k) dst[n][k] = *(const LAS bf16x8*)(lds + PG8_SB(b, h) + boff + n * 2048 + k * 1024); } while (0)
; #define PG8_MMA(ai, bj, At, Bt) do { __builtin_amdgcn_s_setprio(1); _Pragma("unroll") for (int m = 0; m < 4; ++m) _Pragma("unroll") for (int n = 0; n < 2; ++n) _Pragma("unroll") for (int k = 0; k < 2; ++k) \
;         acc[ai][bj][m][n] = __builtin_amdgcn_mfma_f32_16x16x32_bf16(Bt[n][k], At[m][k], acc[ai][bj][m][n], 0, 0, 0); __builtin_amdgcn_s_setprio(0); } while (0)
; #define PG8_WAIT_V(n) asm volatile("s_waitcnt vmcnt(" #n ")" ::: "memory")
; #define PG8_WAIT_L(n) asm volatile("s_waitcnt lgkmcnt(" #n ")" ::: "memory")
; #define PG8_BAR __builtin_amdgcn_s_barrier()
; #define PG8_SCHED __builtin_amdgcn_sched_barrier(0)
; template <class Epi>
; __device__ __forceinline__ void gemm_phase(LAS unsigned char* lds, const Gemm g, const StaticOrder& S, const Epi& E) {
;     ...
;             PG8_WAIT_V(8); PG8_WAIT_L(0); PG8_BAR; PG8_MMA(1, 0, At, B0); PG8_MMA(1, 1, At, B1); PG8_BAR; PG8_SCHED;
;             PG8_LDB(B0, 1, 0); PG8_LDB(B1, 1, 1); PG8_SCHED; PG8_LDA(At, 1, 0); PG8_STAGE(PG8_SA(0, 1), a2 + hstepA, voffA);
;             PG8_WAIT_V(8); PG8_WAIT_L(0); PG8_BAR; PG8_MMA(0, 0, At, B0); PG8_MMA(0, 1, At, B1); PG8_BAR; PG8_SCHED;
	s_setprio 1
	s_waitcnt lgkmcnt(0)
	v_mfma_f32_16x16x32_bf16 v[60:63], v[152:155], v[184:187], v[60:63]
	v_mfma_f32_16x16x32_bf16 v[56:59], v[160:163], v[184:187], v[56:59]
	v_mfma_f32_16x16x32_bf16 v[52:55], v[168:171], v[184:187], v[52:55]
	v_mfma_f32_16x16x32_bf16 v[48:51], v[176:179], v[184:187], v[48:51]
	v_mfma_f32_16x16x32_bf16 v[32:35], v[176:179], v[192:195], v[32:35]
	v_mfma_f32_16x16x32_bf16 v[36:39], v[168:171], v[192:195], v[36:39]
	v_mfma_f32_16x16x32_bf16 v[40:43], v[160:163], v[192:195], v[40:43]
	v_mfma_f32_16x16x32_bf16 v[44:47], v[152:155], v[192:195], v[44:47]
	v_mfma_f32_16x16x32_bf16 v[28:31], v[152:155], v[200:203], v[28:31]
	v_mfma_f32_16x16x32_bf16 v[24:27], v[160:163], v[200:203], v[24:27]
	v_mfma_f32_16x16x32_bf16 v[20:23], v[168:171], v[200:203], v[20:23]
	v_mfma_f32_16x16x32_bf16 v[16:19], v[176:179], v[200:203], v[16:19]
	v_mfma_f32_16x16x32_bf16 v[0:3], v[176:179], v[212:215], v[0:3]
	v_mfma_f32_16x16x32_bf16 v[4:7], v[168:171], v[212:215], v[4:7]
	v_mfma_f32_16x16x32_bf16 v[8:11], v[160:163], v[212:215], v[8:11]
	v_mfma_f32_16x16x32_bf16 v[12:15], v[152:155], v[212:215], v[12:15]
	s_setprio 0
	s_setprio 1
	v_mfma_f32_16x16x32_bf16 v[60:63], v[156:159], v[188:191], v[60:63]
	v_mfma_f32_16x16x32_bf16 v[56:59], v[164:167], v[188:191], v[56:59]
	v_mfma_f32_16x16x32_bf16 v[52:55], v[172:175], v[188:191], v[52:55]
	v_mfma_f32_16x16x32_bf16 v[48:51], v[180:183], v[188:191], v[48:51]
	v_mfma_f32_16x16x32_bf16 v[32:35], v[180:183], v[196:199], v[32:35]
	v_mfma_f32_16x16x32_bf16 v[36:39], v[172:175], v[196:199], v[36:39]
	v_mfma_f32_16x16x32_bf16 v[40:43], v[164:167], v[196:199], v[40:43]
	v_mfma_f32_16x16x32_bf16 v[44:47], v[156:159], v[196:199], v[44:47]
	v_mfma_f32_16x16x32_bf16 v[28:31], v[156:159], v[208:211], v[28:31]
	v_mfma_f32_16x16x32_bf16 v[24:27], v[164:167], v[208:211], v[24:27]
	v_mfma_f32_16x16x32_bf16 v[20:23], v[172:175], v[208:211], v[20:23]
	v_mfma_f32_16x16x32_bf16 v[16:19], v[180:183], v[208:211], v[16:19]
	v_mfma_f32_16x16x32_bf16 v[0:3], v[180:183], v[216:219], v[0:3]
	v_mfma_f32_16x16x32_bf16 v[4:7], v[172:175], v[216:219], v[4:7]
	v_mfma_f32_16x16x32_bf16 v[8:11], v[164:167], v[216:219], v[8:11]
	v_mfma_f32_16x16x32_bf16 v[12:15], v[156:159], v[216:219], v[12:15]
	s_setprio 0
	s_barrier
	s_add_i32 s84, 0, 0x18000
	s_add_i32 s85, 0, 0x1c000
	v_add_u32_e32 v164, s84, v148
	v_add_u32_e32 v180, s85, v148
	ds_read_b128 v[152:155], v164
	ds_read_b128 v[156:159], v164 offset:1024
	ds_read_b128 v[160:163], v164 offset:2048
	ds_read_b128 v[164:167], v164 offset:3072
	ds_read_b128 v[168:171], v180
	ds_read_b128 v[172:175], v180 offset:1024
	ds_read_b128 v[176:179], v180 offset:2048
	ds_read_b128 v[180:183], v180 offset:3072
	s_add_u32 s48, s48, 0x10000
	s_addc_u32 s49, s49, 0
	s_mov_b32 m0, s58
	v_lshl_add_u64 v[230:231], s[48:49], 0, v[128:129]
	ds_read_b128 v[184:187], v151 offset:32768
	ds_read_b128 v[188:191], v151 offset:33792
	ds_read_b128 v[192:195], v151 offset:34816
	ds_read_b128 v[196:199], v151 offset:35840
	ds_read_b128 v[200:203], v151 offset:36864
	ds_read_b128 v[208:211], v151 offset:37888
	ds_read_b128 v[212:215], v151 offset:38912
	ds_read_b128 v[216:219], v151 offset:39936
	global_load_lds_dwordx4 v[230:231], off
	v_lshl_add_u64 v[230:231], s[48:49], 0, v[132:133]
	s_mov_b32 m0, s59
	s_nop 0
	global_load_lds_dwordx4 v[230:231], off
	s_waitcnt vmcnt(8)
	s_waitcnt lgkmcnt(0)
	s_barrier
	s_setprio 1
	s_waitcnt lgkmcnt(0)
	v_mfma_f32_16x16x32_bf16 v[120:123], v[152:155], v[184:187], v[120:123]
	v_mfma_f32_16x16x32_bf16 v[124:127], v[160:163], v[184:187], v[124:127]
	v_mfma_f32_16x16x32_bf16 v[116:119], v[168:171], v[184:187], v[116:119]
	v_mfma_f32_16x16x32_bf16 v[112:115], v[176:179], v[184:187], v[112:115]
	v_mfma_f32_16x16x32_bf16 v[96:99], v[176:179], v[192:195], v[96:99]
	v_mfma_f32_16x16x32_bf16 v[100:103], v[168:171], v[192:195], v[100:103]
	v_mfma_f32_16x16x32_bf16 v[104:107], v[160:163], v[192:195], v[104:107]
	v_mfma_f32_16x16x32_bf16 v[108:111], v[152:155], v[192:195], v[108:111]
	v_mfma_f32_16x16x32_bf16 v[92:95], v[152:155], v[200:203], v[92:95]
	v_mfma_f32_16x16x32_bf16 v[88:91], v[160:163], v[200:203], v[88:91]
	v_mfma_f32_16x16x32_bf16 v[84:87], v[168:171], v[200:203], v[84:87]
	v_mfma_f32_16x16x32_bf16 v[80:83], v[176:179], v[200:203], v[80:83]
	v_mfma_f32_16x16x32_bf16 v[64:67], v[176:179], v[212:215], v[64:67]
	v_mfma_f32_16x16x32_bf16 v[68:71], v[168:171], v[212:215], v[68:71]
	v_mfma_f32_16x16x32_bf16 v[72:75], v[160:163], v[212:215], v[72:75]
	v_mfma_f32_16x16x32_bf16 v[76:79], v[152:155], v[212:215], v[76:79]
	s_setprio 0
	s_setprio 1
	v_mfma_f32_16x16x32_bf16 v[120:123], v[156:159], v[188:191], v[120:123]
	v_mfma_f32_16x16x32_bf16 v[124:127], v[164:167], v[188:191], v[124:127]
	v_mfma_f32_16x16x32_bf16 v[116:119], v[172:175], v[188:191], v[116:119]
	v_mfma_f32_16x16x32_bf16 v[112:115], v[180:183], v[188:191], v[112:115]
	v_mfma_f32_16x16x32_bf16 v[96:99], v[180:183], v[196:199], v[96:99]
	v_mfma_f32_16x16x32_bf16 v[100:103], v[172:175], v[196:199], v[100:103]
	v_mfma_f32_16x16x32_bf16 v[104:107], v[164:167], v[196:199], v[104:107]
	v_mfma_f32_16x16x32_bf16 v[108:111], v[156:159], v[196:199], v[108:111]
	v_mfma_f32_16x16x32_bf16 v[92:95], v[156:159], v[208:211], v[92:95]
	v_mfma_f32_16x16x32_bf16 v[88:91], v[164:167], v[208:211], v[88:91]
	v_mfma_f32_16x16x32_bf16 v[84:87], v[172:175], v[208:211], v[84:87]
	v_mfma_f32_16x16x32_bf16 v[80:83], v[180:183], v[208:211], v[80:83]
	v_mfma_f32_16x16x32_bf16 v[64:67], v[180:183], v[216:219], v[64:67]
	v_mfma_f32_16x16x32_bf16 v[68:71], v[172:175], v[216:219], v[68:71]
	v_mfma_f32_16x16x32_bf16 v[72:75], v[164:167], v[216:219], v[72:75]
	v_mfma_f32_16x16x32_bf16 v[76:79], v[156:159], v[216:219], v[76:79]
	s_setprio 0
	s_barrier
; #define PG8_STAGE(bufoff, gbase, voff) do { _Pragma("unroll") for (int _i = 0; _i < 2; ++_i) \
;         __builtin_amdgcn_global_load_lds((const unsigned*)((const char*)(gbase) + (voff)[_i]), (LAS unsigned*)(lds + (bufoff) + ldsw + _i * 8192), 16, 0, 0); } while (0)
; #define PG8_LDA(dst, b, h) do { _Pragma("unroll") for (int m = 0; m < 4; ++m) _Pragma("unroll") for (int k = 0; k < 2; ++k) dst[m][k] = *(const LAS bf16x8*)(lds + PG8_SA(b, h) + aoff + m * 2048 + k * 1024); } while (0)
; #define PG8_MMA(ai, bj, At, Bt) do { __builtin_amdgcn_s_setprio(1); _Pragma("unroll") for (int m = 0; m < 4; ++m) _Pragma("unroll") for (int n = 0; n < 2; ++n) _Pragma("unroll") for (int k = 0; k < 2; ++k) \
;         acc[ai][bj][m][n] = __builtin_amdgcn_mfma_f32_16x16x32_bf16(Bt[n][k], At[m][k], acc[ai][bj][m][n], 0, 0, 0); __builtin_amdgcn_s_setprio(0); } while (0)
; #define PG8_WAIT_V(n) asm volatile("s_waitcnt vmcnt(" #n ")" ::: "memory")
; #define PG8_WAIT_L(n) asm volatile("s_waitcnt lgkmcnt(" #n ")" ::: "memory")
; #define PG8_BAR __builtin_amdgcn_s_barrier()
; #define PG8_SCHED __builtin_amdgcn_sched_barrier(0)
; template <class Epi>
; __device__ __forceinline__ void gemm_phase(LAS unsigned char* lds, const Gemm g, const StaticOrder& S, const Epi& E) {
;     ...
;         for (int t = 0; t < nt; t += 2) {
;     ...
;             PG8_LDA(At, 1, 1); PG8_STAGE(PG8_SB(1, 0), b3, voffB); PG8_STAGE(PG8_SB(1, 1), b3 + hstepB, voffB); PG8_STAGE(PG8_SA(1, 0), a3, voffA);
;             PG8_WAIT_V(8); PG8_WAIT_L(0); PG8_BAR; PG8_MMA(1, 0, At, B0); PG8_MMA(1, 1, At, B1); PG8_BAR; PG8_SCHED;
	s_add_i32 s48, s84, s51
	v_lshl_add_u64 v[220:221], v[220:221], 0, s[12:13]
	s_mov_b32 m0, s48
	ds_read_b128 v[184:187], v151 offset:49152
	ds_read_b128 v[188:191], v151 offset:50176
	ds_read_b128 v[192:195], v151 offset:51200
	ds_read_b128 v[196:199], v151 offset:52224
	ds_read_b128 v[200:203], v151 offset:53248
	ds_read_b128 v[208:211], v151 offset:54272
	ds_read_b128 v[212:215], v151 offset:55296
	ds_read_b128 v[216:219], v151 offset:56320
	global_load_lds_dwordx4 v[220:221], off
	s_add_i32 m0, s48, 0x2000
	s_add_u32 s46, s46, 0x10080
	v_lshl_add_u64 v[220:221], v[222:223], 0, s[12:13]
	s_addc_u32 s47, s47, 0
	s_add_i32 s48, s85, s51
	global_load_lds_dwordx4 v[220:221], off
	v_lshl_add_u64 v[220:221], s[46:47], 0, v[130:131]
	s_mov_b32 m0, s48
	s_nop 0
	global_load_lds_dwordx4 v[220:221], off
	v_lshl_add_u64 v[220:221], s[46:47], 0, v[134:135]
	s_add_i32 m0, s48, 0x2000
	s_nop 0
	global_load_lds_dwordx4 v[220:221], off
	v_lshl_add_u64 v[220:221], v[224:225], 0, s[12:13]
	s_mov_b32 m0, s63
	s_nop 0
	global_load_lds_dwordx4 v[220:221], off
	v_lshl_add_u64 v[220:221], v[226:227], 0, s[12:13]
	s_mov_b32 m0, s64
	s_nop 0
	global_load_lds_dwordx4 v[220:221], off
	s_waitcnt vmcnt(8)
	s_waitcnt lgkmcnt(0)
	s_barrier
	s_setprio 1
	s_waitcnt lgkmcnt(0)
	v_mfma_f32_16x16x32_bf16 v[60:63], v[152:155], v[184:187], v[60:63]
	v_mfma_f32_16x16x32_bf16 v[56:59], v[160:163], v[184:187], v[56:59]
	v_mfma_f32_16x16x32_bf16 v[52:55], v[168:171], v[184:187], v[52:55]
	v_mfma_f32_16x16x32_bf16 v[48:51], v[176:179], v[184:187], v[48:51]
	v_mfma_f32_16x16x32_bf16 v[32:35], v[176:179], v[192:195], v[32:35]
	v_mfma_f32_16x16x32_bf16 v[36:39], v[168:171], v[192:195], v[36:39]
	v_mfma_f32_16x16x32_bf16 v[40:43], v[160:163], v[192:195], v[40:43]
	v_mfma_f32_16x16x32_bf16 v[44:47], v[152:155], v[192:195], v[44:47]
	v_mfma_f32_16x16x32_bf16 v[28:31], v[152:155], v[200:203], v[28:31]
	v_mfma_f32_16x16x32_bf16 v[24:27], v[160:163], v[200:203], v[24:27]
	v_mfma_f32_16x16x32_bf16 v[20:23], v[168:171], v[200:203], v[20:23]
	v_mfma_f32_16x16x32_bf16 v[16:19], v[176:179], v[200:203], v[16:19]
	v_mfma_f32_16x16x32_bf16 v[0:3], v[176:179], v[212:215], v[0:3]
	v_mfma_f32_16x16x32_bf16 v[4:7], v[168:171], v[212:215], v[4:7]
	v_mfma_f32_16x16x32_bf16 v[8:11], v[160:163], v[212:215], v[8:11]
	v_mfma_f32_16x16x32_bf16 v[12:15], v[152:155], v[212:215], v[12:15]
	s_setprio 0
	s_setprio 1
	v_mfma_f32_16x16x32_bf16 v[60:63], v[156:159], v[188:191], v[60:63]
	v_mfma_f32_16x16x32_bf16 v[56:59], v[164:167], v[188:191], v[56:59]
	v_mfma_f32_16x16x32_bf16 v[52:55], v[172:175], v[188:191], v[52:55]
	v_mfma_f32_16x16x32_bf16 v[48:51], v[180:183], v[188:191], v[48:51]
	v_mfma_f32_16x16x32_bf16 v[32:35], v[180:183], v[196:199], v[32:35]
	v_mfma_f32_16x16x32_bf16 v[36:39], v[172:175], v[196:199], v[36:39]
	v_mfma_f32_16x16x32_bf16 v[40:43], v[164:167], v[196:199], v[40:43]
	v_mfma_f32_16x16x32_bf16 v[44:47], v[156:159], v[196:199], v[44:47]
	v_mfma_f32_16x16x32_bf16 v[28:31], v[156:159], v[208:211], v[28:31]
	v_mfma_f32_16x16x32_bf16 v[24:27], v[164:167], v[208:211], v[24:27]
	v_mfma_f32_16x16x32_bf16 v[20:23], v[172:175], v[208:211], v[20:23]
	v_mfma_f32_16x16x32_bf16 v[16:19], v[180:183], v[208:211], v[16:19]
	v_mfma_f32_16x16x32_bf16 v[0:3], v[180:183], v[216:219], v[0:3]
	v_mfma_f32_16x16x32_bf16 v[4:7], v[172:175], v[216:219], v[4:7]
	v_mfma_f32_16x16x32_bf16 v[8:11], v[164:167], v[216:219], v[8:11]
	v_mfma_f32_16x16x32_bf16 v[12:15], v[156:159], v[216:219], v[12:15]
	s_setprio 0
	s_barrier
	s_add_u32 s44, s44, 0x100
	s_addc_u32 s45, s45, 0
	s_add_u32 s79, s79, 0x100
	s_addc_u32 s82, s82, 0
	s_cmp_ge_i32 s83, s61
	s_mov_b32 s46, s83
	s_cbranch_scc0 .LBB0_1161

; #define PG8_STAGE(bufoff, gbase, voff) do { _Pragma("unroll") for (int _i = 0; _i < 2; ++_i) \
;         __builtin_amdgcn_global_load_lds((const unsigned*)((const char*)(gbase) + (voff)[_i]), (LAS unsigned*)(lds + (bufoff) + ldsw + _i * 8192), 16, 0, 0); } while (0)
; #define PG8_LDA(dst, b, h) do { _Pragma("unroll") for (int m = 0; m < 4; ++m) _Pragma("unroll") for (int k = 0; k < 2; ++k) dst[m][k] = *(const LAS bf16x8*)(lds + PG8_SA(b, h) + aoff + m * 2048 + k * 1024); } while (0)
; #define PG8_LDB(dst, b, h) do { _Pragma("unroll") for (int n = 0; n < 2; ++n) _Pragma("unroll") for (int k = 0; k < 2; ++k) dst[n][k] = *(const LAS bf16x8*)(lds + PG8_SB(b, h) + boff + n * 2048 + k * 1024); } while (0)
; #define PG8_MMA(ai, bj, At, Bt) do { __builtin_amdgcn_s_setprio(1); _Pragma("unroll") for (int m = 0; m < 4; ++m) _Pragma("unroll") for (int n = 0; n < 2; ++n) _Pragma("unroll") for (int k = 0; k < 2; ++k) \
;         acc[ai][bj][m][n] = __builtin_amdgcn_mfma_f32_16x16x32_bf16(Bt[n][k], At[m][k], acc[ai][bj][m][n], 0, 0, 0); __builtin_amdgcn_s_setprio(0); } while (0)
; #define PG8_WAIT_V(n) asm volatile("s_waitcnt vmcnt(" #n ")" ::: "memory")
; #define PG8_WAIT_L(n) asm volatile("s_waitcnt lgkmcnt(" #n ")" ::: "memory")
; #define PG8_BAR __builtin_amdgcn_s_barrier()
; #define PG8_SCHED __builtin_amdgcn_sched_barrier(0)
; template <class Epi>
; __device__ __forceinline__ void gemm_phase(LAS unsigned char* lds, const Gemm g, const StaticOrder& S, const Epi& E) {
;     ...
;         for (int t = 0; t < nt; t += 2) {
;             const bool last = (t == nt - 2);
;             const char* a1 = cA + (size_t)(t + 1) * kstep;
;             const char* a2 = last ? nA : cA + (size_t)(t + 2) * kstep; const char* b2 = last ? nB : cB + (size_t)(t + 2) * kstep;
;             const char* a3 = a2 + kstep; const char* b3 = b2 + kstep;
;             PG8_LDB(B0, 0, 0); PG8_LDB(B1, 0, 1); PG8_SCHED; PG8_LDA(At, 0, 0); PG8_STAGE(PG8_SA(1, 1), a1 + hstepA, voffA);
;             PG8_WAIT_V(8); PG8_WAIT_L(0); PG8_BAR; PG8_MMA(0, 0, At, B0); PG8_MMA(0, 1, At, B1); PG8_BAR; PG8_SCHED;
;             PG8_LDA(At, 0, 1); PG8_STAGE(PG8_SB(0, 0), b2, voffB); PG8_STAGE(PG8_SB(0, 1), b2 + hstepB, voffB); PG8_STAGE(PG8_SA(0, 0), a2, voffA);
;             PG8_WAIT_V(8); PG8_WAIT_L(0); PG8_BAR; PG8_MMA(1, 0, At, B0); PG8_MMA(1, 1, At, B1); PG8_BAR; PG8_SCHED;
.LBB0_1244:
	ds_read_b128 v[150:153], v187
	ds_read_b128 v[154:157], v187 offset:1024
	ds_read_b128 v[158:161], v187 offset:2048
	ds_read_b128 v[162:165], v187 offset:3072
	ds_read_b128 v[166:169], v188
	ds_read_b128 v[170:173], v188 offset:1024
	ds_read_b128 v[174:177], v188 offset:2048
	ds_read_b128 v[178:181], v188 offset:3072
	s_add_i32 s84, s52, 2
	s_add_u32 s12, s4, 0x100
	s_addc_u32 s13, s5, 0
	s_cmp_eq_u32 s67, s52
	s_cselect_b32 s52, s50, s1
	s_cselect_b32 s55, s49, s13
	s_cselect_b32 s54, s48, s12
	s_cselect_b32 s53, s51, s77
	v_lshl_add_u64 v[224:225], s[4:5], 0, v[142:143]
	s_add_i32 m0, s59, 0xc000
	ds_read_b128 v[182:185], v189
	ds_read_b128 v[192:195], v189 offset:1024
	ds_read_b128 v[196:199], v189 offset:2048
	ds_read_b128 v[200:203], v189 offset:3072
	ds_read_b128 v[208:211], v189 offset:4096
	ds_read_b128 v[212:215], v189 offset:5120
	ds_read_b128 v[216:219], v189 offset:6144
	ds_read_b128 v[220:223], v189 offset:7168
	global_load_lds_dwordx4 v[224:225], off
	v_lshl_add_u64 v[224:225], s[4:5], 0, v[144:145]
	s_add_i32 m0, s59, 0xe000
	s_nop 0
	global_load_lds_dwordx4 v[224:225], off
	s_waitcnt vmcnt(8)
	s_waitcnt lgkmcnt(0)
	s_barrier
	s_setprio 1
	s_waitcnt lgkmcnt(0)
	v_mfma_f32_16x16x32_bf16 v[124:127], v[150:153], v[182:185], v[124:127]
	v_mfma_f32_16x16x32_bf16 v[120:123], v[158:161], v[182:185], v[120:123]
	v_mfma_f32_16x16x32_bf16 v[108:111], v[166:169], v[182:185], v[108:111]
	v_mfma_f32_16x16x32_bf16 v[100:103], v[174:177], v[182:185], v[100:103]
	v_mfma_f32_16x16x32_bf16 v[84:87], v[174:177], v[196:199], v[84:87]
	v_mfma_f32_16x16x32_bf16 v[92:95], v[166:169], v[196:199], v[92:95]
	v_mfma_f32_16x16x32_bf16 v[112:115], v[158:161], v[196:199], v[112:115]
	v_mfma_f32_16x16x32_bf16 v[116:119], v[150:153], v[196:199], v[116:119]
	v_mfma_f32_16x16x32_bf16 v[104:107], v[150:153], v[208:211], v[104:107]
	v_mfma_f32_16x16x32_bf16 v[96:99], v[158:161], v[208:211], v[96:99]
	v_mfma_f32_16x16x32_bf16 v[76:79], v[166:169], v[208:211], v[76:79]
	v_mfma_f32_16x16x32_bf16 v[72:75], v[174:177], v[208:211], v[72:75]
	v_mfma_f32_16x16x32_bf16 v[64:67], v[174:177], v[216:219], v[64:67]
	v_mfma_f32_16x16x32_bf16 v[68:71], v[166:169], v[216:219], v[68:71]
	v_mfma_f32_16x16x32_bf16 v[80:83], v[158:161], v[216:219], v[80:83]
	v_mfma_f32_16x16x32_bf16 v[88:91], v[150:153], v[216:219], v[88:91]
	s_setprio 0
	s_setprio 1
	v_mfma_f32_16x16x32_bf16 v[124:127], v[154:157], v[192:195], v[124:127]
	v_mfma_f32_16x16x32_bf16 v[120:123], v[162:165], v[192:195], v[120:123]
	v_mfma_f32_16x16x32_bf16 v[108:111], v[170:173], v[192:195], v[108:111]
	v_mfma_f32_16x16x32_bf16 v[100:103], v[178:181], v[192:195], v[100:103]
	v_mfma_f32_16x16x32_bf16 v[84:87], v[178:181], v[200:203], v[84:87]
	v_mfma_f32_16x16x32_bf16 v[92:95], v[170:173], v[200:203], v[92:95]
	v_mfma_f32_16x16x32_bf16 v[112:115], v[162:165], v[200:203], v[112:115]
	v_mfma_f32_16x16x32_bf16 v[116:119], v[154:157], v[200:203], v[116:119]
	v_mfma_f32_16x16x32_bf16 v[104:107], v[154:157], v[212:215], v[104:107]
	v_mfma_f32_16x16x32_bf16 v[96:99], v[162:165], v[212:215], v[96:99]
	v_mfma_f32_16x16x32_bf16 v[76:79], v[170:173], v[212:215], v[76:79]
	v_mfma_f32_16x16x32_bf16 v[72:75], v[178:181], v[212:215], v[72:75]
	v_mfma_f32_16x16x32_bf16 v[64:67], v[178:181], v[220:223], v[64:67]
	v_mfma_f32_16x16x32_bf16 v[68:71], v[170:173], v[220:223], v[68:71]
	v_mfma_f32_16x16x32_bf16 v[80:83], v[162:165], v[220:223], v[80:83]
	v_mfma_f32_16x16x32_bf16 v[88:91], v[154:157], v[220:223], v[88:91]
	s_setprio 0
	s_barrier
	s_add_i32 s4, s70, s58
	v_lshl_add_u64 v[224:225], s[52:53], 0, v[130:131]
	s_mov_b32 m0, s4
	ds_read_b128 v[182:185], v189 offset:16384
	ds_read_b128 v[192:195], v189 offset:17408
	ds_read_b128 v[196:199], v189 offset:18432
	ds_read_b128 v[200:203], v189 offset:19456
	ds_read_b128 v[208:211], v189 offset:20480
	ds_read_b128 v[212:215], v189 offset:21504
	ds_read_b128 v[216:219], v189 offset:22528
	ds_read_b128 v[220:223], v189 offset:23552
	global_load_lds_dwordx4 v[224:225], off
	s_add_i32 m0, s4, 0x2000
	s_add_u32 s4, s52, 0x158000
	v_lshl_add_u64 v[226:227], s[52:53], 0, v[134:135]
	s_addc_u32 s5, s53, 0
	s_add_i32 s85, s71, s58
	global_load_lds_dwordx4 v[226:227], off
	v_lshl_add_u64 v[230:231], s[4:5], 0, v[130:131]
	s_mov_b32 m0, s85
	v_lshl_add_u64 v[232:233], s[54:55], 0, v[132:133]
	global_load_lds_dwordx4 v[230:231], off
	v_lshl_add_u64 v[230:231], s[4:5], 0, v[134:135]
	s_add_i32 m0, s85, 0x2000
	s_nop 0
	global_load_lds_dwordx4 v[230:231], off
	v_lshl_add_u64 v[230:231], s[54:55], 0, v[128:129]
	s_mov_b32 m0, s59
	s_nop 0
	global_load_lds_dwordx4 v[230:231], off
	s_mov_b32 m0, s60
	s_nop 0
	global_load_lds_dwordx4 v[232:233], off
	s_waitcnt vmcnt(8)
	s_waitcnt lgkmcnt(0)
	s_barrier
; #define PG8_STAGE(bufoff, gbase, voff) do { _Pragma("unroll") for (int _i = 0; _i < 2; ++_i) \
;         __builtin_amdgcn_global_load_lds((const unsigned*)((const char*)(gbase) + (voff)[_i]), (LAS unsigned*)(lds + (bufoff) + ldsw + _i * 8192), 16, 0, 0); } while (0)
; #define PG8_LDA(dst, b, h) do { _Pragma("unroll") for (int m = 0; m < 4; ++m) _Pragma("unroll") for (int k = 0; k < 2; ++k) dst[m][k] = *(const LAS bf16x8*)(lds + PG8_SA(b, h) + aoff + m * 2048 + k * 1024); } while (0)
; #define PG8_LDB(dst, b, h) do { _Pragma("unroll") for (int n = 0; n < 2; ++n) _Pragma("unroll") for (int k = 0; k < 2; ++k) dst[n][k] = *(const LAS bf16x8*)(lds + PG8_SB(b, h) + boff + n * 2048 + k * 1024); } while (0)
; #define PG8_MMA(ai, bj, At, Bt) do { __builtin_amdgcn_s_setprio(1); _Pragma("unroll") for (int m = 0; m < 4; ++m) _Pragma("unroll") for (int n = 0; n < 2; ++n) _Pragma("unroll") for (int k = 0; k < 2; ++k) \
;         acc[ai][bj][m][n] = __builtin_amdgcn_mfma_f32_16x16x32_bf16(Bt[n][k], At[m][k], acc[ai][bj][m][n], 0, 0, 0); __builtin_amdgcn_s_setprio(0); } while (0)
; #define PG8_WAIT_V(n) asm volatile("s_waitcnt vmcnt(" #n ")" ::: "memory")
; #define PG8_WAIT_L(n) asm volatile("s_waitcnt lgkmcnt(" #n ")" ::: "memory")
; #define PG8_BAR __builtin_amdgcn_s_barrier()
; #define PG8_SCHED __builtin_amdgcn_sched_barrier(0)
; template <class Epi>
; __device__ __forceinline__ void gemm_phase(LAS unsigned char* lds, const Gemm g, const StaticOrder& S, const Epi& E) {
;     ...
;             PG8_WAIT_V(8); PG8_WAIT_L(0); PG8_BAR; PG8_MMA(1, 0, At, B0); PG8_MMA(1, 1, At, B1); PG8_BAR; PG8_SCHED;
;             PG8_LDB(B0, 1, 0); PG8_LDB(B1, 1, 1); PG8_SCHED; PG8_LDA(At, 1, 0); PG8_STAGE(PG8_SA(0, 1), a2 + hstepA, voffA);
;             PG8_WAIT_V(8); PG8_WAIT_L(0); PG8_BAR; PG8_MMA(0, 0, At, B0); PG8_MMA(0, 1, At, B1); PG8_BAR; PG8_SCHED;
	s_setprio 1
	s_waitcnt lgkmcnt(0)
	v_mfma_f32_16x16x32_bf16 v[60:63], v[150:153], v[182:185], v[60:63]
	v_mfma_f32_16x16x32_bf16 v[56:59], v[158:161], v[182:185], v[56:59]
	v_mfma_f32_16x16x32_bf16 v[44:47], v[166:169], v[182:185], v[44:47]
	v_mfma_f32_16x16x32_bf16 v[36:39], v[174:177], v[182:185], v[36:39]
	v_mfma_f32_16x16x32_bf16 v[20:23], v[174:177], v[196:199], v[20:23]
	v_mfma_f32_16x16x32_bf16 v[28:31], v[166:169], v[196:199], v[28:31]
	v_mfma_f32_16x16x32_bf16 v[48:51], v[158:161], v[196:199], v[48:51]
	v_mfma_f32_16x16x32_bf16 v[52:55], v[150:153], v[196:199], v[52:55]
	v_mfma_f32_16x16x32_bf16 v[40:43], v[150:153], v[208:211], v[40:43]
	v_mfma_f32_16x16x32_bf16 v[32:35], v[158:161], v[208:211], v[32:35]
	v_mfma_f32_16x16x32_bf16 v[12:15], v[166:169], v[208:211], v[12:15]
	v_mfma_f32_16x16x32_bf16 v[8:11], v[174:177], v[208:211], v[8:11]
	v_mfma_f32_16x16x32_bf16 v[0:3], v[174:177], v[216:219], v[0:3]
	v_mfma_f32_16x16x32_bf16 v[4:7], v[166:169], v[216:219], v[4:7]
	v_mfma_f32_16x16x32_bf16 v[16:19], v[158:161], v[216:219], v[16:19]
	v_mfma_f32_16x16x32_bf16 v[24:27], v[150:153], v[216:219], v[24:27]
	s_setprio 0
	s_setprio 1
	v_mfma_f32_16x16x32_bf16 v[60:63], v[154:157], v[192:195], v[60:63]
	v_mfma_f32_16x16x32_bf16 v[56:59], v[162:165], v[192:195], v[56:59]
	v_mfma_f32_16x16x32_bf16 v[44:47], v[170:173], v[192:195], v[44:47]
	v_mfma_f32_16x16x32_bf16 v[36:39], v[178:181], v[192:195], v[36:39]
	v_mfma_f32_16x16x32_bf16 v[20:23], v[178:181], v[200:203], v[20:23]
	v_mfma_f32_16x16x32_bf16 v[28:31], v[170:173], v[200:203], v[28:31]
	v_mfma_f32_16x16x32_bf16 v[48:51], v[162:165], v[200:203], v[48:51]
	v_mfma_f32_16x16x32_bf16 v[52:55], v[154:157], v[200:203], v[52:55]
	v_mfma_f32_16x16x32_bf16 v[40:43], v[154:157], v[212:215], v[40:43]
	v_mfma_f32_16x16x32_bf16 v[32:35], v[162:165], v[212:215], v[32:35]
	v_mfma_f32_16x16x32_bf16 v[12:15], v[170:173], v[212:215], v[12:15]
	v_mfma_f32_16x16x32_bf16 v[8:11], v[178:181], v[212:215], v[8:11]
	v_mfma_f32_16x16x32_bf16 v[0:3], v[178:181], v[220:223], v[0:3]
	v_mfma_f32_16x16x32_bf16 v[4:7], v[170:173], v[220:223], v[4:7]
	v_mfma_f32_16x16x32_bf16 v[16:19], v[162:165], v[220:223], v[16:19]
	v_mfma_f32_16x16x32_bf16 v[24:27], v[154:157], v[220:223], v[24:27]
	s_setprio 0
	s_barrier
	s_add_i32 s85, 0, 0x18000
	s_add_i32 s86, 0, 0x1c000
	v_add_u32_e32 v162, s85, v186
	v_add_u32_e32 v178, s86, v186
	ds_read_b128 v[150:153], v162
	ds_read_b128 v[154:157], v162 offset:1024
	ds_read_b128 v[158:161], v162 offset:2048
	ds_read_b128 v[162:165], v162 offset:3072
	ds_read_b128 v[166:169], v178
	ds_read_b128 v[170:173], v178 offset:1024
	ds_read_b128 v[174:177], v178 offset:2048
	ds_read_b128 v[178:181], v178 offset:3072
	s_add_u32 s4, s54, 0x158000
	s_addc_u32 s5, s55, 0
	s_mov_b32 m0, s61
	v_lshl_add_u64 v[234:235], s[4:5], 0, v[128:129]
	ds_read_b128 v[182:185], v189 offset:32768
	ds_read_b128 v[192:195], v189 offset:33792
	ds_read_b128 v[196:199], v189 offset:34816
	ds_read_b128 v[200:203], v189 offset:35840
	ds_read_b128 v[208:211], v189 offset:36864
	ds_read_b128 v[212:215], v189 offset:37888
	ds_read_b128 v[216:219], v189 offset:38912
	ds_read_b128 v[220:223], v189 offset:39936
	global_load_lds_dwordx4 v[234:235], off
	v_lshl_add_u64 v[234:235], s[4:5], 0, v[132:133]
	s_mov_b32 m0, s62
	s_nop 0
	global_load_lds_dwordx4 v[234:235], off
	s_waitcnt vmcnt(8)
	s_waitcnt lgkmcnt(0)
	s_barrier
	s_setprio 1
	s_waitcnt lgkmcnt(0)
	v_mfma_f32_16x16x32_bf16 v[124:127], v[150:153], v[182:185], v[124:127]
	v_mfma_f32_16x16x32_bf16 v[120:123], v[158:161], v[182:185], v[120:123]
	v_mfma_f32_16x16x32_bf16 v[108:111], v[166:169], v[182:185], v[108:111]
	v_mfma_f32_16x16x32_bf16 v[100:103], v[174:177], v[182:185], v[100:103]
	v_mfma_f32_16x16x32_bf16 v[84:87], v[174:177], v[196:199], v[84:87]
	v_mfma_f32_16x16x32_bf16 v[92:95], v[166:169], v[196:199], v[92:95]
	v_mfma_f32_16x16x32_bf16 v[112:115], v[158:161], v[196:199], v[112:115]
	v_mfma_f32_16x16x32_bf16 v[116:119], v[150:153], v[196:199], v[116:119]
	v_mfma_f32_16x16x32_bf16 v[104:107], v[150:153], v[208:211], v[104:107]
	v_mfma_f32_16x16x32_bf16 v[96:99], v[158:161], v[208:211], v[96:99]
	v_mfma_f32_16x16x32_bf16 v[76:79], v[166:169], v[208:211], v[76:79]
	v_mfma_f32_16x16x32_bf16 v[72:75], v[174:177], v[208:211], v[72:75]
	v_mfma_f32_16x16x32_bf16 v[64:67], v[174:177], v[216:219], v[64:67]
	v_mfma_f32_16x16x32_bf16 v[68:71], v[166:169], v[216:219], v[68:71]
	v_mfma_f32_16x16x32_bf16 v[80:83], v[158:161], v[216:219], v[80:83]
	v_mfma_f32_16x16x32_bf16 v[88:91], v[150:153], v[216:219], v[88:91]
	s_setprio 0
	s_setprio 1
	v_mfma_f32_16x16x32_bf16 v[124:127], v[154:157], v[192:195], v[124:127]
	v_mfma_f32_16x16x32_bf16 v[120:123], v[162:165], v[192:195], v[120:123]
	v_mfma_f32_16x16x32_bf16 v[108:111], v[170:173], v[192:195], v[108:111]
	v_mfma_f32_16x16x32_bf16 v[100:103], v[178:181], v[192:195], v[100:103]
	v_mfma_f32_16x16x32_bf16 v[84:87], v[178:181], v[200:203], v[84:87]
	v_mfma_f32_16x16x32_bf16 v[92:95], v[170:173], v[200:203], v[92:95]
	v_mfma_f32_16x16x32_bf16 v[112:115], v[162:165], v[200:203], v[112:115]
	v_mfma_f32_16x16x32_bf16 v[116:119], v[154:157], v[200:203], v[116:119]
	v_mfma_f32_16x16x32_bf16 v[104:107], v[154:157], v[212:215], v[104:107]
	v_mfma_f32_16x16x32_bf16 v[96:99], v[162:165], v[212:215], v[96:99]
	v_mfma_f32_16x16x32_bf16 v[76:79], v[170:173], v[212:215], v[76:79]
	v_mfma_f32_16x16x32_bf16 v[72:75], v[178:181], v[212:215], v[72:75]
	v_mfma_f32_16x16x32_bf16 v[64:67], v[178:181], v[220:223], v[64:67]
	v_mfma_f32_16x16x32_bf16 v[68:71], v[170:173], v[220:223], v[68:71]
	v_mfma_f32_16x16x32_bf16 v[80:83], v[162:165], v[220:223], v[80:83]
	v_mfma_f32_16x16x32_bf16 v[88:91], v[154:157], v[220:223], v[88:91]
	s_setprio 0
	s_barrier
; #define PG8_STAGE(bufoff, gbase, voff) do { _Pragma("unroll") for (int _i = 0; _i < 2; ++_i) \
;         __builtin_amdgcn_global_load_lds((const unsigned*)((const char*)(gbase) + (voff)[_i]), (LAS unsigned*)(lds + (bufoff) + ldsw + _i * 8192), 16, 0, 0); } while (0)
; #define PG8_LDA(dst, b, h) do { _Pragma("unroll") for (int m = 0; m < 4; ++m) _Pragma("unroll") for (int k = 0; k < 2; ++k) dst[m][k] = *(const LAS bf16x8*)(lds + PG8_SA(b, h) + aoff + m * 2048 + k * 1024); } while (0)
; #define PG8_MMA(ai, bj, At, Bt) do { __builtin_amdgcn_s_setprio(1); _Pragma("unroll") for (int m = 0; m < 4; ++m) _Pragma("unroll") for (int n = 0; n < 2; ++n) _Pragma("unroll") for (int k = 0; k < 2; ++k) \
;         acc[ai][bj][m][n] = __builtin_amdgcn_mfma_f32_16x16x32_bf16(Bt[n][k], At[m][k], acc[ai][bj][m][n], 0, 0, 0); __builtin_amdgcn_s_setprio(0); } while (0)
; #define PG8_WAIT_V(n) asm volatile("s_waitcnt vmcnt(" #n ")" ::: "memory")
; #define PG8_WAIT_L(n) asm volatile("s_waitcnt lgkmcnt(" #n ")" ::: "memory")
; #define PG8_BAR __builtin_amdgcn_s_barrier()
; #define PG8_SCHED __builtin_amdgcn_sched_barrier(0)
; template <class Epi>
; __device__ __forceinline__ void gemm_phase(LAS unsigned char* lds, const Gemm g, const StaticOrder& S, const Epi& E) {
;     ...
;         for (int t = 0; t < nt; t += 2) {
;     ...
;             PG8_LDA(At, 1, 1); PG8_STAGE(PG8_SB(1, 0), b3, voffB); PG8_STAGE(PG8_SB(1, 1), b3 + hstepB, voffB); PG8_STAGE(PG8_SA(1, 0), a3, voffA);
;             PG8_WAIT_V(8); PG8_WAIT_L(0); PG8_BAR; PG8_MMA(1, 0, At, B0); PG8_MMA(1, 1, At, B1); PG8_BAR; PG8_SCHED;
	s_add_i32 s4, s85, s58
	v_lshl_add_u64 v[224:225], v[224:225], 0, s[16:17]
	s_mov_b32 m0, s4
	ds_read_b128 v[182:185], v189 offset:49152
	ds_read_b128 v[192:195], v189 offset:50176
	ds_read_b128 v[196:199], v189 offset:51200
	ds_read_b128 v[200:203], v189 offset:52224
	ds_read_b128 v[208:211], v189 offset:53248
	ds_read_b128 v[212:215], v189 offset:54272
	ds_read_b128 v[216:219], v189 offset:55296
	ds_read_b128 v[220:223], v189 offset:56320
	global_load_lds_dwordx4 v[224:225], off
	s_add_i32 m0, s4, 0x2000
	s_add_u32 s4, s52, 0x158080
	v_lshl_add_u64 v[224:225], v[226:227], 0, s[16:17]
	s_addc_u32 s5, s53, 0
	s_add_i32 s52, s86, s58
	global_load_lds_dwordx4 v[224:225], off
	v_lshl_add_u64 v[224:225], s[4:5], 0, v[130:131]
	s_mov_b32 m0, s52
	s_nop 0
	global_load_lds_dwordx4 v[224:225], off
	v_lshl_add_u64 v[224:225], s[4:5], 0, v[134:135]
	s_add_i32 m0, s52, 0x2000
	s_nop 0
	global_load_lds_dwordx4 v[224:225], off
	v_lshl_add_u64 v[224:225], v[230:231], 0, s[16:17]
	s_mov_b32 m0, s65
	s_nop 0
	global_load_lds_dwordx4 v[224:225], off
	v_lshl_add_u64 v[224:225], v[232:233], 0, s[16:17]
	s_mov_b32 m0, s66
	s_nop 0
	global_load_lds_dwordx4 v[224:225], off
	s_waitcnt vmcnt(8)
	s_waitcnt lgkmcnt(0)
	s_barrier
	s_setprio 1
	s_waitcnt lgkmcnt(0)
	v_mfma_f32_16x16x32_bf16 v[60:63], v[150:153], v[182:185], v[60:63]
	v_mfma_f32_16x16x32_bf16 v[56:59], v[158:161], v[182:185], v[56:59]
	v_mfma_f32_16x16x32_bf16 v[44:47], v[166:169], v[182:185], v[44:47]
	v_mfma_f32_16x16x32_bf16 v[36:39], v[174:177], v[182:185], v[36:39]
	v_mfma_f32_16x16x32_bf16 v[20:23], v[174:177], v[196:199], v[20:23]
	v_mfma_f32_16x16x32_bf16 v[28:31], v[166:169], v[196:199], v[28:31]
	v_mfma_f32_16x16x32_bf16 v[48:51], v[158:161], v[196:199], v[48:51]
	v_mfma_f32_16x16x32_bf16 v[52:55], v[150:153], v[196:199], v[52:55]
	v_mfma_f32_16x16x32_bf16 v[40:43], v[150:153], v[208:211], v[40:43]
	v_mfma_f32_16x16x32_bf16 v[32:35], v[158:161], v[208:211], v[32:35]
	v_mfma_f32_16x16x32_bf16 v[12:15], v[166:169], v[208:211], v[12:15]
	v_mfma_f32_16x16x32_bf16 v[8:11], v[174:177], v[208:211], v[8:11]
	v_mfma_f32_16x16x32_bf16 v[0:3], v[174:177], v[216:219], v[0:3]
	v_mfma_f32_16x16x32_bf16 v[4:7], v[166:169], v[216:219], v[4:7]
	v_mfma_f32_16x16x32_bf16 v[16:19], v[158:161], v[216:219], v[16:19]
	v_mfma_f32_16x16x32_bf16 v[24:27], v[150:153], v[216:219], v[24:27]
	s_setprio 0
	s_setprio 1
	v_mfma_f32_16x16x32_bf16 v[60:63], v[154:157], v[192:195], v[60:63]
	v_mfma_f32_16x16x32_bf16 v[56:59], v[162:165], v[192:195], v[56:59]
	v_mfma_f32_16x16x32_bf16 v[44:47], v[170:173], v[192:195], v[44:47]
	v_mfma_f32_16x16x32_bf16 v[36:39], v[178:181], v[192:195], v[36:39]
	v_mfma_f32_16x16x32_bf16 v[20:23], v[178:181], v[200:203], v[20:23]
	v_mfma_f32_16x16x32_bf16 v[28:31], v[170:173], v[200:203], v[28:31]
	v_mfma_f32_16x16x32_bf16 v[48:51], v[162:165], v[200:203], v[48:51]
	v_mfma_f32_16x16x32_bf16 v[52:55], v[154:157], v[200:203], v[52:55]
	v_mfma_f32_16x16x32_bf16 v[40:43], v[154:157], v[212:215], v[40:43]
	v_mfma_f32_16x16x32_bf16 v[32:35], v[162:165], v[212:215], v[32:35]
	v_mfma_f32_16x16x32_bf16 v[12:15], v[170:173], v[212:215], v[12:15]
	v_mfma_f32_16x16x32_bf16 v[8:11], v[178:181], v[212:215], v[8:11]
	v_mfma_f32_16x16x32_bf16 v[0:3], v[178:181], v[220:223], v[0:3]
	v_mfma_f32_16x16x32_bf16 v[4:7], v[170:173], v[220:223], v[4:7]
	v_mfma_f32_16x16x32_bf16 v[16:19], v[162:165], v[220:223], v[16:19]
	v_mfma_f32_16x16x32_bf16 v[24:27], v[154:157], v[220:223], v[24:27]
	s_setprio 0
	s_barrier
	s_add_u32 s1, s1, 0x100
	s_addc_u32 s77, s77, 0
	s_cmp_ge_i32 s84, s64
	s_mov_b64 s[4:5], s[12:13]
	s_mov_b32 s52, s84
	s_cbranch_scc0 .LBB0_1244
;     __device__ __forceinline__ void operator()(Acc& acc, const Unit& u, int wr, int wc, int fr, int fq) const {
;         const size_t off0 = ((size_t)u.pm * BM + wr * 64 + fr) * DM + u.pn * BM + wc * 32 + 8 * fq;
;         u32x4 pa[2][2], pb[2][2];
	v_pk_mul_f32 v[170:171], v[126:127], 0.5 op_sel_hi:[1,0]
	v_pk_mul_f32 v[172:173], v[124:125], 0.5 op_sel_hi:[1,0]
	v_pk_mul_f32 v[174:175], v[122:123], 0.5 op_sel_hi:[1,0]
	v_pk_mul_f32 v[176:177], v[120:121], 0.5 op_sel_hi:[1,0]
	v_pk_mul_f32 v[178:179], v[110:111], 0.5 op_sel_hi:[1,0]
	v_pk_mul_f32 v[180:181], v[108:109], 0.5 op_sel_hi:[1,0]
	v_pk_mul_f32 v[182:183], v[102:103], 0.5 op_sel_hi:[1,0]
	v_pk_mul_f32 v[184:185], v[100:101], 0.5 op_sel_hi:[1,0]
	v_pk_mul_f32 v[160:161], v[118:119], 0.5 op_sel_hi:[1,0]
	v_pk_mul_f32 v[158:159], v[116:117], 0.5 op_sel_hi:[1,0]
	v_pk_mul_f32 v[156:157], v[114:115], 0.5 op_sel_hi:[1,0]
	v_pk_mul_f32 v[154:155], v[112:113], 0.5 op_sel_hi:[1,0]
	v_pk_mul_f32 v[168:169], v[94:95], 0.5 op_sel_hi:[1,0]
	v_pk_mul_f32 v[166:167], v[92:93], 0.5 op_sel_hi:[1,0]
	v_pk_mul_f32 v[164:165], v[86:87], 0.5 op_sel_hi:[1,0]
	v_pk_mul_f32 v[162:163], v[84:85], 0.5 op_sel_hi:[1,0]
	v_pk_mul_f32 v[116:117], v[106:107], 0.5 op_sel_hi:[1,0]
	v_pk_mul_f32 v[118:119], v[104:105], 0.5 op_sel_hi:[1,0]
	v_pk_mul_f32 v[120:121], v[98:99], 0.5 op_sel_hi:[1,0]
	v_pk_mul_f32 v[122:123], v[96:97], 0.5 op_sel_hi:[1,0]
	v_pk_mul_f32 v[124:125], v[78:79], 0.5 op_sel_hi:[1,0]
	v_pk_mul_f32 v[126:127], v[76:77], 0.5 op_sel_hi:[1,0]
	v_pk_mul_f32 v[150:151], v[74:75], 0.5 op_sel_hi:[1,0]
	v_pk_mul_f32 v[152:153], v[72:73], 0.5 op_sel_hi:[1,0]
	v_pk_mul_f32 v[104:105], v[90:91], 0.5 op_sel_hi:[1,0]
	v_pk_mul_f32 v[102:103], v[88:89], 0.5 op_sel_hi:[1,0]
	v_pk_mul_f32 v[100:101], v[82:83], 0.5 op_sel_hi:[1,0]
	v_pk_mul_f32 v[98:99], v[80:81], 0.5 op_sel_hi:[1,0]
	v_pk_mul_f32 v[112:113], v[70:71], 0.5 op_sel_hi:[1,0]
	v_pk_mul_f32 v[110:111], v[68:69], 0.5 op_sel_hi:[1,0]
	v_pk_mul_f32 v[108:109], v[66:67], 0.5 op_sel_hi:[1,0]
	v_pk_mul_f32 v[106:107], v[64:65], 0.5 op_sel_hi:[1,0]
	v_pk_mul_f32 v[80:81], v[62:63], 0.5 op_sel_hi:[1,0]
	v_pk_mul_f32 v[82:83], v[60:61], 0.5 op_sel_hi:[1,0]
	v_pk_mul_f32 v[84:85], v[58:59], 0.5 op_sel_hi:[1,0]
	v_pk_mul_f32 v[86:87], v[56:57], 0.5 op_sel_hi:[1,0]
	v_pk_mul_f32 v[88:89], v[46:47], 0.5 op_sel_hi:[1,0]
	v_pk_mul_f32 v[90:91], v[44:45], 0.5 op_sel_hi:[1,0]
	v_pk_mul_f32 v[92:93], v[38:39], 0.5 op_sel_hi:[1,0]
	v_pk_mul_f32 v[94:95], v[36:37], 0.5 op_sel_hi:[1,0]
	v_pk_mul_f32 v[70:71], v[54:55], 0.5 op_sel_hi:[1,0]
	v_pk_mul_f32 v[68:69], v[52:53], 0.5 op_sel_hi:[1,0]
	v_pk_mul_f32 v[66:67], v[50:51], 0.5 op_sel_hi:[1,0]
	v_pk_mul_f32 v[64:65], v[48:49], 0.5 op_sel_hi:[1,0]
	v_pk_mul_f32 v[78:79], v[30:31], 0.5 op_sel_hi:[1,0]
	v_pk_mul_f32 v[76:77], v[28:29], 0.5 op_sel_hi:[1,0]
	v_pk_mul_f32 v[74:75], v[22:23], 0.5 op_sel_hi:[1,0]
	v_pk_mul_f32 v[72:73], v[20:21], 0.5 op_sel_hi:[1,0]
	v_pk_mul_f32 v[54:55], v[42:43], 0.5 op_sel_hi:[1,0]
	v_pk_mul_f32 v[52:53], v[40:41], 0.5 op_sel_hi:[1,0]
	v_pk_mul_f32 v[50:51], v[34:35], 0.5 op_sel_hi:[1,0]
	v_pk_mul_f32 v[48:49], v[32:33], 0.5 op_sel_hi:[1,0]
	v_pk_mul_f32 v[62:63], v[14:15], 0.5 op_sel_hi:[1,0]
	v_pk_mul_f32 v[60:61], v[12:13], 0.5 op_sel_hi:[1,0]
	v_pk_mul_f32 v[58:59], v[10:11], 0.5 op_sel_hi:[1,0]
	v_pk_mul_f32 v[56:57], v[8:9], 0.5 op_sel_hi:[1,0]
	v_pk_mul_f32 v[38:39], v[26:27], 0.5 op_sel_hi:[1,0]
	v_pk_mul_f32 v[36:37], v[24:25], 0.5 op_sel_hi:[1,0]
	v_pk_mul_f32 v[34:35], v[18:19], 0.5 op_sel_hi:[1,0]
	v_pk_mul_f32 v[32:33], v[16:17], 0.5 op_sel_hi:[1,0]
	v_pk_mul_f32 v[46:47], v[6:7], 0.5 op_sel_hi:[1,0]
	v_pk_mul_f32 v[44:45], v[4:5], 0.5 op_sel_hi:[1,0]
	v_pk_mul_f32 v[42:43], v[2:3], 0.5 op_sel_hi:[1,0]
	v_pk_mul_f32 v[40:41], v[0:1], 0.5 op_sel_hi:[1,0]

; #define PG8_STAGE(bufoff, gbase, voff) do { _Pragma("unroll") for (int _i = 0; _i < 2; ++_i) \
;         __builtin_amdgcn_global_load_lds((const unsigned*)((const char*)(gbase) + (voff)[_i]), (LAS unsigned*)(lds + (bufoff) + ldsw + _i * 8192), 16, 0, 0); } while (0)
; #define PG8_LDA(dst, b, h) do { _Pragma("unroll") for (int m = 0; m < 4; ++m) _Pragma("unroll") for (int k = 0; k < 2; ++k) dst[m][k] = *(const LAS bf16x8*)(lds + PG8_SA(b, h) + aoff + m * 2048 + k * 1024); } while (0)
; #define PG8_LDB(dst, b, h) do { _Pragma("unroll") for (int n = 0; n < 2; ++n) _Pragma("unroll") for (int k = 0; k < 2; ++k) dst[n][k] = *(const LAS bf16x8*)(lds + PG8_SB(b, h) + boff + n * 2048 + k * 1024); } while (0)
; #define PG8_MMA(ai, bj, At, Bt) do { __builtin_amdgcn_s_setprio(1); _Pragma("unroll") for (int m = 0; m < 4; ++m) _Pragma("unroll") for (int n = 0; n < 2; ++n) _Pragma("unroll") for (int k = 0; k < 2; ++k) \
;         acc[ai][bj][m][n] = __builtin_amdgcn_mfma_f32_16x16x32_bf16(Bt[n][k], At[m][k], acc[ai][bj][m][n], 0, 0, 0); __builtin_amdgcn_s_setprio(0); } while (0)
; #define PG8_WAIT_V(n) asm volatile("s_waitcnt vmcnt(" #n ")" ::: "memory")
; #define PG8_WAIT_L(n) asm volatile("s_waitcnt lgkmcnt(" #n ")" ::: "memory")
; #define PG8_BAR __builtin_amdgcn_s_barrier()
; #define PG8_SCHED __builtin_amdgcn_sched_barrier(0)
; template <class Epi>
; __device__ __forceinline__ void gemm_phase(LAS unsigned char* lds, const Gemm g, const StaticOrder& S, const Epi& E) {
;     ...
;         for (int t = 0; t < nt; t += 2) {
;             const bool last = (t == nt - 2);
;             const char* a1 = cA + (size_t)(t + 1) * kstep;
;             const char* a2 = last ? nA : cA + (size_t)(t + 2) * kstep; const char* b2 = last ? nB : cB + (size_t)(t + 2) * kstep;
;             const char* a3 = a2 + kstep; const char* b3 = b2 + kstep;
;             PG8_LDB(B0, 0, 0); PG8_LDB(B1, 0, 1); PG8_SCHED; PG8_LDA(At, 0, 0); PG8_STAGE(PG8_SA(1, 1), a1 + hstepA, voffA);
;             PG8_WAIT_V(8); PG8_WAIT_L(0); PG8_BAR; PG8_MMA(0, 0, At, B0); PG8_MMA(0, 1, At, B1); PG8_BAR; PG8_SCHED;
;             PG8_LDA(At, 0, 1); PG8_STAGE(PG8_SB(0, 0), b2, voffB); PG8_STAGE(PG8_SB(0, 1), b2 + hstepB, voffB); PG8_STAGE(PG8_SA(0, 0), a2, voffA);
;             PG8_WAIT_V(8); PG8_WAIT_L(0); PG8_BAR; PG8_MMA(1, 0, At, B0); PG8_MMA(1, 1, At, B1); PG8_BAR; PG8_SCHED;
.LBB0_1338:
	ds_read_b128 v[128:131], v173
	ds_read_b128 v[132:135], v173 offset:1024
	ds_read_b128 v[136:139], v173 offset:2048
	ds_read_b128 v[140:143], v173 offset:3072
	ds_read_b128 v[144:147], v175
	ds_read_b128 v[148:151], v175 offset:1024
	ds_read_b128 v[176:179], v175 offset:2048
	ds_read_b128 v[184:187], v175 offset:3072
	s_add_i32 s20, s10, 2
	s_add_u32 s11, s8, 0xfff80080
	s_addc_u32 s12, s9, -1
	s_cmp_eq_u32 s56, s10
	s_cselect_b32 s10, s17, s18
	s_cselect_b32 s13, s1, s12
	s_cselect_b32 s12, s15, s11
	s_cselect_b32 s11, s16, s19
	v_lshl_add_u64 v[224:225], s[8:9], 0, v[164:165]
	s_add_i32 m0, s47, 0xc000
	ds_read_b128 v[188:191], v181
	ds_read_b128 v[192:195], v181 offset:1024
	ds_read_b128 v[196:199], v181 offset:2048
	ds_read_b128 v[200:203], v181 offset:3072
	ds_read_b128 v[208:211], v181 offset:4096
	ds_read_b128 v[212:215], v181 offset:5120
	ds_read_b128 v[216:219], v181 offset:6144
	ds_read_b128 v[220:223], v181 offset:7168
	global_load_lds_dwordx4 v[224:225], off
	v_lshl_add_u64 v[224:225], s[8:9], 0, v[166:167]
	s_add_i32 m0, s47, 0xe000
	s_nop 0
	global_load_lds_dwordx4 v[224:225], off
	s_waitcnt vmcnt(8)
	s_waitcnt lgkmcnt(0)
	s_barrier
	s_setprio 1
	s_waitcnt lgkmcnt(0)
	v_mfma_f32_16x16x32_bf16 v[124:127], v[128:131], v[188:191], v[124:127]
	v_mfma_f32_16x16x32_bf16 v[120:123], v[136:139], v[188:191], v[120:123]
	v_mfma_f32_16x16x32_bf16 v[116:119], v[144:147], v[188:191], v[116:119]
	v_mfma_f32_16x16x32_bf16 v[112:115], v[176:179], v[188:191], v[112:115]
	v_mfma_f32_16x16x32_bf16 v[96:99], v[176:179], v[196:199], v[96:99]
	v_mfma_f32_16x16x32_bf16 v[100:103], v[144:147], v[196:199], v[100:103]
	v_mfma_f32_16x16x32_bf16 v[104:107], v[136:139], v[196:199], v[104:107]
	v_mfma_f32_16x16x32_bf16 v[108:111], v[128:131], v[196:199], v[108:111]
	v_mfma_f32_16x16x32_bf16 v[92:95], v[128:131], v[208:211], v[92:95]
	v_mfma_f32_16x16x32_bf16 v[88:91], v[136:139], v[208:211], v[88:91]
	v_mfma_f32_16x16x32_bf16 v[84:87], v[144:147], v[208:211], v[84:87]
	v_mfma_f32_16x16x32_bf16 v[80:83], v[176:179], v[208:211], v[80:83]
	v_mfma_f32_16x16x32_bf16 v[64:67], v[176:179], v[216:219], v[64:67]
	v_mfma_f32_16x16x32_bf16 v[68:71], v[144:147], v[216:219], v[68:71]
	v_mfma_f32_16x16x32_bf16 v[72:75], v[136:139], v[216:219], v[72:75]
	v_mfma_f32_16x16x32_bf16 v[76:79], v[128:131], v[216:219], v[76:79]
	s_setprio 0
	s_setprio 1
	v_mfma_f32_16x16x32_bf16 v[124:127], v[132:135], v[192:195], v[124:127]
	v_mfma_f32_16x16x32_bf16 v[120:123], v[140:143], v[192:195], v[120:123]
	v_mfma_f32_16x16x32_bf16 v[116:119], v[148:151], v[192:195], v[116:119]
	v_mfma_f32_16x16x32_bf16 v[112:115], v[184:187], v[192:195], v[112:115]
	v_mfma_f32_16x16x32_bf16 v[96:99], v[184:187], v[200:203], v[96:99]
	v_mfma_f32_16x16x32_bf16 v[100:103], v[148:151], v[200:203], v[100:103]
	v_mfma_f32_16x16x32_bf16 v[104:107], v[140:143], v[200:203], v[104:107]
	v_mfma_f32_16x16x32_bf16 v[108:111], v[132:135], v[200:203], v[108:111]
	v_mfma_f32_16x16x32_bf16 v[92:95], v[132:135], v[212:215], v[92:95]
	v_mfma_f32_16x16x32_bf16 v[88:91], v[140:143], v[212:215], v[88:91]
	v_mfma_f32_16x16x32_bf16 v[84:87], v[148:151], v[212:215], v[84:87]
	v_mfma_f32_16x16x32_bf16 v[80:83], v[184:187], v[212:215], v[80:83]
	v_mfma_f32_16x16x32_bf16 v[64:67], v[184:187], v[220:223], v[64:67]
	v_mfma_f32_16x16x32_bf16 v[68:71], v[148:151], v[220:223], v[68:71]
	v_mfma_f32_16x16x32_bf16 v[72:75], v[140:143], v[220:223], v[72:75]
	v_mfma_f32_16x16x32_bf16 v[76:79], v[132:135], v[220:223], v[76:79]
	s_setprio 0
	s_barrier
	s_add_i32 s21, s59, s46
	v_lshl_add_u64 v[224:225], s[10:11], 0, v[154:155]
	s_mov_b32 m0, s21
	ds_read_b128 v[188:191], v181 offset:16384
	ds_read_b128 v[192:195], v181 offset:17408
	ds_read_b128 v[196:199], v181 offset:18432
	ds_read_b128 v[200:203], v181 offset:19456
	ds_read_b128 v[208:211], v181 offset:20480
	ds_read_b128 v[212:215], v181 offset:21504
	ds_read_b128 v[216:219], v181 offset:22528
	ds_read_b128 v[220:223], v181 offset:23552
	global_load_lds_dwordx4 v[224:225], off
	s_add_i32 m0, s21, 0x2000
	s_add_u32 s68, s10, 0x80000
	v_lshl_add_u64 v[226:227], s[10:11], 0, v[158:159]
	s_addc_u32 s69, s11, 0
	s_add_i32 s21, s60, s46
	global_load_lds_dwordx4 v[226:227], off
	v_lshl_add_u64 v[230:231], s[68:69], 0, v[154:155]
	s_mov_b32 m0, s21
	v_lshl_add_u64 v[232:233], s[12:13], 0, v[156:157]
	global_load_lds_dwordx4 v[230:231], off
	v_lshl_add_u64 v[230:231], s[68:69], 0, v[158:159]
	s_add_i32 m0, s21, 0x2000
	s_nop 0
	global_load_lds_dwordx4 v[230:231], off
	v_lshl_add_u64 v[230:231], s[12:13], 0, v[152:153]
	s_mov_b32 m0, s47
	s_nop 0
	global_load_lds_dwordx4 v[230:231], off
	s_mov_b32 m0, s48
	s_nop 0
	global_load_lds_dwordx4 v[232:233], off
	s_waitcnt vmcnt(8)
	s_waitcnt lgkmcnt(0)
	s_barrier
; #define PG8_STAGE(bufoff, gbase, voff) do { _Pragma("unroll") for (int _i = 0; _i < 2; ++_i) \
;         __builtin_amdgcn_global_load_lds((const unsigned*)((const char*)(gbase) + (voff)[_i]), (LAS unsigned*)(lds + (bufoff) + ldsw + _i * 8192), 16, 0, 0); } while (0)
; #define PG8_LDA(dst, b, h) do { _Pragma("unroll") for (int m = 0; m < 4; ++m) _Pragma("unroll") for (int k = 0; k < 2; ++k) dst[m][k] = *(const LAS bf16x8*)(lds + PG8_SA(b, h) + aoff + m * 2048 + k * 1024); } while (0)
; #define PG8_LDB(dst, b, h) do { _Pragma("unroll") for (int n = 0; n < 2; ++n) _Pragma("unroll") for (int k = 0; k < 2; ++k) dst[n][k] = *(const LAS bf16x8*)(lds + PG8_SB(b, h) + boff + n * 2048 + k * 1024); } while (0)
; #define PG8_MMA(ai, bj, At, Bt) do { __builtin_amdgcn_s_setprio(1); _Pragma("unroll") for (int m = 0; m < 4; ++m) _Pragma("unroll") for (int n = 0; n < 2; ++n) _Pragma("unroll") for (int k = 0; k < 2; ++k) \
;         acc[ai][bj][m][n] = __builtin_amdgcn_mfma_f32_16x16x32_bf16(Bt[n][k], At[m][k], acc[ai][bj][m][n], 0, 0, 0); __builtin_amdgcn_s_setprio(0); } while (0)
; #define PG8_WAIT_V(n) asm volatile("s_waitcnt vmcnt(" #n ")" ::: "memory")
; #define PG8_WAIT_L(n) asm volatile("s_waitcnt lgkmcnt(" #n ")" ::: "memory")
; #define PG8_BAR __builtin_amdgcn_s_barrier()
; #define PG8_SCHED __builtin_amdgcn_sched_barrier(0)
; template <class Epi>
; __device__ __forceinline__ void gemm_phase(LAS unsigned char* lds, const Gemm g, const StaticOrder& S, const Epi& E) {
;     ...
;             PG8_WAIT_V(8); PG8_WAIT_L(0); PG8_BAR; PG8_MMA(1, 0, At, B0); PG8_MMA(1, 1, At, B1); PG8_BAR; PG8_SCHED;
;             PG8_LDB(B0, 1, 0); PG8_LDB(B1, 1, 1); PG8_SCHED; PG8_LDA(At, 1, 0); PG8_STAGE(PG8_SA(0, 1), a2 + hstepA, voffA);
;             PG8_WAIT_V(8); PG8_WAIT_L(0); PG8_BAR; PG8_MMA(0, 0, At, B0); PG8_MMA(0, 1, At, B1); PG8_BAR; PG8_SCHED;
	s_setprio 1
	s_waitcnt lgkmcnt(0)
	v_mfma_f32_16x16x32_bf16 v[60:63], v[128:131], v[188:191], v[60:63]
	v_mfma_f32_16x16x32_bf16 v[56:59], v[136:139], v[188:191], v[56:59]
	v_mfma_f32_16x16x32_bf16 v[52:55], v[144:147], v[188:191], v[52:55]
	v_mfma_f32_16x16x32_bf16 v[48:51], v[176:179], v[188:191], v[48:51]
	v_mfma_f32_16x16x32_bf16 v[32:35], v[176:179], v[196:199], v[32:35]
	v_mfma_f32_16x16x32_bf16 v[36:39], v[144:147], v[196:199], v[36:39]
	v_mfma_f32_16x16x32_bf16 v[40:43], v[136:139], v[196:199], v[40:43]
	v_mfma_f32_16x16x32_bf16 v[44:47], v[128:131], v[196:199], v[44:47]
	v_mfma_f32_16x16x32_bf16 v[28:31], v[128:131], v[208:211], v[28:31]
	v_mfma_f32_16x16x32_bf16 v[24:27], v[136:139], v[208:211], v[24:27]
	v_mfma_f32_16x16x32_bf16 v[20:23], v[144:147], v[208:211], v[20:23]
	v_mfma_f32_16x16x32_bf16 v[16:19], v[176:179], v[208:211], v[16:19]
	v_mfma_f32_16x16x32_bf16 v[0:3], v[176:179], v[216:219], v[0:3]
	v_mfma_f32_16x16x32_bf16 v[4:7], v[144:147], v[216:219], v[4:7]
	v_mfma_f32_16x16x32_bf16 v[8:11], v[136:139], v[216:219], v[8:11]
	v_mfma_f32_16x16x32_bf16 v[12:15], v[128:131], v[216:219], v[12:15]
	s_setprio 0
	s_setprio 1
	v_mfma_f32_16x16x32_bf16 v[60:63], v[132:135], v[192:195], v[60:63]
	v_mfma_f32_16x16x32_bf16 v[56:59], v[140:143], v[192:195], v[56:59]
	v_mfma_f32_16x16x32_bf16 v[52:55], v[148:151], v[192:195], v[52:55]
	v_mfma_f32_16x16x32_bf16 v[48:51], v[184:187], v[192:195], v[48:51]
	v_mfma_f32_16x16x32_bf16 v[32:35], v[184:187], v[200:203], v[32:35]
	v_mfma_f32_16x16x32_bf16 v[36:39], v[148:151], v[200:203], v[36:39]
	v_mfma_f32_16x16x32_bf16 v[40:43], v[140:143], v[200:203], v[40:43]
	v_mfma_f32_16x16x32_bf16 v[44:47], v[132:135], v[200:203], v[44:47]
	v_mfma_f32_16x16x32_bf16 v[28:31], v[132:135], v[212:215], v[28:31]
	v_mfma_f32_16x16x32_bf16 v[24:27], v[140:143], v[212:215], v[24:27]
	v_mfma_f32_16x16x32_bf16 v[20:23], v[148:151], v[212:215], v[20:23]
	v_mfma_f32_16x16x32_bf16 v[16:19], v[184:187], v[212:215], v[16:19]
	v_mfma_f32_16x16x32_bf16 v[0:3], v[184:187], v[220:223], v[0:3]
	v_mfma_f32_16x16x32_bf16 v[4:7], v[148:151], v[220:223], v[4:7]
	v_mfma_f32_16x16x32_bf16 v[8:11], v[140:143], v[220:223], v[8:11]
	v_mfma_f32_16x16x32_bf16 v[12:15], v[132:135], v[220:223], v[12:15]
	s_setprio 0
	s_barrier
	s_add_i32 s21, 0, 0x18000
	s_add_i32 s33, 0, 0x1c000
	v_add_u32_e32 v140, s21, v163
	v_add_u32_e32 v172, s33, v163
	ds_read_b128 v[128:131], v140
	ds_read_b128 v[132:135], v140 offset:1024
	ds_read_b128 v[136:139], v140 offset:2048
	ds_read_b128 v[140:143], v140 offset:3072
	ds_read_b128 v[144:147], v172
	ds_read_b128 v[148:151], v172 offset:1024
	ds_read_b128 v[176:179], v172 offset:2048
	ds_read_b128 v[184:187], v172 offset:3072
	s_add_u32 s12, s12, 0x80000
	s_addc_u32 s13, s13, 0
	s_mov_b32 m0, s49
	v_lshl_add_u64 v[234:235], s[12:13], 0, v[152:153]
	ds_read_b128 v[188:191], v181 offset:32768
	ds_read_b128 v[192:195], v181 offset:33792
	ds_read_b128 v[196:199], v181 offset:34816
	ds_read_b128 v[200:203], v181 offset:35840
	ds_read_b128 v[208:211], v181 offset:36864
	ds_read_b128 v[212:215], v181 offset:37888
	ds_read_b128 v[216:219], v181 offset:38912
	ds_read_b128 v[220:223], v181 offset:39936
	global_load_lds_dwordx4 v[234:235], off
	v_lshl_add_u64 v[234:235], s[12:13], 0, v[156:157]
	s_mov_b32 m0, s50
	s_nop 0
	global_load_lds_dwordx4 v[234:235], off
	s_waitcnt vmcnt(8)
	s_waitcnt lgkmcnt(0)
	s_barrier
	s_setprio 1
	s_waitcnt lgkmcnt(0)
	v_mfma_f32_16x16x32_bf16 v[124:127], v[128:131], v[188:191], v[124:127]
	v_mfma_f32_16x16x32_bf16 v[120:123], v[136:139], v[188:191], v[120:123]
	v_mfma_f32_16x16x32_bf16 v[116:119], v[144:147], v[188:191], v[116:119]
	v_mfma_f32_16x16x32_bf16 v[112:115], v[176:179], v[188:191], v[112:115]
	v_mfma_f32_16x16x32_bf16 v[96:99], v[176:179], v[196:199], v[96:99]
	v_mfma_f32_16x16x32_bf16 v[100:103], v[144:147], v[196:199], v[100:103]
	v_mfma_f32_16x16x32_bf16 v[104:107], v[136:139], v[196:199], v[104:107]
	v_mfma_f32_16x16x32_bf16 v[108:111], v[128:131], v[196:199], v[108:111]
	v_mfma_f32_16x16x32_bf16 v[92:95], v[128:131], v[208:211], v[92:95]
	v_mfma_f32_16x16x32_bf16 v[88:91], v[136:139], v[208:211], v[88:91]
	v_mfma_f32_16x16x32_bf16 v[84:87], v[144:147], v[208:211], v[84:87]
	v_mfma_f32_16x16x32_bf16 v[80:83], v[176:179], v[208:211], v[80:83]
	v_mfma_f32_16x16x32_bf16 v[64:67], v[176:179], v[216:219], v[64:67]
	v_mfma_f32_16x16x32_bf16 v[68:71], v[144:147], v[216:219], v[68:71]
	v_mfma_f32_16x16x32_bf16 v[72:75], v[136:139], v[216:219], v[72:75]
	v_mfma_f32_16x16x32_bf16 v[76:79], v[128:131], v[216:219], v[76:79]
	s_setprio 0
	s_setprio 1
	v_mfma_f32_16x16x32_bf16 v[124:127], v[132:135], v[192:195], v[124:127]
	v_mfma_f32_16x16x32_bf16 v[120:123], v[140:143], v[192:195], v[120:123]
	v_mfma_f32_16x16x32_bf16 v[116:119], v[148:151], v[192:195], v[116:119]
	v_mfma_f32_16x16x32_bf16 v[112:115], v[184:187], v[192:195], v[112:115]
	v_mfma_f32_16x16x32_bf16 v[96:99], v[184:187], v[200:203], v[96:99]
	v_mfma_f32_16x16x32_bf16 v[100:103], v[148:151], v[200:203], v[100:103]
	v_mfma_f32_16x16x32_bf16 v[104:107], v[140:143], v[200:203], v[104:107]
	v_mfma_f32_16x16x32_bf16 v[108:111], v[132:135], v[200:203], v[108:111]
	v_mfma_f32_16x16x32_bf16 v[92:95], v[132:135], v[212:215], v[92:95]
	v_mfma_f32_16x16x32_bf16 v[88:91], v[140:143], v[212:215], v[88:91]
	v_mfma_f32_16x16x32_bf16 v[84:87], v[148:151], v[212:215], v[84:87]
	v_mfma_f32_16x16x32_bf16 v[80:83], v[184:187], v[212:215], v[80:83]
	v_mfma_f32_16x16x32_bf16 v[64:67], v[184:187], v[220:223], v[64:67]
	v_mfma_f32_16x16x32_bf16 v[68:71], v[148:151], v[220:223], v[68:71]
	v_mfma_f32_16x16x32_bf16 v[72:75], v[140:143], v[220:223], v[72:75]
	v_mfma_f32_16x16x32_bf16 v[76:79], v[132:135], v[220:223], v[76:79]
	s_setprio 0
	s_barrier
; #define PG8_STAGE(bufoff, gbase, voff) do { _Pragma("unroll") for (int _i = 0; _i < 2; ++_i) \
;         __builtin_amdgcn_global_load_lds((const unsigned*)((const char*)(gbase) + (voff)[_i]), (LAS unsigned*)(lds + (bufoff) + ldsw + _i * 8192), 16, 0, 0); } while (0)
; #define PG8_LDA(dst, b, h) do { _Pragma("unroll") for (int m = 0; m < 4; ++m) _Pragma("unroll") for (int k = 0; k < 2; ++k) dst[m][k] = *(const LAS bf16x8*)(lds + PG8_SA(b, h) + aoff + m * 2048 + k * 1024); } while (0)
; #define PG8_MMA(ai, bj, At, Bt) do { __builtin_amdgcn_s_setprio(1); _Pragma("unroll") for (int m = 0; m < 4; ++m) _Pragma("unroll") for (int n = 0; n < 2; ++n) _Pragma("unroll") for (int k = 0; k < 2; ++k) \
;         acc[ai][bj][m][n] = __builtin_amdgcn_mfma_f32_16x16x32_bf16(Bt[n][k], At[m][k], acc[ai][bj][m][n], 0, 0, 0); __builtin_amdgcn_s_setprio(0); } while (0)
; #define PG8_WAIT_V(n) asm volatile("s_waitcnt vmcnt(" #n ")" ::: "memory")
; #define PG8_WAIT_L(n) asm volatile("s_waitcnt lgkmcnt(" #n ")" ::: "memory")
; #define PG8_BAR __builtin_amdgcn_s_barrier()
; #define PG8_SCHED __builtin_amdgcn_sched_barrier(0)
; template <class Epi>
; __device__ __forceinline__ void gemm_phase(LAS unsigned char* lds, const Gemm g, const StaticOrder& S, const Epi& E) {
;     ...
;             PG8_LDA(At, 1, 1); PG8_STAGE(PG8_SB(1, 0), b3, voffB); PG8_STAGE(PG8_SB(1, 1), b3 + hstepB, voffB); PG8_STAGE(PG8_SA(1, 0), a3, voffA);
;             PG8_WAIT_V(8); PG8_WAIT_L(0); PG8_BAR; PG8_MMA(1, 0, At, B0); PG8_MMA(1, 1, At, B1); PG8_BAR; PG8_SCHED;
;         }
	s_add_i32 s12, s21, s46
	v_lshl_add_u64 v[224:225], v[224:225], 0, s[28:29]
	s_mov_b32 m0, s12
	ds_read_b128 v[188:191], v181 offset:49152
	ds_read_b128 v[192:195], v181 offset:50176
	ds_read_b128 v[196:199], v181 offset:51200
	ds_read_b128 v[200:203], v181 offset:52224
	ds_read_b128 v[208:211], v181 offset:53248
	ds_read_b128 v[212:215], v181 offset:54272
	ds_read_b128 v[216:219], v181 offset:55296
	ds_read_b128 v[220:223], v181 offset:56320
	global_load_lds_dwordx4 v[224:225], off
	s_add_i32 m0, s12, 0x2000
	s_add_u32 s10, s10, 0x80080
	v_lshl_add_u64 v[224:225], v[226:227], 0, s[28:29]
	s_addc_u32 s11, s11, 0
	s_add_i32 s12, s33, s46
	global_load_lds_dwordx4 v[224:225], off
	v_lshl_add_u64 v[224:225], s[10:11], 0, v[154:155]
	s_mov_b32 m0, s12
	s_nop 0
	global_load_lds_dwordx4 v[224:225], off
	v_lshl_add_u64 v[224:225], s[10:11], 0, v[158:159]
	s_add_i32 m0, s12, 0x2000
	s_nop 0
	global_load_lds_dwordx4 v[224:225], off
	v_lshl_add_u64 v[224:225], v[230:231], 0, s[28:29]
	s_mov_b32 m0, s54
	s_nop 0
	global_load_lds_dwordx4 v[224:225], off
	v_lshl_add_u64 v[224:225], v[232:233], 0, s[28:29]
	s_mov_b32 m0, s55
	s_nop 0
	global_load_lds_dwordx4 v[224:225], off
	s_waitcnt vmcnt(8)
	s_waitcnt lgkmcnt(0)
	s_barrier
	s_setprio 1
	s_waitcnt lgkmcnt(0)
	v_mfma_f32_16x16x32_bf16 v[60:63], v[128:131], v[188:191], v[60:63]
	v_mfma_f32_16x16x32_bf16 v[56:59], v[136:139], v[188:191], v[56:59]
	v_mfma_f32_16x16x32_bf16 v[52:55], v[144:147], v[188:191], v[52:55]
	v_mfma_f32_16x16x32_bf16 v[48:51], v[176:179], v[188:191], v[48:51]
	v_mfma_f32_16x16x32_bf16 v[32:35], v[176:179], v[196:199], v[32:35]
	v_mfma_f32_16x16x32_bf16 v[36:39], v[144:147], v[196:199], v[36:39]
	v_mfma_f32_16x16x32_bf16 v[40:43], v[136:139], v[196:199], v[40:43]
	v_mfma_f32_16x16x32_bf16 v[44:47], v[128:131], v[196:199], v[44:47]
	v_mfma_f32_16x16x32_bf16 v[28:31], v[128:131], v[208:211], v[28:31]
	v_mfma_f32_16x16x32_bf16 v[24:27], v[136:139], v[208:211], v[24:27]
	v_mfma_f32_16x16x32_bf16 v[20:23], v[144:147], v[208:211], v[20:23]
	v_mfma_f32_16x16x32_bf16 v[16:19], v[176:179], v[208:211], v[16:19]
	v_mfma_f32_16x16x32_bf16 v[0:3], v[176:179], v[216:219], v[0:3]
	v_mfma_f32_16x16x32_bf16 v[4:7], v[144:147], v[216:219], v[4:7]
	v_mfma_f32_16x16x32_bf16 v[8:11], v[136:139], v[216:219], v[8:11]
	v_mfma_f32_16x16x32_bf16 v[12:15], v[128:131], v[216:219], v[12:15]
	s_setprio 0
	s_setprio 1
	v_mfma_f32_16x16x32_bf16 v[60:63], v[132:135], v[192:195], v[60:63]
	v_mfma_f32_16x16x32_bf16 v[56:59], v[140:143], v[192:195], v[56:59]
	v_mfma_f32_16x16x32_bf16 v[52:55], v[148:151], v[192:195], v[52:55]
	v_mfma_f32_16x16x32_bf16 v[48:51], v[184:187], v[192:195], v[48:51]
	v_mfma_f32_16x16x32_bf16 v[32:35], v[184:187], v[200:203], v[32:35]
	v_mfma_f32_16x16x32_bf16 v[36:39], v[148:151], v[200:203], v[36:39]
	v_mfma_f32_16x16x32_bf16 v[40:43], v[140:143], v[200:203], v[40:43]
	v_mfma_f32_16x16x32_bf16 v[44:47], v[132:135], v[200:203], v[44:47]
	v_mfma_f32_16x16x32_bf16 v[28:31], v[132:135], v[212:215], v[28:31]
	v_mfma_f32_16x16x32_bf16 v[24:27], v[140:143], v[212:215], v[24:27]
	v_mfma_f32_16x16x32_bf16 v[20:23], v[148:151], v[212:215], v[20:23]
	v_mfma_f32_16x16x32_bf16 v[16:19], v[184:187], v[212:215], v[16:19]
	v_mfma_f32_16x16x32_bf16 v[0:3], v[184:187], v[220:223], v[0:3]
	v_mfma_f32_16x16x32_bf16 v[4:7], v[148:151], v[220:223], v[4:7]
	v_mfma_f32_16x16x32_bf16 v[8:11], v[140:143], v[220:223], v[8:11]
	v_mfma_f32_16x16x32_bf16 v[12:15], v[132:135], v[220:223], v[12:15]
	s_setprio 0
	s_barrier
	s_add_u32 s8, s8, 0x100
	s_addc_u32 s9, s9, 0
	s_add_u32 s18, s18, 0x100
	s_addc_u32 s19, s19, 0
	s_cmp_ge_i32 s20, s53
	s_mov_b32 s10, s20
	s_cbranch_scc0 .LBB0_1338
